# adds gate low-rank MFMA load hoist (40 loads in flight) and two-row software-pipelined rmsnorm pass
# speedup vs baseline: 1.0305x; 1.0022x over previous
; __device__ __forceinline__ unsigned cvtpk(float lo, float hi) { f32x2 v = {lo, hi}; bf16x2_t b = __builtin_convertvector(v, bf16x2_t); return __builtin_bit_cast(unsigned, b); }
; __device__ __forceinline__ int hw_lane() { int l; asm volatile("v_mbcnt_lo_u32_b32 %0, -1, 0\n\tv_mbcnt_hi_u32_b32 %0, -1, %0" : "=v"(l)); return l; }
; __device__ __forceinline__ void rms_row_to_bf16(const float* xrow, bf16_t* orow, int lane) {
;     const f32x4* xr = (const f32x4*)xrow + lane;
;     f32x4 v[8]; float s = 0.f;
; #pragma unroll
;     for (int j = 0; j < 8; ++j) { v[j] = xr[64 * j]; s += (v[j].x * v[j].x + v[j].y * v[j].y) + (v[j].z * v[j].z + v[j].w * v[j].w); }
;     const float rstd = 1.0f / sqrtf(wave_sum(s) * (1.0f / DM) + EPS);
;     u32x2* o8 = (u32x2*)orow + lane;
; #pragma unroll
;     for (int j = 0; j < 8; ++j) { u32x2 w; w.x = cvtpk(v[j].x * rstd, v[j].y * rstd); w.y = cvtpk(v[j].z * rstd, v[j].w * rstd); o8[64 * j] = w; }
; }
; __device__ __forceinline__ void norm_pass(const float* src, bf16_t* XN, int gw, int NGW, int lane) {
;     lane = hw_lane();
;     for (int m = gw; m < MTOK; m += NGW) rms_row_to_bf16(src + (size_t)m * DM, XN + (size_t)m * DM, lane);
; }
.LBB0_76:
	global_load_dwordx4 v[4:7], v[24:25], off offset:-4096
	global_load_dwordx4 v[0:3], v[24:25], off offset:-3072
	global_load_dwordx4 v[8:11], v[24:25], off offset:-2048
	global_load_dwordx4 v[16:19], v[24:25], off offset:-1024
	global_load_dwordx4 v[12:15], v[24:25], off
	global_load_dwordx4 v[20:23], v[24:25], off offset:1024
	global_load_dwordx4 v[40:43], v[24:25], off offset:2048
	global_load_dwordx4 v[36:39], v[24:25], off offset:3072
	s_add_i32 s10, s10, s0
	v_lshl_add_u64 v[24:25], v[24:25], 0, s[2:3]
	s_cmpk_gt_i32 s10, 0x3fff
	s_cbranch_scc1 .Lnp_Afirst_last
	global_load_dwordx4 v[84:87], v[24:25], off offset:-4096
	global_load_dwordx4 v[88:91], v[24:25], off offset:-3072
	global_load_dwordx4 v[92:95], v[24:25], off offset:-2048
	global_load_dwordx4 v[96:99], v[24:25], off offset:-1024
	global_load_dwordx4 v[100:103], v[24:25], off
	global_load_dwordx4 v[104:107], v[24:25], off offset:1024
	global_load_dwordx4 v[108:111], v[24:25], off offset:2048
	global_load_dwordx4 v[112:115], v[24:25], off offset:3072
	s_add_i32 s10, s10, s0
	v_lshl_add_u64 v[24:25], v[24:25], 0, s[2:3]
	s_waitcnt vmcnt(8)
	v_pk_mul_f32 v[44:45], v[4:5], v[4:5]
	v_pk_fma_f32 v[44:45], v[6:7], v[6:7], v[44:45]
	v_pk_fma_f32 v[44:45], v[0:1], v[0:1], v[44:45]
	v_pk_fma_f32 v[44:45], v[2:3], v[2:3], v[44:45]
	v_pk_fma_f32 v[44:45], v[8:9], v[8:9], v[44:45]
	v_pk_fma_f32 v[44:45], v[10:11], v[10:11], v[44:45]
	v_pk_fma_f32 v[44:45], v[16:17], v[16:17], v[44:45]
	v_pk_fma_f32 v[44:45], v[18:19], v[18:19], v[44:45]
	v_pk_fma_f32 v[44:45], v[12:13], v[12:13], v[44:45]
	v_pk_fma_f32 v[44:45], v[14:15], v[14:15], v[44:45]
	v_pk_fma_f32 v[44:45], v[20:21], v[20:21], v[44:45]
	v_pk_fma_f32 v[44:45], v[22:23], v[22:23], v[44:45]
	v_pk_fma_f32 v[44:45], v[40:41], v[40:41], v[44:45]
	v_pk_fma_f32 v[44:45], v[42:43], v[42:43], v[44:45]
	v_pk_fma_f32 v[44:45], v[36:37], v[36:37], v[44:45]
	v_pk_fma_f32 v[44:45], v[38:39], v[38:39], v[44:45]
	s_nop 0
	v_add_f32_e32 v44, v44, v45
	s_nop 1
	v_add_f32_dpp v44, v44, v44 quad_perm:[1,0,3,2] row_mask:0xf bank_mask:0xf
	s_nop 1
	v_add_f32_dpp v44, v44, v44 quad_perm:[2,3,0,1] row_mask:0xf bank_mask:0xf
	s_nop 1
	v_add_f32_dpp v44, v44, v44 row_half_mirror row_mask:0xf bank_mask:0xf
	s_nop 1
	v_add_f32_dpp v44, v44, v44 row_ror:8 row_mask:0xf bank_mask:0xf
	s_nop 1
	ds_bpermute_b32 v45, v32, v44
	s_waitcnt lgkmcnt(0)
	v_add_f32_e32 v44, v44, v45
	ds_bpermute_b32 v45, v33, v44
	s_waitcnt lgkmcnt(0)
	v_add_f32_e32 v44, v44, v45
	v_fmamk_f32 v44, v44, 0x3a000000, v34
	s_nop 0
	v_rsq_f32_e32 v44, v44
	s_nop 0
	v_pk_mul_f32 v[4:5], v[4:5], v[44:45] op_sel_hi:[1,0]
	v_pk_mul_f32 v[6:7], v[6:7], v[44:45] op_sel_hi:[1,0]
	v_pk_mul_f32 v[0:1], v[0:1], v[44:45] op_sel_hi:[1,0]
	v_pk_mul_f32 v[2:3], v[2:3], v[44:45] op_sel_hi:[1,0]
	v_pk_mul_f32 v[8:9], v[8:9], v[44:45] op_sel_hi:[1,0]
	v_pk_mul_f32 v[10:11], v[10:11], v[44:45] op_sel_hi:[1,0]
	v_pk_mul_f32 v[16:17], v[16:17], v[44:45] op_sel_hi:[1,0]
	v_pk_mul_f32 v[18:19], v[18:19], v[44:45] op_sel_hi:[1,0]
	v_pk_mul_f32 v[12:13], v[12:13], v[44:45] op_sel_hi:[1,0]
	v_pk_mul_f32 v[14:15], v[14:15], v[44:45] op_sel_hi:[1,0]
	v_pk_mul_f32 v[20:21], v[20:21], v[44:45] op_sel_hi:[1,0]
	v_pk_mul_f32 v[22:23], v[22:23], v[44:45] op_sel_hi:[1,0]
	v_pk_mul_f32 v[40:41], v[40:41], v[44:45] op_sel_hi:[1,0]
	v_pk_mul_f32 v[42:43], v[42:43], v[44:45] op_sel_hi:[1,0]
	v_pk_mul_f32 v[36:37], v[36:37], v[44:45] op_sel_hi:[1,0]
	v_pk_mul_f32 v[38:39], v[38:39], v[44:45] op_sel_hi:[1,0]
	v_cvt_pk_bf16_f32 v4, v4, v5
	v_cvt_pk_bf16_f32 v5, v6, v7
	v_cvt_pk_bf16_f32 v0, v0, v1
	v_cvt_pk_bf16_f32 v1, v2, v3
	v_cvt_pk_bf16_f32 v8, v8, v9
	v_cvt_pk_bf16_f32 v9, v10, v11
	v_cvt_pk_bf16_f32 v16, v16, v17
	v_cvt_pk_bf16_f32 v17, v18, v19
	v_cvt_pk_bf16_f32 v12, v12, v13
	v_cvt_pk_bf16_f32 v13, v14, v15
	v_cvt_pk_bf16_f32 v20, v20, v21
	v_cvt_pk_bf16_f32 v21, v22, v23
	v_cvt_pk_bf16_f32 v40, v40, v41
	v_cvt_pk_bf16_f32 v41, v42, v43
	v_cvt_pk_bf16_f32 v36, v36, v37
	v_cvt_pk_bf16_f32 v37, v38, v39
	global_store_dwordx2 v[26:27], v[4:5], off
	global_store_dwordx2 v[26:27], v[0:1], off offset:512
	global_store_dwordx2 v[26:27], v[8:9], off offset:1024
	global_store_dwordx2 v[26:27], v[16:17], off offset:1536
	global_store_dwordx2 v[26:27], v[12:13], off offset:2048
	global_store_dwordx2 v[26:27], v[20:21], off offset:2560
	global_store_dwordx2 v[26:27], v[40:41], off offset:3072
	global_store_dwordx2 v[26:27], v[36:37], off offset:3584
	v_lshl_add_u64 v[26:27], v[26:27], 0, s[6:7]
; __device__ __forceinline__ unsigned cvtpk(float lo, float hi) { f32x2 v = {lo, hi}; bf16x2_t b = __builtin_convertvector(v, bf16x2_t); return __builtin_bit_cast(unsigned, b); }
; __device__ __forceinline__ int hw_lane() { int l; asm volatile("v_mbcnt_lo_u32_b32 %0, -1, 0\n\tv_mbcnt_hi_u32_b32 %0, -1, %0" : "=v"(l)); return l; }
; __device__ __forceinline__ void rms_row_to_bf16(const float* xrow, bf16_t* orow, int lane) {
;     const f32x4* xr = (const f32x4*)xrow + lane;
;     f32x4 v[8]; float s = 0.f;
; #pragma unroll
;     for (int j = 0; j < 8; ++j) { v[j] = xr[64 * j]; s += (v[j].x * v[j].x + v[j].y * v[j].y) + (v[j].z * v[j].z + v[j].w * v[j].w); }
;     const float rstd = 1.0f / sqrtf(wave_sum(s) * (1.0f / DM) + EPS);
;     u32x2* o8 = (u32x2*)orow + lane;
; #pragma unroll
;     for (int j = 0; j < 8; ++j) { u32x2 w; w.x = cvtpk(v[j].x * rstd, v[j].y * rstd); w.y = cvtpk(v[j].z * rstd, v[j].w * rstd); o8[64 * j] = w; }
; }
; __device__ __forceinline__ void norm_pass(const float* src, bf16_t* XN, int gw, int NGW, int lane) {
;     lane = hw_lane();
;     for (int m = gw; m < MTOK; m += NGW) rms_row_to_bf16(src + (size_t)m * DM, XN + (size_t)m * DM, lane);
; }
.Lnp_loop:
	s_cmpk_gt_i32 s10, 0x3fff
	s_cbranch_scc1 .Lnp_B_last
	global_load_dwordx4 v[4:7], v[24:25], off offset:-4096
	global_load_dwordx4 v[0:3], v[24:25], off offset:-3072
	global_load_dwordx4 v[8:11], v[24:25], off offset:-2048
	global_load_dwordx4 v[16:19], v[24:25], off offset:-1024
	global_load_dwordx4 v[12:15], v[24:25], off
	global_load_dwordx4 v[20:23], v[24:25], off offset:1024
	global_load_dwordx4 v[40:43], v[24:25], off offset:2048
	global_load_dwordx4 v[36:39], v[24:25], off offset:3072
	s_add_i32 s10, s10, s0
	v_lshl_add_u64 v[24:25], v[24:25], 0, s[2:3]
	s_waitcnt vmcnt(16)
	v_pk_mul_f32 v[44:45], v[84:85], v[84:85]
	v_pk_fma_f32 v[44:45], v[86:87], v[86:87], v[44:45]
	v_pk_fma_f32 v[44:45], v[88:89], v[88:89], v[44:45]
	v_pk_fma_f32 v[44:45], v[90:91], v[90:91], v[44:45]
	v_pk_fma_f32 v[44:45], v[92:93], v[92:93], v[44:45]
	v_pk_fma_f32 v[44:45], v[94:95], v[94:95], v[44:45]
	v_pk_fma_f32 v[44:45], v[96:97], v[96:97], v[44:45]
	v_pk_fma_f32 v[44:45], v[98:99], v[98:99], v[44:45]
	v_pk_fma_f32 v[44:45], v[100:101], v[100:101], v[44:45]
	v_pk_fma_f32 v[44:45], v[102:103], v[102:103], v[44:45]
	v_pk_fma_f32 v[44:45], v[104:105], v[104:105], v[44:45]
	v_pk_fma_f32 v[44:45], v[106:107], v[106:107], v[44:45]
	v_pk_fma_f32 v[44:45], v[108:109], v[108:109], v[44:45]
	v_pk_fma_f32 v[44:45], v[110:111], v[110:111], v[44:45]
	v_pk_fma_f32 v[44:45], v[112:113], v[112:113], v[44:45]
	v_pk_fma_f32 v[44:45], v[114:115], v[114:115], v[44:45]
	s_nop 0
	v_add_f32_e32 v44, v44, v45
	s_nop 1
	v_add_f32_dpp v44, v44, v44 quad_perm:[1,0,3,2] row_mask:0xf bank_mask:0xf
	s_nop 1
	v_add_f32_dpp v44, v44, v44 quad_perm:[2,3,0,1] row_mask:0xf bank_mask:0xf
	s_nop 1
	v_add_f32_dpp v44, v44, v44 row_half_mirror row_mask:0xf bank_mask:0xf
	s_nop 1
	v_add_f32_dpp v44, v44, v44 row_ror:8 row_mask:0xf bank_mask:0xf
	s_nop 1
	ds_bpermute_b32 v45, v32, v44
	s_waitcnt lgkmcnt(0)
	v_add_f32_e32 v44, v44, v45
	ds_bpermute_b32 v45, v33, v44
	s_waitcnt lgkmcnt(0)
	v_add_f32_e32 v44, v44, v45
	v_fmamk_f32 v44, v44, 0x3a000000, v34
	s_nop 0
	v_rsq_f32_e32 v44, v44
	s_nop 0
	v_pk_mul_f32 v[84:85], v[84:85], v[44:45] op_sel_hi:[1,0]
	v_pk_mul_f32 v[86:87], v[86:87], v[44:45] op_sel_hi:[1,0]
	v_pk_mul_f32 v[88:89], v[88:89], v[44:45] op_sel_hi:[1,0]
	v_pk_mul_f32 v[90:91], v[90:91], v[44:45] op_sel_hi:[1,0]
	v_pk_mul_f32 v[92:93], v[92:93], v[44:45] op_sel_hi:[1,0]
	v_pk_mul_f32 v[94:95], v[94:95], v[44:45] op_sel_hi:[1,0]
	v_pk_mul_f32 v[96:97], v[96:97], v[44:45] op_sel_hi:[1,0]
	v_pk_mul_f32 v[98:99], v[98:99], v[44:45] op_sel_hi:[1,0]
	v_pk_mul_f32 v[100:101], v[100:101], v[44:45] op_sel_hi:[1,0]
	v_pk_mul_f32 v[102:103], v[102:103], v[44:45] op_sel_hi:[1,0]
	v_pk_mul_f32 v[104:105], v[104:105], v[44:45] op_sel_hi:[1,0]
	v_pk_mul_f32 v[106:107], v[106:107], v[44:45] op_sel_hi:[1,0]
	v_pk_mul_f32 v[108:109], v[108:109], v[44:45] op_sel_hi:[1,0]
	v_pk_mul_f32 v[110:111], v[110:111], v[44:45] op_sel_hi:[1,0]
	v_pk_mul_f32 v[112:113], v[112:113], v[44:45] op_sel_hi:[1,0]
	v_pk_mul_f32 v[114:115], v[114:115], v[44:45] op_sel_hi:[1,0]
	v_cvt_pk_bf16_f32 v84, v84, v85
	v_cvt_pk_bf16_f32 v85, v86, v87
	v_cvt_pk_bf16_f32 v88, v88, v89
	v_cvt_pk_bf16_f32 v89, v90, v91
	v_cvt_pk_bf16_f32 v92, v92, v93
	v_cvt_pk_bf16_f32 v93, v94, v95
	v_cvt_pk_bf16_f32 v96, v96, v97
	v_cvt_pk_bf16_f32 v97, v98, v99
	v_cvt_pk_bf16_f32 v100, v100, v101
	v_cvt_pk_bf16_f32 v101, v102, v103
	v_cvt_pk_bf16_f32 v104, v104, v105
	v_cvt_pk_bf16_f32 v105, v106, v107
	v_cvt_pk_bf16_f32 v108, v108, v109
	v_cvt_pk_bf16_f32 v109, v110, v111
	v_cvt_pk_bf16_f32 v112, v112, v113
	v_cvt_pk_bf16_f32 v113, v114, v115
	global_store_dwordx2 v[26:27], v[84:85], off
	global_store_dwordx2 v[26:27], v[88:89], off offset:512
	global_store_dwordx2 v[26:27], v[92:93], off offset:1024
	global_store_dwordx2 v[26:27], v[96:97], off offset:1536
	global_store_dwordx2 v[26:27], v[100:101], off offset:2048
	global_store_dwordx2 v[26:27], v[104:105], off offset:2560
	global_store_dwordx2 v[26:27], v[108:109], off offset:3072
	global_store_dwordx2 v[26:27], v[112:113], off offset:3584
	v_lshl_add_u64 v[26:27], v[26:27], 0, s[6:7]
	s_cmpk_gt_i32 s10, 0x3fff
	s_cbranch_scc1 .Lnp_A_last
	global_load_dwordx4 v[84:87], v[24:25], off offset:-4096
	global_load_dwordx4 v[88:91], v[24:25], off offset:-3072
	global_load_dwordx4 v[92:95], v[24:25], off offset:-2048
	global_load_dwordx4 v[96:99], v[24:25], off offset:-1024
	global_load_dwordx4 v[100:103], v[24:25], off
	global_load_dwordx4 v[104:107], v[24:25], off offset:1024
	global_load_dwordx4 v[108:111], v[24:25], off offset:2048
	global_load_dwordx4 v[112:115], v[24:25], off offset:3072
	s_add_i32 s10, s10, s0
	v_lshl_add_u64 v[24:25], v[24:25], 0, s[2:3]
	s_waitcnt vmcnt(16)
	v_pk_mul_f32 v[44:45], v[4:5], v[4:5]
	v_pk_fma_f32 v[44:45], v[6:7], v[6:7], v[44:45]
	v_pk_fma_f32 v[44:45], v[0:1], v[0:1], v[44:45]
	v_pk_fma_f32 v[44:45], v[2:3], v[2:3], v[44:45]
	v_pk_fma_f32 v[44:45], v[8:9], v[8:9], v[44:45]
	v_pk_fma_f32 v[44:45], v[10:11], v[10:11], v[44:45]
	v_pk_fma_f32 v[44:45], v[16:17], v[16:17], v[44:45]
	v_pk_fma_f32 v[44:45], v[18:19], v[18:19], v[44:45]
	v_pk_fma_f32 v[44:45], v[12:13], v[12:13], v[44:45]
	v_pk_fma_f32 v[44:45], v[14:15], v[14:15], v[44:45]
	v_pk_fma_f32 v[44:45], v[20:21], v[20:21], v[44:45]
	v_pk_fma_f32 v[44:45], v[22:23], v[22:23], v[44:45]
	v_pk_fma_f32 v[44:45], v[40:41], v[40:41], v[44:45]
	v_pk_fma_f32 v[44:45], v[42:43], v[42:43], v[44:45]
	v_pk_fma_f32 v[44:45], v[36:37], v[36:37], v[44:45]
	v_pk_fma_f32 v[44:45], v[38:39], v[38:39], v[44:45]
	s_nop 0
	v_add_f32_e32 v44, v44, v45
	s_nop 1
	v_add_f32_dpp v44, v44, v44 quad_perm:[1,0,3,2] row_mask:0xf bank_mask:0xf
	s_nop 1
	v_add_f32_dpp v44, v44, v44 quad_perm:[2,3,0,1] row_mask:0xf bank_mask:0xf
	s_nop 1
	v_add_f32_dpp v44, v44, v44 row_half_mirror row_mask:0xf bank_mask:0xf
	s_nop 1
	v_add_f32_dpp v44, v44, v44 row_ror:8 row_mask:0xf bank_mask:0xf
	s_nop 1
	ds_bpermute_b32 v45, v32, v44
	s_waitcnt lgkmcnt(0)
; __device__ __forceinline__ unsigned cvtpk(float lo, float hi) { f32x2 v = {lo, hi}; bf16x2_t b = __builtin_convertvector(v, bf16x2_t); return __builtin_bit_cast(unsigned, b); }
; __device__ __forceinline__ int hw_lane() { int l; asm volatile("v_mbcnt_lo_u32_b32 %0, -1, 0\n\tv_mbcnt_hi_u32_b32 %0, -1, %0" : "=v"(l)); return l; }
; __device__ __forceinline__ void rms_row_to_bf16(const float* xrow, bf16_t* orow, int lane) {
;     const f32x4* xr = (const f32x4*)xrow + lane;
;     f32x4 v[8]; float s = 0.f;
; #pragma unroll
;     for (int j = 0; j < 8; ++j) { v[j] = xr[64 * j]; s += (v[j].x * v[j].x + v[j].y * v[j].y) + (v[j].z * v[j].z + v[j].w * v[j].w); }
;     const float rstd = 1.0f / sqrtf(wave_sum(s) * (1.0f / DM) + EPS);
;     u32x2* o8 = (u32x2*)orow + lane;
; #pragma unroll
;     for (int j = 0; j < 8; ++j) { u32x2 w; w.x = cvtpk(v[j].x * rstd, v[j].y * rstd); w.y = cvtpk(v[j].z * rstd, v[j].w * rstd); o8[64 * j] = w; }
; }
; __device__ __forceinline__ void norm_pass(const float* src, bf16_t* XN, int gw, int NGW, int lane) {
;     lane = hw_lane();
;     for (int m = gw; m < MTOK; m += NGW) rms_row_to_bf16(src + (size_t)m * DM, XN + (size_t)m * DM, lane);
; }
	v_add_f32_e32 v44, v44, v45
	ds_bpermute_b32 v45, v33, v44
	s_waitcnt lgkmcnt(0)
	v_add_f32_e32 v44, v44, v45
	v_fmamk_f32 v44, v44, 0x3a000000, v34
	s_nop 0
	v_rsq_f32_e32 v44, v44
	s_nop 0
	v_pk_mul_f32 v[4:5], v[4:5], v[44:45] op_sel_hi:[1,0]
	v_pk_mul_f32 v[6:7], v[6:7], v[44:45] op_sel_hi:[1,0]
	v_pk_mul_f32 v[0:1], v[0:1], v[44:45] op_sel_hi:[1,0]
	v_pk_mul_f32 v[2:3], v[2:3], v[44:45] op_sel_hi:[1,0]
	v_pk_mul_f32 v[8:9], v[8:9], v[44:45] op_sel_hi:[1,0]
	v_pk_mul_f32 v[10:11], v[10:11], v[44:45] op_sel_hi:[1,0]
	v_pk_mul_f32 v[16:17], v[16:17], v[44:45] op_sel_hi:[1,0]
	v_pk_mul_f32 v[18:19], v[18:19], v[44:45] op_sel_hi:[1,0]
	v_pk_mul_f32 v[12:13], v[12:13], v[44:45] op_sel_hi:[1,0]
	v_pk_mul_f32 v[14:15], v[14:15], v[44:45] op_sel_hi:[1,0]
	v_pk_mul_f32 v[20:21], v[20:21], v[44:45] op_sel_hi:[1,0]
	v_pk_mul_f32 v[22:23], v[22:23], v[44:45] op_sel_hi:[1,0]
	v_pk_mul_f32 v[40:41], v[40:41], v[44:45] op_sel_hi:[1,0]
	v_pk_mul_f32 v[42:43], v[42:43], v[44:45] op_sel_hi:[1,0]
	v_pk_mul_f32 v[36:37], v[36:37], v[44:45] op_sel_hi:[1,0]
	v_pk_mul_f32 v[38:39], v[38:39], v[44:45] op_sel_hi:[1,0]
	v_cvt_pk_bf16_f32 v4, v4, v5
	v_cvt_pk_bf16_f32 v5, v6, v7
	v_cvt_pk_bf16_f32 v0, v0, v1
	v_cvt_pk_bf16_f32 v1, v2, v3
	v_cvt_pk_bf16_f32 v8, v8, v9
	v_cvt_pk_bf16_f32 v9, v10, v11
	v_cvt_pk_bf16_f32 v16, v16, v17
	v_cvt_pk_bf16_f32 v17, v18, v19
	v_cvt_pk_bf16_f32 v12, v12, v13
	v_cvt_pk_bf16_f32 v13, v14, v15
	v_cvt_pk_bf16_f32 v20, v20, v21
	v_cvt_pk_bf16_f32 v21, v22, v23
	v_cvt_pk_bf16_f32 v40, v40, v41
	v_cvt_pk_bf16_f32 v41, v42, v43
	v_cvt_pk_bf16_f32 v36, v36, v37
	v_cvt_pk_bf16_f32 v37, v38, v39
	global_store_dwordx2 v[26:27], v[4:5], off
	global_store_dwordx2 v[26:27], v[0:1], off offset:512
	global_store_dwordx2 v[26:27], v[8:9], off offset:1024
	global_store_dwordx2 v[26:27], v[16:17], off offset:1536
	global_store_dwordx2 v[26:27], v[12:13], off offset:2048
	global_store_dwordx2 v[26:27], v[20:21], off offset:2560
	global_store_dwordx2 v[26:27], v[40:41], off offset:3072
	global_store_dwordx2 v[26:27], v[36:37], off offset:3584
	v_lshl_add_u64 v[26:27], v[26:27], 0, s[6:7]
	s_branch .Lnp_loop
.Lnp_Afirst_last:
	s_waitcnt vmcnt(0)
	v_pk_mul_f32 v[44:45], v[4:5], v[4:5]
	v_pk_fma_f32 v[44:45], v[6:7], v[6:7], v[44:45]
	v_pk_fma_f32 v[44:45], v[0:1], v[0:1], v[44:45]
	v_pk_fma_f32 v[44:45], v[2:3], v[2:3], v[44:45]
	v_pk_fma_f32 v[44:45], v[8:9], v[8:9], v[44:45]
	v_pk_fma_f32 v[44:45], v[10:11], v[10:11], v[44:45]
	v_pk_fma_f32 v[44:45], v[16:17], v[16:17], v[44:45]
	v_pk_fma_f32 v[44:45], v[18:19], v[18:19], v[44:45]
	v_pk_fma_f32 v[44:45], v[12:13], v[12:13], v[44:45]
	v_pk_fma_f32 v[44:45], v[14:15], v[14:15], v[44:45]
	v_pk_fma_f32 v[44:45], v[20:21], v[20:21], v[44:45]
	v_pk_fma_f32 v[44:45], v[22:23], v[22:23], v[44:45]
	v_pk_fma_f32 v[44:45], v[40:41], v[40:41], v[44:45]
	v_pk_fma_f32 v[44:45], v[42:43], v[42:43], v[44:45]
	v_pk_fma_f32 v[44:45], v[36:37], v[36:37], v[44:45]
	v_pk_fma_f32 v[44:45], v[38:39], v[38:39], v[44:45]
	s_nop 0
	v_add_f32_e32 v44, v44, v45
	s_nop 1
	v_add_f32_dpp v44, v44, v44 quad_perm:[1,0,3,2] row_mask:0xf bank_mask:0xf
	s_nop 1
	v_add_f32_dpp v44, v44, v44 quad_perm:[2,3,0,1] row_mask:0xf bank_mask:0xf
	s_nop 1
	v_add_f32_dpp v44, v44, v44 row_half_mirror row_mask:0xf bank_mask:0xf
	s_nop 1
	v_add_f32_dpp v44, v44, v44 row_ror:8 row_mask:0xf bank_mask:0xf
	s_nop 1
	ds_bpermute_b32 v45, v32, v44
	s_waitcnt lgkmcnt(0)
	v_add_f32_e32 v44, v44, v45
	ds_bpermute_b32 v45, v33, v44
	s_waitcnt lgkmcnt(0)
	v_add_f32_e32 v44, v44, v45
	v_fmamk_f32 v44, v44, 0x3a000000, v34
	s_nop 0
	v_rsq_f32_e32 v44, v44
	s_nop 0
	v_pk_mul_f32 v[4:5], v[4:5], v[44:45] op_sel_hi:[1,0]
	v_pk_mul_f32 v[6:7], v[6:7], v[44:45] op_sel_hi:[1,0]
	v_pk_mul_f32 v[0:1], v[0:1], v[44:45] op_sel_hi:[1,0]
	v_pk_mul_f32 v[2:3], v[2:3], v[44:45] op_sel_hi:[1,0]
	v_pk_mul_f32 v[8:9], v[8:9], v[44:45] op_sel_hi:[1,0]
	v_pk_mul_f32 v[10:11], v[10:11], v[44:45] op_sel_hi:[1,0]
	v_pk_mul_f32 v[16:17], v[16:17], v[44:45] op_sel_hi:[1,0]
	v_pk_mul_f32 v[18:19], v[18:19], v[44:45] op_sel_hi:[1,0]
	v_pk_mul_f32 v[12:13], v[12:13], v[44:45] op_sel_hi:[1,0]
	v_pk_mul_f32 v[14:15], v[14:15], v[44:45] op_sel_hi:[1,0]
	v_pk_mul_f32 v[20:21], v[20:21], v[44:45] op_sel_hi:[1,0]
	v_pk_mul_f32 v[22:23], v[22:23], v[44:45] op_sel_hi:[1,0]
	v_pk_mul_f32 v[40:41], v[40:41], v[44:45] op_sel_hi:[1,0]
	v_pk_mul_f32 v[42:43], v[42:43], v[44:45] op_sel_hi:[1,0]
	v_pk_mul_f32 v[36:37], v[36:37], v[44:45] op_sel_hi:[1,0]
	v_pk_mul_f32 v[38:39], v[38:39], v[44:45] op_sel_hi:[1,0]
	v_cvt_pk_bf16_f32 v4, v4, v5
	v_cvt_pk_bf16_f32 v5, v6, v7
	v_cvt_pk_bf16_f32 v0, v0, v1
	v_cvt_pk_bf16_f32 v1, v2, v3
	v_cvt_pk_bf16_f32 v8, v8, v9
	v_cvt_pk_bf16_f32 v9, v10, v11
	v_cvt_pk_bf16_f32 v16, v16, v17
	v_cvt_pk_bf16_f32 v17, v18, v19
	v_cvt_pk_bf16_f32 v12, v12, v13
	v_cvt_pk_bf16_f32 v13, v14, v15
	v_cvt_pk_bf16_f32 v20, v20, v21
	v_cvt_pk_bf16_f32 v21, v22, v23
	v_cvt_pk_bf16_f32 v40, v40, v41
	v_cvt_pk_bf16_f32 v41, v42, v43
	v_cvt_pk_bf16_f32 v36, v36, v37
	v_cvt_pk_bf16_f32 v37, v38, v39
	global_store_dwordx2 v[26:27], v[4:5], off
	global_store_dwordx2 v[26:27], v[0:1], off offset:512
	global_store_dwordx2 v[26:27], v[8:9], off offset:1024
	global_store_dwordx2 v[26:27], v[16:17], off offset:1536
	global_store_dwordx2 v[26:27], v[12:13], off offset:2048
	global_store_dwordx2 v[26:27], v[20:21], off offset:2560
	global_store_dwordx2 v[26:27], v[40:41], off offset:3072
	global_store_dwordx2 v[26:27], v[36:37], off offset:3584
	v_lshl_add_u64 v[26:27], v[26:27], 0, s[6:7]
	s_branch .LBB0_77
; __device__ __forceinline__ unsigned cvtpk(float lo, float hi) { f32x2 v = {lo, hi}; bf16x2_t b = __builtin_convertvector(v, bf16x2_t); return __builtin_bit_cast(unsigned, b); }
; __device__ __forceinline__ int hw_lane() { int l; asm volatile("v_mbcnt_lo_u32_b32 %0, -1, 0\n\tv_mbcnt_hi_u32_b32 %0, -1, %0" : "=v"(l)); return l; }
; __device__ __forceinline__ void rms_row_to_bf16(const float* xrow, bf16_t* orow, int lane) {
;     const f32x4* xr = (const f32x4*)xrow + lane;
;     f32x4 v[8]; float s = 0.f;
; #pragma unroll
;     for (int j = 0; j < 8; ++j) { v[j] = xr[64 * j]; s += (v[j].x * v[j].x + v[j].y * v[j].y) + (v[j].z * v[j].z + v[j].w * v[j].w); }
;     const float rstd = 1.0f / sqrtf(wave_sum(s) * (1.0f / DM) + EPS);
;     u32x2* o8 = (u32x2*)orow + lane;
; #pragma unroll
;     for (int j = 0; j < 8; ++j) { u32x2 w; w.x = cvtpk(v[j].x * rstd, v[j].y * rstd); w.y = cvtpk(v[j].z * rstd, v[j].w * rstd); o8[64 * j] = w; }
; }
; __device__ __forceinline__ void norm_pass(const float* src, bf16_t* XN, int gw, int NGW, int lane) {
;     lane = hw_lane();
;     for (int m = gw; m < MTOK; m += NGW) rms_row_to_bf16(src + (size_t)m * DM, XN + (size_t)m * DM, lane);
; }
.Lnp_B_last:
	s_waitcnt vmcnt(8)
	v_pk_mul_f32 v[44:45], v[84:85], v[84:85]
	v_pk_fma_f32 v[44:45], v[86:87], v[86:87], v[44:45]
	v_pk_fma_f32 v[44:45], v[88:89], v[88:89], v[44:45]
	v_pk_fma_f32 v[44:45], v[90:91], v[90:91], v[44:45]
	v_pk_fma_f32 v[44:45], v[92:93], v[92:93], v[44:45]
	v_pk_fma_f32 v[44:45], v[94:95], v[94:95], v[44:45]
	v_pk_fma_f32 v[44:45], v[96:97], v[96:97], v[44:45]
	v_pk_fma_f32 v[44:45], v[98:99], v[98:99], v[44:45]
	v_pk_fma_f32 v[44:45], v[100:101], v[100:101], v[44:45]
	v_pk_fma_f32 v[44:45], v[102:103], v[102:103], v[44:45]
	v_pk_fma_f32 v[44:45], v[104:105], v[104:105], v[44:45]
	v_pk_fma_f32 v[44:45], v[106:107], v[106:107], v[44:45]
	v_pk_fma_f32 v[44:45], v[108:109], v[108:109], v[44:45]
	v_pk_fma_f32 v[44:45], v[110:111], v[110:111], v[44:45]
	v_pk_fma_f32 v[44:45], v[112:113], v[112:113], v[44:45]
	v_pk_fma_f32 v[44:45], v[114:115], v[114:115], v[44:45]
	s_nop 0
	v_add_f32_e32 v44, v44, v45
	s_nop 1
	v_add_f32_dpp v44, v44, v44 quad_perm:[1,0,3,2] row_mask:0xf bank_mask:0xf
	s_nop 1
	v_add_f32_dpp v44, v44, v44 quad_perm:[2,3,0,1] row_mask:0xf bank_mask:0xf
	s_nop 1
	v_add_f32_dpp v44, v44, v44 row_half_mirror row_mask:0xf bank_mask:0xf
	s_nop 1
	v_add_f32_dpp v44, v44, v44 row_ror:8 row_mask:0xf bank_mask:0xf
	s_nop 1
	ds_bpermute_b32 v45, v32, v44
	s_waitcnt lgkmcnt(0)
	v_add_f32_e32 v44, v44, v45
	ds_bpermute_b32 v45, v33, v44
	s_waitcnt lgkmcnt(0)
	v_add_f32_e32 v44, v44, v45
	v_fmamk_f32 v44, v44, 0x3a000000, v34
	s_nop 0
	v_rsq_f32_e32 v44, v44
	s_nop 0
	v_pk_mul_f32 v[84:85], v[84:85], v[44:45] op_sel_hi:[1,0]
	v_pk_mul_f32 v[86:87], v[86:87], v[44:45] op_sel_hi:[1,0]
	v_pk_mul_f32 v[88:89], v[88:89], v[44:45] op_sel_hi:[1,0]
	v_pk_mul_f32 v[90:91], v[90:91], v[44:45] op_sel_hi:[1,0]
	v_pk_mul_f32 v[92:93], v[92:93], v[44:45] op_sel_hi:[1,0]
	v_pk_mul_f32 v[94:95], v[94:95], v[44:45] op_sel_hi:[1,0]
	v_pk_mul_f32 v[96:97], v[96:97], v[44:45] op_sel_hi:[1,0]
	v_pk_mul_f32 v[98:99], v[98:99], v[44:45] op_sel_hi:[1,0]
	v_pk_mul_f32 v[100:101], v[100:101], v[44:45] op_sel_hi:[1,0]
	v_pk_mul_f32 v[102:103], v[102:103], v[44:45] op_sel_hi:[1,0]
	v_pk_mul_f32 v[104:105], v[104:105], v[44:45] op_sel_hi:[1,0]
	v_pk_mul_f32 v[106:107], v[106:107], v[44:45] op_sel_hi:[1,0]
	v_pk_mul_f32 v[108:109], v[108:109], v[44:45] op_sel_hi:[1,0]
	v_pk_mul_f32 v[110:111], v[110:111], v[44:45] op_sel_hi:[1,0]
	v_pk_mul_f32 v[112:113], v[112:113], v[44:45] op_sel_hi:[1,0]
	v_pk_mul_f32 v[114:115], v[114:115], v[44:45] op_sel_hi:[1,0]
	v_cvt_pk_bf16_f32 v84, v84, v85
	v_cvt_pk_bf16_f32 v85, v86, v87
	v_cvt_pk_bf16_f32 v88, v88, v89
	v_cvt_pk_bf16_f32 v89, v90, v91
	v_cvt_pk_bf16_f32 v92, v92, v93
	v_cvt_pk_bf16_f32 v93, v94, v95
	v_cvt_pk_bf16_f32 v96, v96, v97
	v_cvt_pk_bf16_f32 v97, v98, v99
	v_cvt_pk_bf16_f32 v100, v100, v101
	v_cvt_pk_bf16_f32 v101, v102, v103
	v_cvt_pk_bf16_f32 v104, v104, v105
	v_cvt_pk_bf16_f32 v105, v106, v107
	v_cvt_pk_bf16_f32 v108, v108, v109
	v_cvt_pk_bf16_f32 v109, v110, v111
	v_cvt_pk_bf16_f32 v112, v112, v113
	v_cvt_pk_bf16_f32 v113, v114, v115
	global_store_dwordx2 v[26:27], v[84:85], off
	global_store_dwordx2 v[26:27], v[88:89], off offset:512
	global_store_dwordx2 v[26:27], v[92:93], off offset:1024
	global_store_dwordx2 v[26:27], v[96:97], off offset:1536
	global_store_dwordx2 v[26:27], v[100:101], off offset:2048
	global_store_dwordx2 v[26:27], v[104:105], off offset:2560
	global_store_dwordx2 v[26:27], v[108:109], off offset:3072
	global_store_dwordx2 v[26:27], v[112:113], off offset:3584
	v_lshl_add_u64 v[26:27], v[26:27], 0, s[6:7]
	s_branch .LBB0_77
.Lnp_A_last:
	s_waitcnt vmcnt(8)
	v_pk_mul_f32 v[44:45], v[4:5], v[4:5]
	v_pk_fma_f32 v[44:45], v[6:7], v[6:7], v[44:45]
	v_pk_fma_f32 v[44:45], v[0:1], v[0:1], v[44:45]
	v_pk_fma_f32 v[44:45], v[2:3], v[2:3], v[44:45]
	v_pk_fma_f32 v[44:45], v[8:9], v[8:9], v[44:45]
	v_pk_fma_f32 v[44:45], v[10:11], v[10:11], v[44:45]
	v_pk_fma_f32 v[44:45], v[16:17], v[16:17], v[44:45]
	v_pk_fma_f32 v[44:45], v[18:19], v[18:19], v[44:45]
	v_pk_fma_f32 v[44:45], v[12:13], v[12:13], v[44:45]
	v_pk_fma_f32 v[44:45], v[14:15], v[14:15], v[44:45]
	v_pk_fma_f32 v[44:45], v[20:21], v[20:21], v[44:45]
	v_pk_fma_f32 v[44:45], v[22:23], v[22:23], v[44:45]
	v_pk_fma_f32 v[44:45], v[40:41], v[40:41], v[44:45]
	v_pk_fma_f32 v[44:45], v[42:43], v[42:43], v[44:45]
	v_pk_fma_f32 v[44:45], v[36:37], v[36:37], v[44:45]
	v_pk_fma_f32 v[44:45], v[38:39], v[38:39], v[44:45]
	s_nop 0
	v_add_f32_e32 v44, v44, v45
	s_nop 1
	v_add_f32_dpp v44, v44, v44 quad_perm:[1,0,3,2] row_mask:0xf bank_mask:0xf
	s_nop 1
	v_add_f32_dpp v44, v44, v44 quad_perm:[2,3,0,1] row_mask:0xf bank_mask:0xf
	s_nop 1
	v_add_f32_dpp v44, v44, v44 row_half_mirror row_mask:0xf bank_mask:0xf
	s_nop 1
	v_add_f32_dpp v44, v44, v44 row_ror:8 row_mask:0xf bank_mask:0xf
	s_nop 1
	ds_bpermute_b32 v45, v32, v44
	s_waitcnt lgkmcnt(0)
	v_add_f32_e32 v44, v44, v45
	ds_bpermute_b32 v45, v33, v44
	s_waitcnt lgkmcnt(0)
	v_add_f32_e32 v44, v44, v45
	v_fmamk_f32 v44, v44, 0x3a000000, v34
	s_nop 0
	v_rsq_f32_e32 v44, v44
	s_nop 0
	v_pk_mul_f32 v[4:5], v[4:5], v[44:45] op_sel_hi:[1,0]
	v_pk_mul_f32 v[6:7], v[6:7], v[44:45] op_sel_hi:[1,0]
	v_pk_mul_f32 v[0:1], v[0:1], v[44:45] op_sel_hi:[1,0]
	v_pk_mul_f32 v[2:3], v[2:3], v[44:45] op_sel_hi:[1,0]
	v_pk_mul_f32 v[8:9], v[8:9], v[44:45] op_sel_hi:[1,0]
	v_pk_mul_f32 v[10:11], v[10:11], v[44:45] op_sel_hi:[1,0]
	v_pk_mul_f32 v[16:17], v[16:17], v[44:45] op_sel_hi:[1,0]
	v_pk_mul_f32 v[18:19], v[18:19], v[44:45] op_sel_hi:[1,0]
	v_pk_mul_f32 v[12:13], v[12:13], v[44:45] op_sel_hi:[1,0]
	v_pk_mul_f32 v[14:15], v[14:15], v[44:45] op_sel_hi:[1,0]
	v_pk_mul_f32 v[20:21], v[20:21], v[44:45] op_sel_hi:[1,0]
	v_pk_mul_f32 v[22:23], v[22:23], v[44:45] op_sel_hi:[1,0]
	v_pk_mul_f32 v[40:41], v[40:41], v[44:45] op_sel_hi:[1,0]
	v_pk_mul_f32 v[42:43], v[42:43], v[44:45] op_sel_hi:[1,0]
	v_pk_mul_f32 v[36:37], v[36:37], v[44:45] op_sel_hi:[1,0]
	v_pk_mul_f32 v[38:39], v[38:39], v[44:45] op_sel_hi:[1,0]
	v_cvt_pk_bf16_f32 v4, v4, v5
	v_cvt_pk_bf16_f32 v5, v6, v7
	v_cvt_pk_bf16_f32 v0, v0, v1
	v_cvt_pk_bf16_f32 v1, v2, v3
	v_cvt_pk_bf16_f32 v8, v8, v9
	v_cvt_pk_bf16_f32 v9, v10, v11
	v_cvt_pk_bf16_f32 v16, v16, v17
	v_cvt_pk_bf16_f32 v17, v18, v19
	v_cvt_pk_bf16_f32 v12, v12, v13
	v_cvt_pk_bf16_f32 v13, v14, v15
	v_cvt_pk_bf16_f32 v20, v20, v21
	v_cvt_pk_bf16_f32 v21, v22, v23
	v_cvt_pk_bf16_f32 v40, v40, v41
	v_cvt_pk_bf16_f32 v41, v42, v43
	v_cvt_pk_bf16_f32 v36, v36, v37
	v_cvt_pk_bf16_f32 v37, v38, v39
	global_store_dwordx2 v[26:27], v[4:5], off
	global_store_dwordx2 v[26:27], v[0:1], off offset:512
	global_store_dwordx2 v[26:27], v[8:9], off offset:1024
	global_store_dwordx2 v[26:27], v[16:17], off offset:1536
	global_store_dwordx2 v[26:27], v[12:13], off offset:2048
	global_store_dwordx2 v[26:27], v[20:21], off offset:2560
	global_store_dwordx2 v[26:27], v[40:41], off offset:3072
	global_store_dwordx2 v[26:27], v[36:37], off offset:3584
	v_lshl_add_u64 v[26:27], v[26:27], 0, s[6:7]

; __device__ __forceinline__ f32x4 mfma16(bf16x8 a, bf16x8 b, f32x4 c) { return __builtin_amdgcn_mfma_f32_16x16x32_bf16(a, b, c, 0, 0, 0); }
; __device__ __forceinline__ void phase_qkrope_gla_prep(const Params& p, LAS unsigned char* lds, int wave, int lane) {
;     ...
;         for (int bc = blockIdx.x; bc < 256; bc += gridDim.x) {
;             const int m0 = bc * 64;
;             __syncthreads();
;             f32x4 accg[4];
; #pragma unroll
;             for (int ti = 0; ti < 4; ++ti) accg[ti] = (f32x4){0.f, 0.f, 0.f, 0.f};
; #pragma unroll
;             for (int k8 = 0; k8 < 8; ++k8) { const int kk = 256 * wave + 32 * k8 + 8 * g;
;                 const bf16x8 bfr = *(const bf16x8*)(wgl + (size_t)fr * DM + kk);
; #pragma unroll
;                 for (int ti = 0; ti < 4; ++ti) { const bf16x8 afr = *(const bf16x8*)(X1B + (size_t)(m0 + 16 * ti + fr) * DM + kk);
;                     accg[ti] = mfma16(afr, bfr, accg[ti]); } }
; #pragma unroll
;             for (int ti = 0; ti < 4; ++ti)
; #pragma unroll
;                 for (int jj = 0; jj < 4; ++jj) part[(wave * 64 + 16 * ti + 4 * g + jj) * 16 + fr] = accg[ti][jj];
.LBB0_518:
	v_add_u32_e32 v78, s0, v52
	v_subrev_u32_e32 v0, 63, v78
	v_ashrrev_i32_e32 v1, 31, v0
	v_lshlrev_b64 v[0:1], 12, v[0:1]
	v_lshl_add_u64 v[0:1], v[12:13], 0, v[0:1]
	v_subrev_u32_e32 v2, 47, v78
	v_ashrrev_i32_e32 v3, 31, v2
	v_lshlrev_b64 v[2:3], 12, v[2:3]
	v_lshl_add_u64 v[2:3], v[12:13], 0, v[2:3]
	v_subrev_u32_e32 v46, 31, v78
	v_add_u32_e32 v48, -15, v78
	v_ashrrev_i32_e32 v47, 31, v46
	v_ashrrev_i32_e32 v49, 31, v48
	v_lshlrev_b64 v[46:47], 12, v[46:47]
	v_lshlrev_b64 v[48:49], 12, v[48:49]
	v_lshl_add_u64 v[46:47], v[12:13], 0, v[46:47]
	v_lshl_add_u64 v[48:49], v[12:13], 0, v[48:49]
	s_sub_i32 s19, s0, 63
	global_load_dwordx4 v[86:89], v[10:11], off
	global_load_dwordx4 v[118:121], v[0:1], off
	global_load_dwordx4 v[150:153], v[2:3], off
	global_load_dwordx4 v[182:185], v[46:47], off
	global_load_dwordx4 v[214:217], v[48:49], off
	global_load_dwordx4 v[90:93], v[10:11], off offset:64
	global_load_dwordx4 v[122:125], v[0:1], off offset:64
	global_load_dwordx4 v[154:157], v[2:3], off offset:64
	global_load_dwordx4 v[186:189], v[46:47], off offset:64
	global_load_dwordx4 v[218:221], v[48:49], off offset:64
	global_load_dwordx4 v[94:97], v[10:11], off offset:128
	global_load_dwordx4 v[126:129], v[0:1], off offset:128
	global_load_dwordx4 v[158:161], v[2:3], off offset:128
	global_load_dwordx4 v[190:193], v[46:47], off offset:128
	global_load_dwordx4 v[222:225], v[48:49], off offset:128
	global_load_dwordx4 v[98:101], v[10:11], off offset:192
	global_load_dwordx4 v[130:133], v[0:1], off offset:192
	global_load_dwordx4 v[162:165], v[2:3], off offset:192
	global_load_dwordx4 v[194:197], v[46:47], off offset:192
	global_load_dwordx4 v[226:229], v[48:49], off offset:192
	global_load_dwordx4 v[102:105], v[10:11], off offset:256
	global_load_dwordx4 v[134:137], v[0:1], off offset:256
	global_load_dwordx4 v[166:169], v[2:3], off offset:256
	global_load_dwordx4 v[198:201], v[46:47], off offset:256
	global_load_dwordx4 v[230:233], v[48:49], off offset:256
	global_load_dwordx4 v[106:109], v[10:11], off offset:320
	global_load_dwordx4 v[138:141], v[0:1], off offset:320
	global_load_dwordx4 v[170:173], v[2:3], off offset:320
	global_load_dwordx4 v[202:205], v[46:47], off offset:320
	global_load_dwordx4 v[234:237], v[48:49], off offset:320
	global_load_dwordx4 v[110:113], v[10:11], off offset:384
	global_load_dwordx4 v[142:145], v[0:1], off offset:384
	global_load_dwordx4 v[174:177], v[2:3], off offset:384
	global_load_dwordx4 v[206:209], v[46:47], off offset:384
	global_load_dwordx4 v[238:241], v[48:49], off offset:384
	global_load_dwordx4 v[114:117], v[10:11], off offset:448
	global_load_dwordx4 v[146:149], v[0:1], off offset:448
	global_load_dwordx4 v[178:181], v[2:3], off offset:448
	global_load_dwordx4 v[210:213], v[46:47], off offset:448
	global_load_dwordx4 v[242:245], v[48:49], off offset:448
	s_barrier
	s_waitcnt vmcnt(35)
	v_mfma_f32_16x16x32_bf16 v[66:69], v[118:121], v[86:89], 0
	v_mfma_f32_16x16x32_bf16 v[0:3], v[150:153], v[86:89], 0
	v_mfma_f32_16x16x32_bf16 v[70:73], v[182:185], v[86:89], 0
	v_mfma_f32_16x16x32_bf16 v[46:49], v[214:217], v[86:89], 0
	s_waitcnt vmcnt(30)
	v_mfma_f32_16x16x32_bf16 v[66:69], v[122:125], v[90:93], v[66:69]
	v_mfma_f32_16x16x32_bf16 v[0:3], v[154:157], v[90:93], v[0:3]
	v_mfma_f32_16x16x32_bf16 v[70:73], v[186:189], v[90:93], v[70:73]
	v_mfma_f32_16x16x32_bf16 v[46:49], v[218:221], v[90:93], v[46:49]
	s_waitcnt vmcnt(25)
	v_mfma_f32_16x16x32_bf16 v[66:69], v[126:129], v[94:97], v[66:69]
	v_mfma_f32_16x16x32_bf16 v[0:3], v[158:161], v[94:97], v[0:3]
	v_mfma_f32_16x16x32_bf16 v[70:73], v[190:193], v[94:97], v[70:73]
	v_mfma_f32_16x16x32_bf16 v[46:49], v[222:225], v[94:97], v[46:49]
	s_waitcnt vmcnt(20)
	v_mfma_f32_16x16x32_bf16 v[66:69], v[130:133], v[98:101], v[66:69]
	v_mfma_f32_16x16x32_bf16 v[0:3], v[162:165], v[98:101], v[0:3]
	v_mfma_f32_16x16x32_bf16 v[70:73], v[194:197], v[98:101], v[70:73]
	v_mfma_f32_16x16x32_bf16 v[46:49], v[226:229], v[98:101], v[46:49]
	s_waitcnt vmcnt(15)
	v_mfma_f32_16x16x32_bf16 v[66:69], v[134:137], v[102:105], v[66:69]
	v_mfma_f32_16x16x32_bf16 v[0:3], v[166:169], v[102:105], v[0:3]
	v_mfma_f32_16x16x32_bf16 v[70:73], v[198:201], v[102:105], v[70:73]
	v_mfma_f32_16x16x32_bf16 v[46:49], v[230:233], v[102:105], v[46:49]
	s_waitcnt vmcnt(10)
	v_mfma_f32_16x16x32_bf16 v[66:69], v[138:141], v[106:109], v[66:69]
	v_mfma_f32_16x16x32_bf16 v[0:3], v[170:173], v[106:109], v[0:3]
	v_mfma_f32_16x16x32_bf16 v[70:73], v[202:205], v[106:109], v[70:73]
	v_mfma_f32_16x16x32_bf16 v[46:49], v[234:237], v[106:109], v[46:49]
	s_waitcnt vmcnt(5)
	v_mfma_f32_16x16x32_bf16 v[66:69], v[142:145], v[110:113], v[66:69]
	v_mfma_f32_16x16x32_bf16 v[0:3], v[174:177], v[110:113], v[0:3]
	v_mfma_f32_16x16x32_bf16 v[70:73], v[206:209], v[110:113], v[70:73]
	v_mfma_f32_16x16x32_bf16 v[46:49], v[238:241], v[110:113], v[46:49]
	s_waitcnt vmcnt(0)
	v_mfma_f32_16x16x32_bf16 v[66:69], v[146:149], v[114:117], v[66:69]
	v_mfma_f32_16x16x32_bf16 v[0:3], v[178:181], v[114:117], v[0:3]
	v_mfma_f32_16x16x32_bf16 v[70:73], v[210:213], v[114:117], v[70:73]
	v_mfma_f32_16x16x32_bf16 v[46:49], v[242:245], v[114:117], v[46:49]
	s_nop 7
	ds_write2_b32 v55, v66, v67 offset1:16
	ds_write2_b32 v55, v68, v69 offset0:32 offset1:48
	ds_write2_b32 v58, v0, v1 offset1:16
	ds_write2_b32 v58, v2, v3 offset0:32 offset1:48
	s_nop 1
	ds_write2_b32 v59, v70, v71 offset1:16
	ds_write2_b32 v59, v72, v73 offset0:32 offset1:48
	ds_write2_b32 v60, v46, v47 offset1:16
	ds_write2_b32 v60, v48, v49 offset0:32 offset1:48
	s_waitcnt lgkmcnt(0)
	s_barrier
; __device__ __forceinline__ float fexp(float x) { return __builtin_amdgcn_exp2f(x * 1.44269504089f); }
; __device__ __forceinline__ void phase_qkrope_gla_prep(const Params& p, LAS unsigned char* lds, int wave, int lane) {
;     ...
;             __syncthreads();
; #pragma unroll
;             for (int i = 0; i < 2; ++i) { const int idx = tid + 512 * i, tok = idx >> 4; float sum = 0.f;
; #pragma unroll
;                 for (int w = 0; w < 8; ++w) sum += part[w * 1024 + idx];
;                 gl[idx] = sum / sqrtf(rss1[m0 + tok] * (1.0f / DM) + EPS); }
;             float gu[16];
; #pragma unroll
;             for (int r = 0; r < 16; ++r) gu[r] = p.gup[r * 512 + d];
;             const float bias = p.gbias[d];
;             __syncthreads();
;             float bl[64]; float run = 0.f;
; #pragma unroll
;             for (int t = 0; t < 64; ++t) { float lg = bias;
; #pragma unroll
;                 for (int r = 0; r < 16; ++r) lg += gl[t * 16 + r] * gu[r];
;                 const float ls = fminf(lg, 0.f) - 0.69314718056f * __builtin_amdgcn_logf(1.0f + fexp(-fabsf(lg)));
;                 run += ls * (1.0f / 16.0f); bl[t] = run; }
	ds_read2st64_b32 v[0:1], v6 offset1:8
	ds_read2st64_b32 v[2:3], v6 offset0:16 offset1:24
	v_add_u32_e32 v70, s19, v53
	v_ashrrev_i32_e32 v71, 31, v70
	v_lshl_add_u64 v[70:71], v[70:71], 2, s[16:17]
	s_waitcnt lgkmcnt(1)
	v_add_f32_e32 v0, 0, v0
	s_waitcnt lgkmcnt(0)
	v_add_f32_e32 v0, v0, v2
	global_load_dword v2, v[70:71], off
	ds_read2st64_b32 v[46:47], v6 offset0:32 offset1:40
	ds_read2st64_b32 v[48:49], v6 offset0:48 offset1:56
	ds_read2st64_b32 v[62:63], v6 offset0:64 offset1:72
	ds_read2st64_b32 v[64:65], v6 offset0:80 offset1:88
	ds_read2st64_b32 v[66:67], v6 offset0:96 offset1:104
	s_waitcnt lgkmcnt(4)
	v_add_f32_e32 v0, v0, v46
	s_waitcnt lgkmcnt(3)
	v_add_f32_e32 v0, v0, v48
	s_waitcnt lgkmcnt(2)
	v_add_f32_e32 v0, v0, v62
	ds_read2st64_b32 v[68:69], v6 offset0:112 offset1:120
	s_waitcnt lgkmcnt(2)
	v_add_f32_e32 v0, v0, v64
	s_waitcnt lgkmcnt(1)
	v_add_f32_e32 v0, v0, v66
	s_waitcnt lgkmcnt(0)
	v_add_f32_e32 v0, v0, v68
	s_waitcnt vmcnt(0)
	v_fmamk_f32 v2, v2, 0x3a000000, v56
	s_nop 0
	v_rsq_f32_e32 v2, v2
	s_nop 1
	s_nop 0
	v_mov_b32_e32 v2, v2
	s_nop 0
	v_mul_f32_e32 v2, v0, v2
	v_add_f32_e32 v0, 0, v1
	v_add_f32_e32 v0, v0, v3
	v_add_f32_e32 v0, v0, v47
	v_add_f32_e32 v0, v0, v49
	v_add_f32_e32 v0, v0, v63
	v_add_f32_e32 v0, v0, v65
	v_add_f32_e32 v0, v0, v67
	v_add_f32_e32 v3, v0, v69
	v_add_u32_e32 v0, s19, v54
	v_ashrrev_i32_e32 v1, 31, v0
	v_lshl_add_u64 v[0:1], v[0:1], 2, s[16:17]
	global_load_dword v0, v[0:1], off
	s_waitcnt vmcnt(0)
	v_fmamk_f32 v0, v0, 0x3a000000, v56
	s_nop 0
	v_rsq_f32_e32 v0, v0
	s_nop 1
	s_nop 0
	v_mov_b32_e32 v0, v0
	s_nop 0
	v_mul_f32_e32 v0, v3, v0
	ds_write2st64_b32 v6, v2, v0 offset0:128 offset1:136
	global_load_dword v0, v[14:15], off
	global_load_dword v1, v[14:15], off offset:2048
	global_load_dword v2, v[16:17], off
	global_load_dword v3, v[18:19], off
	global_load_dword v133, v[20:21], off
	global_load_dword v130, v[22:23], off
	global_load_dword v131, v[24:25], off
	global_load_dword v132, v[26:27], off
	global_load_dword v126, v[28:29], off
	global_load_dword v127, v[30:31], off
	global_load_dword v128, v[32:33], off
	global_load_dword v129, v[34:35], off
	global_load_dword v47, v[36:37], off
	global_load_dword v76, v[38:39], off
	global_load_dword v124, v[40:41], off
	global_load_dword v125, v[42:43], off
	global_load_dword v46, v[44:45], off
	s_waitcnt lgkmcnt(0)
	s_barrier
	ds_read_b128 v[62:65], v7 offset:32768
	ds_read_b128 v[66:69], v7 offset:32784
	ds_read_b128 v[70:73], v7 offset:32800
	ds_read_b128 v[78:81], v7 offset:32816
	ds_read_b128 v[134:137], v7 offset:36096
	s_waitcnt vmcnt(0) lgkmcnt(4)
	v_fma_f32 v48, v0, v62, v46
	v_fmac_f32_e32 v48, v1, v63
	v_fmac_f32_e32 v48, v2, v64
	v_fmac_f32_e32 v48, v3, v65
	s_waitcnt lgkmcnt(3)
	v_fmac_f32_e32 v48, v133, v66
	v_fmac_f32_e32 v48, v130, v67
	v_fmac_f32_e32 v48, v131, v68
	v_fmac_f32_e32 v48, v132, v69
	s_waitcnt lgkmcnt(2)
	v_fmac_f32_e32 v48, v126, v70
	v_fmac_f32_e32 v48, v127, v71
	v_fmac_f32_e32 v48, v128, v72
	v_fmac_f32_e32 v48, v129, v73
	s_waitcnt lgkmcnt(1)
	v_fmac_f32_e32 v48, v47, v78
	v_fmac_f32_e32 v48, v76, v79
	v_fmac_f32_e32 v48, v124, v80
	v_fmac_f32_e32 v48, v125, v81
	v_min_f32_e32 v49, 0, v48
	v_mul_f32_e64 v48, |v48|, s3
	v_exp_f32_e32 v48, v48
	ds_read_b128 v[62:65], v7 offset:32832
	v_add_f32_e32 v48, 1.0, v48
	v_log_f32_e32 v48, v48
	s_nop 0
	v_fmac_f32_e32 v49, 0xbf317218, v48
	s_waitcnt lgkmcnt(0)
	v_fma_f32 v48, v0, v62, v46
	v_fmac_f32_e32 v48, v1, v63
	v_fmac_f32_e32 v48, v2, v64
	v_fmac_f32_e32 v48, v3, v65
	ds_read_b128 v[62:65], v7 offset:32848
	v_fma_f32 v100, v49, s21, 0
	s_waitcnt lgkmcnt(0)
	v_fmac_f32_e32 v48, v133, v62
	v_fmac_f32_e32 v48, v130, v63
	v_fmac_f32_e32 v48, v131, v64
	v_fmac_f32_e32 v48, v132, v65
	ds_read_b128 v[62:65], v7 offset:32864
	s_waitcnt lgkmcnt(0)
	v_fmac_f32_e32 v48, v126, v62
	v_fmac_f32_e32 v48, v127, v63
	v_fmac_f32_e32 v48, v128, v64
	v_fmac_f32_e32 v48, v129, v65
	ds_read_b128 v[62:65], v7 offset:32880
	s_waitcnt lgkmcnt(0)
	v_fmac_f32_e32 v48, v47, v62
	v_fmac_f32_e32 v48, v76, v63
	v_fmac_f32_e32 v48, v124, v64
	v_fmac_f32_e32 v48, v125, v65
	v_min_f32_e32 v49, 0, v48
	v_mul_f32_e64 v48, |v48|, s3
	v_exp_f32_e32 v48, v48
	ds_read_b128 v[62:65], v7 offset:32896
	v_add_f32_e32 v48, 1.0, v48
	v_log_f32_e32 v48, v48
	s_nop 0
	v_fmac_f32_e32 v49, 0xbf317218, v48
	s_waitcnt lgkmcnt(0)
	v_fma_f32 v48, v0, v62, v46
	v_fmac_f32_e32 v48, v1, v63
	v_fmac_f32_e32 v48, v2, v64
	v_fmac_f32_e32 v48, v3, v65
	ds_read_b128 v[62:65], v7 offset:32912
	v_fmamk_f32 v102, v49, 0x3d800000, v100
	s_waitcnt lgkmcnt(0)
	v_fmac_f32_e32 v48, v133, v62
	v_fmac_f32_e32 v48, v130, v63
	v_fmac_f32_e32 v48, v131, v64
	v_fmac_f32_e32 v48, v132, v65
	ds_read_b128 v[62:65], v7 offset:32928
	s_waitcnt lgkmcnt(0)
	v_fmac_f32_e32 v48, v126, v62
	v_fmac_f32_e32 v48, v127, v63
	v_fmac_f32_e32 v48, v128, v64
	v_fmac_f32_e32 v48, v129, v65
	ds_read_b128 v[62:65], v7 offset:32944
	s_waitcnt lgkmcnt(0)
	v_fmac_f32_e32 v48, v47, v62
	v_fmac_f32_e32 v48, v76, v63
	v_fmac_f32_e32 v48, v124, v64
	v_fmac_f32_e32 v48, v125, v65
	v_min_f32_e32 v49, 0, v48
	v_mul_f32_e64 v48, |v48|, s3
	v_exp_f32_e32 v48, v48
	ds_read_b128 v[62:65], v7 offset:32960
	v_add_f32_e32 v48, 1.0, v48
	v_log_f32_e32 v48, v48
	s_nop 0
	v_fmac_f32_e32 v49, 0xbf317218, v48
	s_waitcnt lgkmcnt(0)
	v_fma_f32 v48, v0, v62, v46
	v_fmac_f32_e32 v48, v1, v63
	v_fmac_f32_e32 v48, v2, v64
	v_fmac_f32_e32 v48, v3, v65
	ds_read_b128 v[62:65], v7 offset:32976
	v_fmamk_f32 v104, v49, 0x3d800000, v102
	s_waitcnt lgkmcnt(0)
	v_fmac_f32_e32 v48, v133, v62
	v_fmac_f32_e32 v48, v130, v63
	v_fmac_f32_e32 v48, v131, v64
	v_fmac_f32_e32 v48, v132, v65
	ds_read_b128 v[62:65], v7 offset:32992
	s_waitcnt lgkmcnt(0)
; __device__ __forceinline__ float fexp(float x) { return __builtin_amdgcn_exp2f(x * 1.44269504089f); }
; __device__ __forceinline__ void phase_qkrope_gla_prep(const Params& p, LAS unsigned char* lds, int wave, int lane) {
;     ...
;             for (int t = 0; t < 64; ++t) { float lg = bias;
; #pragma unroll
;                 for (int r = 0; r < 16; ++r) lg += gl[t * 16 + r] * gu[r];
;                 const float ls = fminf(lg, 0.f) - 0.69314718056f * __builtin_amdgcn_logf(1.0f + fexp(-fabsf(lg)));
;                 run += ls * (1.0f / 16.0f); bl[t] = run; }
	v_fmac_f32_e32 v48, v126, v62
	v_fmac_f32_e32 v48, v127, v63
	v_fmac_f32_e32 v48, v128, v64
	v_fmac_f32_e32 v48, v129, v65
	ds_read_b128 v[62:65], v7 offset:33008
	s_waitcnt lgkmcnt(0)
	v_fmac_f32_e32 v48, v47, v62
	v_fmac_f32_e32 v48, v76, v63
	v_fmac_f32_e32 v48, v124, v64
	v_fmac_f32_e32 v48, v125, v65
	v_min_f32_e32 v49, 0, v48
	v_mul_f32_e64 v48, |v48|, s3
	v_exp_f32_e32 v48, v48
	ds_read_b128 v[62:65], v7 offset:33024
	v_add_f32_e32 v48, 1.0, v48
	v_log_f32_e32 v48, v48
	s_nop 0
	v_fmac_f32_e32 v49, 0xbf317218, v48
	s_waitcnt lgkmcnt(0)
	v_fma_f32 v48, v0, v62, v46
	v_fmac_f32_e32 v48, v1, v63
	v_fmac_f32_e32 v48, v2, v64
	v_fmac_f32_e32 v48, v3, v65
	ds_read_b128 v[62:65], v7 offset:33040
	v_fmamk_f32 v107, v49, 0x3d800000, v104
	s_waitcnt lgkmcnt(0)
	v_fmac_f32_e32 v48, v133, v62
	v_fmac_f32_e32 v48, v130, v63
	v_fmac_f32_e32 v48, v131, v64
	v_fmac_f32_e32 v48, v132, v65
	ds_read_b128 v[62:65], v7 offset:33056
	s_waitcnt lgkmcnt(0)
	v_fmac_f32_e32 v48, v126, v62
	v_fmac_f32_e32 v48, v127, v63
	v_fmac_f32_e32 v48, v128, v64
	v_fmac_f32_e32 v48, v129, v65
	ds_read_b128 v[62:65], v7 offset:33072
	s_waitcnt lgkmcnt(0)
	v_fmac_f32_e32 v48, v47, v62
	v_fmac_f32_e32 v48, v76, v63
	v_fmac_f32_e32 v48, v124, v64
	v_fmac_f32_e32 v48, v125, v65
	v_min_f32_e32 v49, 0, v48
	v_mul_f32_e64 v48, |v48|, s3
	v_exp_f32_e32 v48, v48
	ds_read_b128 v[62:65], v7 offset:33088
	v_add_f32_e32 v48, 1.0, v48
	v_log_f32_e32 v48, v48
	s_nop 0
	v_fmac_f32_e32 v49, 0xbf317218, v48
	s_waitcnt lgkmcnt(0)
	v_fma_f32 v48, v0, v62, v46
	v_fmac_f32_e32 v48, v1, v63
	v_fmac_f32_e32 v48, v2, v64
	v_fmac_f32_e32 v48, v3, v65
	ds_read_b128 v[62:65], v7 offset:33104
	v_fmamk_f32 v109, v49, 0x3d800000, v107
	s_waitcnt lgkmcnt(0)
	v_fmac_f32_e32 v48, v133, v62
	v_fmac_f32_e32 v48, v130, v63
	v_fmac_f32_e32 v48, v131, v64
	v_fmac_f32_e32 v48, v132, v65
	ds_read_b128 v[62:65], v7 offset:33120
	s_waitcnt lgkmcnt(0)
	v_fmac_f32_e32 v48, v126, v62
	v_fmac_f32_e32 v48, v127, v63
	v_fmac_f32_e32 v48, v128, v64
	v_fmac_f32_e32 v48, v129, v65
	ds_read_b128 v[62:65], v7 offset:33136
	s_waitcnt lgkmcnt(0)
	v_fmac_f32_e32 v48, v47, v62
	v_fmac_f32_e32 v48, v76, v63
	v_fmac_f32_e32 v48, v124, v64
	v_fmac_f32_e32 v48, v125, v65
	v_min_f32_e32 v49, 0, v48
	v_mul_f32_e64 v48, |v48|, s3
	v_exp_f32_e32 v48, v48
	ds_read_b128 v[62:65], v7 offset:33152
	v_add_f32_e32 v48, 1.0, v48
	v_log_f32_e32 v48, v48
	s_nop 0
	v_fmac_f32_e32 v49, 0xbf317218, v48
	s_waitcnt lgkmcnt(0)
	v_fma_f32 v48, v0, v62, v46
	v_fmac_f32_e32 v48, v1, v63
	v_fmac_f32_e32 v48, v2, v64
	v_fmac_f32_e32 v48, v3, v65
	ds_read_b128 v[62:65], v7 offset:33168
	v_fmamk_f32 v111, v49, 0x3d800000, v109
	s_waitcnt lgkmcnt(0)
	v_fmac_f32_e32 v48, v133, v62
	v_fmac_f32_e32 v48, v130, v63
	v_fmac_f32_e32 v48, v131, v64
	v_fmac_f32_e32 v48, v132, v65
	ds_read_b128 v[62:65], v7 offset:33184
	s_waitcnt lgkmcnt(0)
	v_fmac_f32_e32 v48, v126, v62
	v_fmac_f32_e32 v48, v127, v63
	v_fmac_f32_e32 v48, v128, v64
	v_fmac_f32_e32 v48, v129, v65
	ds_read_b128 v[62:65], v7 offset:33200
	s_waitcnt lgkmcnt(0)
	v_fmac_f32_e32 v48, v47, v62
	v_fmac_f32_e32 v48, v76, v63
	v_fmac_f32_e32 v48, v124, v64
	v_fmac_f32_e32 v48, v125, v65
	v_min_f32_e32 v49, 0, v48
	v_mul_f32_e64 v48, |v48|, s3
	v_exp_f32_e32 v48, v48
	ds_read_b128 v[62:65], v7 offset:33216
	v_add_f32_e32 v48, 1.0, v48
	v_log_f32_e32 v48, v48
	s_nop 0
	v_fmac_f32_e32 v49, 0xbf317218, v48
	s_waitcnt lgkmcnt(0)
	v_fma_f32 v48, v0, v62, v46
	v_fmac_f32_e32 v48, v1, v63
	v_fmac_f32_e32 v48, v2, v64
	v_fmac_f32_e32 v48, v3, v65
	ds_read_b128 v[62:65], v7 offset:33232
	v_fmamk_f32 v112, v49, 0x3d800000, v111
	s_waitcnt lgkmcnt(0)
	v_fmac_f32_e32 v48, v133, v62
	v_fmac_f32_e32 v48, v130, v63
	v_fmac_f32_e32 v48, v131, v64
	v_fmac_f32_e32 v48, v132, v65
	ds_read_b128 v[62:65], v7 offset:33248
	s_waitcnt lgkmcnt(0)
	v_fmac_f32_e32 v48, v126, v62
	v_fmac_f32_e32 v48, v127, v63
	v_fmac_f32_e32 v48, v128, v64
	v_fmac_f32_e32 v48, v129, v65
	ds_read_b128 v[62:65], v7 offset:33264
	s_waitcnt lgkmcnt(0)
	v_fmac_f32_e32 v48, v47, v62
	v_fmac_f32_e32 v48, v76, v63
	v_fmac_f32_e32 v48, v124, v64
	v_fmac_f32_e32 v48, v125, v65
	v_min_f32_e32 v49, 0, v48
	v_mul_f32_e64 v48, |v48|, s3
	v_exp_f32_e32 v48, v48
	ds_read_b128 v[62:65], v7 offset:33280
	v_add_f32_e32 v48, 1.0, v48
	v_log_f32_e32 v48, v48
	s_nop 0
	v_fmac_f32_e32 v49, 0xbf317218, v48
	s_waitcnt lgkmcnt(0)
	v_fma_f32 v48, v0, v62, v46
	v_fmac_f32_e32 v48, v1, v63
	v_fmac_f32_e32 v48, v2, v64
	v_fmac_f32_e32 v48, v3, v65
	ds_read_b128 v[62:65], v7 offset:33296
	v_fmamk_f32 v114, v49, 0x3d800000, v112
	s_waitcnt lgkmcnt(0)
	v_fmac_f32_e32 v48, v133, v62
	v_fmac_f32_e32 v48, v130, v63
	v_fmac_f32_e32 v48, v131, v64
	v_fmac_f32_e32 v48, v132, v65
	ds_read_b128 v[62:65], v7 offset:33312
	s_waitcnt lgkmcnt(0)
	v_fmac_f32_e32 v48, v126, v62
	v_fmac_f32_e32 v48, v127, v63
	v_fmac_f32_e32 v48, v128, v64
	v_fmac_f32_e32 v48, v129, v65
	ds_read_b128 v[62:65], v7 offset:33328
	s_waitcnt lgkmcnt(0)
	v_fmac_f32_e32 v48, v47, v62
	v_fmac_f32_e32 v48, v76, v63
	v_fmac_f32_e32 v48, v124, v64
	v_fmac_f32_e32 v48, v125, v65
	v_min_f32_e32 v49, 0, v48
	v_mul_f32_e64 v48, |v48|, s3
	v_exp_f32_e32 v48, v48
	ds_read_b128 v[62:65], v7 offset:33344
	v_add_f32_e32 v48, 1.0, v48
	v_log_f32_e32 v48, v48
	s_nop 0
	v_fmac_f32_e32 v49, 0xbf317218, v48
	s_waitcnt lgkmcnt(0)
	v_fma_f32 v48, v0, v62, v46
	v_fmac_f32_e32 v48, v1, v63
	v_fmac_f32_e32 v48, v2, v64
	v_fmac_f32_e32 v48, v3, v65
	ds_read_b128 v[62:65], v7 offset:33360
	v_fmamk_f32 v116, v49, 0x3d800000, v114
	s_waitcnt lgkmcnt(0)
	v_fmac_f32_e32 v48, v133, v62
	v_fmac_f32_e32 v48, v130, v63
	v_fmac_f32_e32 v48, v131, v64
	v_fmac_f32_e32 v48, v132, v65
	ds_read_b128 v[62:65], v7 offset:33376
	s_waitcnt lgkmcnt(0)
; __device__ __forceinline__ float fexp(float x) { return __builtin_amdgcn_exp2f(x * 1.44269504089f); }
; __device__ __forceinline__ void phase_qkrope_gla_prep(const Params& p, LAS unsigned char* lds, int wave, int lane) {
;     ...
;             float bl[64]; float run = 0.f;
; #pragma unroll
;             for (int t = 0; t < 64; ++t) { float lg = bias;
; #pragma unroll
;                 for (int r = 0; r < 16; ++r) lg += gl[t * 16 + r] * gu[r];
;                 const float ls = fminf(lg, 0.f) - 0.69314718056f * __builtin_amdgcn_logf(1.0f + fexp(-fabsf(lg)));
;                 run += ls * (1.0f / 16.0f); bl[t] = run; }
;             const float bref = bl[31], blast = bl[63];
	v_fmac_f32_e32 v48, v126, v62
	v_fmac_f32_e32 v48, v127, v63
	v_fmac_f32_e32 v48, v128, v64
	v_fmac_f32_e32 v48, v129, v65
	ds_read_b128 v[62:65], v7 offset:33392
	s_waitcnt lgkmcnt(0)
	v_fmac_f32_e32 v48, v47, v62
	v_fmac_f32_e32 v48, v76, v63
	v_fmac_f32_e32 v48, v124, v64
	v_fmac_f32_e32 v48, v125, v65
	v_min_f32_e32 v49, 0, v48
	v_mul_f32_e64 v48, |v48|, s3
	v_exp_f32_e32 v48, v48
	ds_read_b128 v[62:65], v7 offset:33408
	v_add_f32_e32 v48, 1.0, v48
	v_log_f32_e32 v48, v48
	s_nop 0
	v_fmac_f32_e32 v49, 0xbf317218, v48
	s_waitcnt lgkmcnt(0)
	v_fma_f32 v48, v0, v62, v46
	v_fmac_f32_e32 v48, v1, v63
	v_fmac_f32_e32 v48, v2, v64
	v_fmac_f32_e32 v48, v3, v65
	ds_read_b128 v[62:65], v7 offset:33424
	v_fmamk_f32 v117, v49, 0x3d800000, v116
	s_waitcnt lgkmcnt(0)
	v_fmac_f32_e32 v48, v133, v62
	v_fmac_f32_e32 v48, v130, v63
	v_fmac_f32_e32 v48, v131, v64
	v_fmac_f32_e32 v48, v132, v65
	ds_read_b128 v[62:65], v7 offset:33440
	s_waitcnt lgkmcnt(0)
	v_fmac_f32_e32 v48, v126, v62
	v_fmac_f32_e32 v48, v127, v63
	v_fmac_f32_e32 v48, v128, v64
	v_fmac_f32_e32 v48, v129, v65
	ds_read_b128 v[62:65], v7 offset:33456
	s_waitcnt lgkmcnt(0)
	v_fmac_f32_e32 v48, v47, v62
	v_fmac_f32_e32 v48, v76, v63
	v_fmac_f32_e32 v48, v124, v64
	v_fmac_f32_e32 v48, v125, v65
	v_min_f32_e32 v49, 0, v48
	v_mul_f32_e64 v48, |v48|, s3
	v_exp_f32_e32 v48, v48
	ds_read_b128 v[62:65], v7 offset:33472
	v_add_f32_e32 v48, 1.0, v48
	v_log_f32_e32 v48, v48
	s_nop 0
	v_fmac_f32_e32 v49, 0xbf317218, v48
	s_waitcnt lgkmcnt(0)
	v_fma_f32 v48, v0, v62, v46
	v_fmac_f32_e32 v48, v1, v63
	v_fmac_f32_e32 v48, v2, v64
	v_fmac_f32_e32 v48, v3, v65
	ds_read_b128 v[62:65], v7 offset:33488
	v_fmamk_f32 v118, v49, 0x3d800000, v117
	s_waitcnt lgkmcnt(0)
	v_fmac_f32_e32 v48, v133, v62
	v_fmac_f32_e32 v48, v130, v63
	v_fmac_f32_e32 v48, v131, v64
	v_fmac_f32_e32 v48, v132, v65
	ds_read_b128 v[62:65], v7 offset:33504
	s_waitcnt lgkmcnt(0)
	v_fmac_f32_e32 v48, v126, v62
	v_fmac_f32_e32 v48, v127, v63
	v_fmac_f32_e32 v48, v128, v64
	v_fmac_f32_e32 v48, v129, v65
	ds_read_b128 v[62:65], v7 offset:33520
	s_waitcnt lgkmcnt(0)
	v_fmac_f32_e32 v48, v47, v62
	v_fmac_f32_e32 v48, v76, v63
	v_fmac_f32_e32 v48, v124, v64
	v_fmac_f32_e32 v48, v125, v65
	v_min_f32_e32 v49, 0, v48
	v_mul_f32_e64 v48, |v48|, s3
	v_exp_f32_e32 v48, v48
	ds_read_b128 v[62:65], v7 offset:33536
	v_add_f32_e32 v48, 1.0, v48
	v_log_f32_e32 v48, v48
	s_nop 0
	v_fmac_f32_e32 v49, 0xbf317218, v48
	s_waitcnt lgkmcnt(0)
	v_fma_f32 v48, v0, v62, v46
	v_fmac_f32_e32 v48, v1, v63
	v_fmac_f32_e32 v48, v2, v64
	v_fmac_f32_e32 v48, v3, v65
	ds_read_b128 v[62:65], v7 offset:33552
	v_fmamk_f32 v119, v49, 0x3d800000, v118
	s_waitcnt lgkmcnt(0)
	v_fmac_f32_e32 v48, v133, v62
	v_fmac_f32_e32 v48, v130, v63
	v_fmac_f32_e32 v48, v131, v64
	v_fmac_f32_e32 v48, v132, v65
	ds_read_b128 v[62:65], v7 offset:33568
	s_waitcnt lgkmcnt(0)
	v_fmac_f32_e32 v48, v126, v62
	v_fmac_f32_e32 v48, v127, v63
	v_fmac_f32_e32 v48, v128, v64
	v_fmac_f32_e32 v48, v129, v65
	ds_read_b128 v[62:65], v7 offset:33584
	s_waitcnt lgkmcnt(0)
	v_fmac_f32_e32 v48, v47, v62
	v_fmac_f32_e32 v48, v76, v63
	v_fmac_f32_e32 v48, v124, v64
	v_fmac_f32_e32 v48, v125, v65
	v_min_f32_e32 v49, 0, v48
	v_mul_f32_e64 v48, |v48|, s3
	v_exp_f32_e32 v48, v48
	ds_read_b128 v[62:65], v7 offset:33600
	v_add_f32_e32 v48, 1.0, v48
	v_log_f32_e32 v48, v48
	s_nop 0
	v_fmac_f32_e32 v49, 0xbf317218, v48
	s_waitcnt lgkmcnt(0)
	v_fma_f32 v48, v0, v62, v46
	v_fmac_f32_e32 v48, v1, v63
	v_fmac_f32_e32 v48, v2, v64
	v_fmac_f32_e32 v48, v3, v65
	ds_read_b128 v[62:65], v7 offset:33616
	v_fmamk_f32 v120, v49, 0x3d800000, v119
	s_waitcnt lgkmcnt(0)
	v_fmac_f32_e32 v48, v133, v62
	v_fmac_f32_e32 v48, v130, v63
	v_fmac_f32_e32 v48, v131, v64
	v_fmac_f32_e32 v48, v132, v65
	ds_read_b128 v[62:65], v7 offset:33632
	s_waitcnt lgkmcnt(0)
	v_fmac_f32_e32 v48, v126, v62
	v_fmac_f32_e32 v48, v127, v63
	v_fmac_f32_e32 v48, v128, v64
	v_fmac_f32_e32 v48, v129, v65
	ds_read_b128 v[62:65], v7 offset:33648
	s_waitcnt lgkmcnt(0)
	v_fmac_f32_e32 v48, v47, v62
	v_fmac_f32_e32 v48, v76, v63
	v_fmac_f32_e32 v48, v124, v64
	v_fmac_f32_e32 v48, v125, v65
	v_min_f32_e32 v49, 0, v48
	v_mul_f32_e64 v48, |v48|, s3
	v_exp_f32_e32 v48, v48
	ds_read_b128 v[62:65], v7 offset:33664
	v_add_f32_e32 v48, 1.0, v48
	v_log_f32_e32 v48, v48
	s_nop 0
	v_fmac_f32_e32 v49, 0xbf317218, v48
	s_waitcnt lgkmcnt(0)
	v_fma_f32 v48, v0, v62, v46
	v_fmac_f32_e32 v48, v1, v63
	v_fmac_f32_e32 v48, v2, v64
	v_fmac_f32_e32 v48, v3, v65
	ds_read_b128 v[62:65], v7 offset:33680
	v_fmamk_f32 v121, v49, 0x3d800000, v120
	s_waitcnt lgkmcnt(0)
	v_fmac_f32_e32 v48, v133, v62
	v_fmac_f32_e32 v48, v130, v63
	v_fmac_f32_e32 v48, v131, v64
	v_fmac_f32_e32 v48, v132, v65
	ds_read_b128 v[62:65], v7 offset:33696
	s_waitcnt lgkmcnt(0)
	v_fmac_f32_e32 v48, v126, v62
	v_fmac_f32_e32 v48, v127, v63
	v_fmac_f32_e32 v48, v128, v64
	v_fmac_f32_e32 v48, v129, v65
	ds_read_b128 v[62:65], v7 offset:33712
	s_waitcnt lgkmcnt(0)
	v_fmac_f32_e32 v48, v47, v62
	v_fmac_f32_e32 v48, v76, v63
	v_fmac_f32_e32 v48, v124, v64
	v_fmac_f32_e32 v48, v125, v65
	v_min_f32_e32 v49, 0, v48
	v_mul_f32_e64 v48, |v48|, s3
	v_exp_f32_e32 v48, v48
	ds_read_b128 v[62:65], v7 offset:33728
	v_add_f32_e32 v48, 1.0, v48
	v_log_f32_e32 v48, v48
	s_nop 0
	v_fmac_f32_e32 v49, 0xbf317218, v48
	s_waitcnt lgkmcnt(0)
	v_fma_f32 v48, v0, v62, v46
	v_fmac_f32_e32 v48, v1, v63
	v_fmac_f32_e32 v48, v2, v64
	v_fmac_f32_e32 v48, v3, v65
	ds_read_b128 v[62:65], v7 offset:33744
	v_fmamk_f32 v122, v49, 0x3d800000, v121
	s_waitcnt lgkmcnt(0)
	v_fmac_f32_e32 v48, v133, v62
	v_fmac_f32_e32 v48, v130, v63
	v_fmac_f32_e32 v48, v131, v64
	v_fmac_f32_e32 v48, v132, v65
	ds_read_b128 v[62:65], v7 offset:33760
	s_waitcnt lgkmcnt(0)
; __device__ __forceinline__ float fexp(float x) { return __builtin_amdgcn_exp2f(x * 1.44269504089f); }
; __device__ __forceinline__ void phase_qkrope_gla_prep(const Params& p, LAS unsigned char* lds, int wave, int lane) {
;     ...
;             float bl[64]; float run = 0.f;
; #pragma unroll
;             for (int t = 0; t < 64; ++t) { float lg = bias;
; #pragma unroll
;                 for (int r = 0; r < 16; ++r) lg += gl[t * 16 + r] * gu[r];
;                 const float ls = fminf(lg, 0.f) - 0.69314718056f * __builtin_amdgcn_logf(1.0f + fexp(-fabsf(lg)));
;                 run += ls * (1.0f / 16.0f); bl[t] = run; }
;             const float bref = bl[31], blast = bl[63];
	v_fmac_f32_e32 v48, v126, v62
	v_fmac_f32_e32 v48, v127, v63
	v_fmac_f32_e32 v48, v128, v64
	v_fmac_f32_e32 v48, v129, v65
	ds_read_b128 v[62:65], v7 offset:33776
	s_waitcnt lgkmcnt(0)
	v_fmac_f32_e32 v48, v47, v62
	v_fmac_f32_e32 v48, v76, v63
	v_fmac_f32_e32 v48, v124, v64
	v_fmac_f32_e32 v48, v125, v65
	v_min_f32_e32 v49, 0, v48
	v_mul_f32_e64 v48, |v48|, s3
	v_exp_f32_e32 v48, v48
	ds_read_b128 v[62:65], v7 offset:33792
	v_add_f32_e32 v48, 1.0, v48
	v_log_f32_e32 v48, v48
	s_nop 0
	v_fmac_f32_e32 v49, 0xbf317218, v48
	s_waitcnt lgkmcnt(0)
	v_fma_f32 v48, v0, v62, v46
	v_fmac_f32_e32 v48, v1, v63
	v_fmac_f32_e32 v48, v2, v64
	v_fmac_f32_e32 v48, v3, v65
	ds_read_b128 v[62:65], v7 offset:33808
	v_fmamk_f32 v123, v49, 0x3d800000, v122
	s_waitcnt lgkmcnt(0)
	v_fmac_f32_e32 v48, v133, v62
	v_fmac_f32_e32 v48, v130, v63
	v_fmac_f32_e32 v48, v131, v64
	v_fmac_f32_e32 v48, v132, v65
	ds_read_b128 v[62:65], v7 offset:33824
	s_waitcnt lgkmcnt(0)
	v_fmac_f32_e32 v48, v126, v62
	v_fmac_f32_e32 v48, v127, v63
	v_fmac_f32_e32 v48, v128, v64
	v_fmac_f32_e32 v48, v129, v65
	ds_read_b128 v[62:65], v7 offset:33840
	s_waitcnt lgkmcnt(0)
	v_fmac_f32_e32 v48, v47, v62
	v_fmac_f32_e32 v48, v76, v63
	v_fmac_f32_e32 v48, v124, v64
	v_fmac_f32_e32 v48, v125, v65
	v_min_f32_e32 v49, 0, v48
	v_mul_f32_e64 v48, |v48|, s3
	v_exp_f32_e32 v48, v48
	ds_read_b128 v[62:65], v7 offset:33856
	v_add_f32_e32 v48, 1.0, v48
	v_log_f32_e32 v48, v48
	s_nop 0
	v_fmac_f32_e32 v49, 0xbf317218, v48
	s_waitcnt lgkmcnt(0)
	v_fma_f32 v48, v0, v62, v46
	v_fmac_f32_e32 v48, v1, v63
	v_fmac_f32_e32 v48, v2, v64
	v_fmac_f32_e32 v48, v3, v65
	ds_read_b128 v[62:65], v7 offset:33872
	v_fmamk_f32 v81, v49, 0x3d800000, v123
	s_waitcnt lgkmcnt(0)
	v_fmac_f32_e32 v48, v133, v62
	v_fmac_f32_e32 v48, v130, v63
	v_fmac_f32_e32 v48, v131, v64
	v_fmac_f32_e32 v48, v132, v65
	ds_read_b128 v[62:65], v7 offset:33888
	s_waitcnt lgkmcnt(0)
	v_fmac_f32_e32 v48, v126, v62
	v_fmac_f32_e32 v48, v127, v63
	v_fmac_f32_e32 v48, v128, v64
	v_fmac_f32_e32 v48, v129, v65
	ds_read_b128 v[62:65], v7 offset:33904
	s_waitcnt lgkmcnt(0)
	v_fmac_f32_e32 v48, v47, v62
	v_fmac_f32_e32 v48, v76, v63
	v_fmac_f32_e32 v48, v124, v64
	v_fmac_f32_e32 v48, v125, v65
	v_min_f32_e32 v49, 0, v48
	v_mul_f32_e64 v48, |v48|, s3
	v_exp_f32_e32 v48, v48
	ds_read_b128 v[62:65], v7 offset:33920
	v_add_f32_e32 v48, 1.0, v48
	v_log_f32_e32 v48, v48
	s_nop 0
	v_fmac_f32_e32 v49, 0xbf317218, v48
	s_waitcnt lgkmcnt(0)
	v_fma_f32 v48, v0, v62, v46
	v_fmac_f32_e32 v48, v1, v63
	v_fmac_f32_e32 v48, v2, v64
	v_fmac_f32_e32 v48, v3, v65
	ds_read_b128 v[62:65], v7 offset:33936
	v_fmamk_f32 v82, v49, 0x3d800000, v81
	s_waitcnt lgkmcnt(0)
	v_fmac_f32_e32 v48, v133, v62
	v_fmac_f32_e32 v48, v130, v63
	v_fmac_f32_e32 v48, v131, v64
	v_fmac_f32_e32 v48, v132, v65
	ds_read_b128 v[62:65], v7 offset:33952
	s_waitcnt lgkmcnt(0)
	v_fmac_f32_e32 v48, v126, v62
	v_fmac_f32_e32 v48, v127, v63
	v_fmac_f32_e32 v48, v128, v64
	v_fmac_f32_e32 v48, v129, v65
	ds_read_b128 v[62:65], v7 offset:33968
	s_waitcnt lgkmcnt(0)
	v_fmac_f32_e32 v48, v47, v62
	v_fmac_f32_e32 v48, v76, v63
	v_fmac_f32_e32 v48, v124, v64
	v_fmac_f32_e32 v48, v125, v65
	v_min_f32_e32 v49, 0, v48
	v_mul_f32_e64 v48, |v48|, s3
	v_exp_f32_e32 v48, v48
	ds_read_b128 v[62:65], v7 offset:33984
	v_add_f32_e32 v48, 1.0, v48
	v_log_f32_e32 v48, v48
	s_nop 0
	v_fmac_f32_e32 v49, 0xbf317218, v48
	s_waitcnt lgkmcnt(0)
	v_fma_f32 v48, v0, v62, v46
	v_fmac_f32_e32 v48, v1, v63
	v_fmac_f32_e32 v48, v2, v64
	v_fmac_f32_e32 v48, v3, v65
	ds_read_b128 v[62:65], v7 offset:34000
	v_fmamk_f32 v85, v49, 0x3d800000, v82
	s_waitcnt lgkmcnt(0)
	v_fmac_f32_e32 v48, v133, v62
	v_fmac_f32_e32 v48, v130, v63
	v_fmac_f32_e32 v48, v131, v64
	v_fmac_f32_e32 v48, v132, v65
	ds_read_b128 v[62:65], v7 offset:34016
	s_waitcnt lgkmcnt(0)
	v_fmac_f32_e32 v48, v126, v62
	v_fmac_f32_e32 v48, v127, v63
	v_fmac_f32_e32 v48, v128, v64
	v_fmac_f32_e32 v48, v129, v65
	ds_read_b128 v[62:65], v7 offset:34032
	s_waitcnt lgkmcnt(0)
	v_fmac_f32_e32 v48, v47, v62
	v_fmac_f32_e32 v48, v76, v63
	v_fmac_f32_e32 v48, v124, v64
	v_fmac_f32_e32 v48, v125, v65
	v_min_f32_e32 v49, 0, v48
	v_mul_f32_e64 v48, |v48|, s3
	v_exp_f32_e32 v48, v48
	ds_read_b128 v[62:65], v7 offset:34048
	v_add_f32_e32 v48, 1.0, v48
	v_log_f32_e32 v48, v48
	s_nop 0
	v_fmac_f32_e32 v49, 0xbf317218, v48
	s_waitcnt lgkmcnt(0)
	v_fma_f32 v48, v0, v62, v46
	v_fmac_f32_e32 v48, v1, v63
	v_fmac_f32_e32 v48, v2, v64
	v_fmac_f32_e32 v48, v3, v65
	ds_read_b128 v[62:65], v7 offset:34064
	v_fmamk_f32 v88, v49, 0x3d800000, v85
	s_waitcnt lgkmcnt(0)
	v_fmac_f32_e32 v48, v133, v62
	v_fmac_f32_e32 v48, v130, v63
	v_fmac_f32_e32 v48, v131, v64
	v_fmac_f32_e32 v48, v132, v65
	ds_read_b128 v[62:65], v7 offset:34080
	s_waitcnt lgkmcnt(0)
	v_fmac_f32_e32 v48, v126, v62
	v_fmac_f32_e32 v48, v127, v63
	v_fmac_f32_e32 v48, v128, v64
	v_fmac_f32_e32 v48, v129, v65
	ds_read_b128 v[62:65], v7 offset:34096
	s_waitcnt lgkmcnt(0)
	v_fmac_f32_e32 v48, v47, v62
	v_fmac_f32_e32 v48, v76, v63
	v_fmac_f32_e32 v48, v124, v64
	v_fmac_f32_e32 v48, v125, v65
	v_min_f32_e32 v49, 0, v48
	v_mul_f32_e64 v48, |v48|, s3
	v_exp_f32_e32 v48, v48
	ds_read_b128 v[62:65], v7 offset:34112
	v_add_f32_e32 v48, 1.0, v48
	v_log_f32_e32 v48, v48
	s_nop 0
	v_fmac_f32_e32 v49, 0xbf317218, v48
	s_waitcnt lgkmcnt(0)
	v_fma_f32 v48, v0, v62, v46
	v_fmac_f32_e32 v48, v1, v63
	v_fmac_f32_e32 v48, v2, v64
	v_fmac_f32_e32 v48, v3, v65
	ds_read_b128 v[62:65], v7 offset:34128
	v_fmamk_f32 v90, v49, 0x3d800000, v88
	s_waitcnt lgkmcnt(0)
	v_fmac_f32_e32 v48, v133, v62
	v_fmac_f32_e32 v48, v130, v63
	v_fmac_f32_e32 v48, v131, v64
	v_fmac_f32_e32 v48, v132, v65
	ds_read_b128 v[62:65], v7 offset:34144
	s_waitcnt lgkmcnt(0)
; __device__ __forceinline__ float fexp(float x) { return __builtin_amdgcn_exp2f(x * 1.44269504089f); }
; __device__ __forceinline__ void phase_qkrope_gla_prep(const Params& p, LAS unsigned char* lds, int wave, int lane) {
;     ...
;             float bl[64]; float run = 0.f;
; #pragma unroll
;             for (int t = 0; t < 64; ++t) { float lg = bias;
; #pragma unroll
;                 for (int r = 0; r < 16; ++r) lg += gl[t * 16 + r] * gu[r];
;                 const float ls = fminf(lg, 0.f) - 0.69314718056f * __builtin_amdgcn_logf(1.0f + fexp(-fabsf(lg)));
;                 run += ls * (1.0f / 16.0f); bl[t] = run; }
;             const float bref = bl[31], blast = bl[63];
	v_fmac_f32_e32 v48, v126, v62
	v_fmac_f32_e32 v48, v127, v63
	v_fmac_f32_e32 v48, v128, v64
	v_fmac_f32_e32 v48, v129, v65
	ds_read_b128 v[62:65], v7 offset:34160
	s_waitcnt lgkmcnt(0)
	v_fmac_f32_e32 v48, v47, v62
	v_fmac_f32_e32 v48, v76, v63
	v_fmac_f32_e32 v48, v124, v64
	v_fmac_f32_e32 v48, v125, v65
	v_min_f32_e32 v49, 0, v48
	v_mul_f32_e64 v48, |v48|, s3
	v_exp_f32_e32 v48, v48
	ds_read_b128 v[62:65], v7 offset:34176
	v_add_f32_e32 v48, 1.0, v48
	v_log_f32_e32 v48, v48
	s_nop 0
	v_fmac_f32_e32 v49, 0xbf317218, v48
	s_waitcnt lgkmcnt(0)
	v_fma_f32 v48, v0, v62, v46
	v_fmac_f32_e32 v48, v1, v63
	v_fmac_f32_e32 v48, v2, v64
	v_fmac_f32_e32 v48, v3, v65
	ds_read_b128 v[62:65], v7 offset:34192
	v_fmamk_f32 v92, v49, 0x3d800000, v90
	s_waitcnt lgkmcnt(0)
	v_fmac_f32_e32 v48, v133, v62
	v_fmac_f32_e32 v48, v130, v63
	v_fmac_f32_e32 v48, v131, v64
	v_fmac_f32_e32 v48, v132, v65
	ds_read_b128 v[62:65], v7 offset:34208
	s_waitcnt lgkmcnt(0)
	v_fmac_f32_e32 v48, v126, v62
	v_fmac_f32_e32 v48, v127, v63
	v_fmac_f32_e32 v48, v128, v64
	v_fmac_f32_e32 v48, v129, v65
	ds_read_b128 v[62:65], v7 offset:34224
	s_waitcnt lgkmcnt(0)
	v_fmac_f32_e32 v48, v47, v62
	v_fmac_f32_e32 v48, v76, v63
	v_fmac_f32_e32 v48, v124, v64
	v_fmac_f32_e32 v48, v125, v65
	v_min_f32_e32 v49, 0, v48
	v_mul_f32_e64 v48, |v48|, s3
	v_exp_f32_e32 v48, v48
	ds_read_b128 v[62:65], v7 offset:34240
	v_add_f32_e32 v48, 1.0, v48
	v_log_f32_e32 v48, v48
	s_nop 0
	v_fmac_f32_e32 v49, 0xbf317218, v48
	s_waitcnt lgkmcnt(0)
	v_fma_f32 v48, v0, v62, v46
	v_fmac_f32_e32 v48, v1, v63
	v_fmac_f32_e32 v48, v2, v64
	v_fmac_f32_e32 v48, v3, v65
	ds_read_b128 v[62:65], v7 offset:34256
	v_fmamk_f32 v94, v49, 0x3d800000, v92
	s_waitcnt lgkmcnt(0)
	v_fmac_f32_e32 v48, v133, v62
	v_fmac_f32_e32 v48, v130, v63
	v_fmac_f32_e32 v48, v131, v64
	v_fmac_f32_e32 v48, v132, v65
	ds_read_b128 v[62:65], v7 offset:34272
	s_waitcnt lgkmcnt(0)
	v_fmac_f32_e32 v48, v126, v62
	v_fmac_f32_e32 v48, v127, v63
	v_fmac_f32_e32 v48, v128, v64
	v_fmac_f32_e32 v48, v129, v65
	ds_read_b128 v[62:65], v7 offset:34288
	s_waitcnt lgkmcnt(0)
	v_fmac_f32_e32 v48, v47, v62
	v_fmac_f32_e32 v48, v76, v63
	v_fmac_f32_e32 v48, v124, v64
	v_fmac_f32_e32 v48, v125, v65
	v_min_f32_e32 v49, 0, v48
	v_mul_f32_e64 v48, |v48|, s3
	v_exp_f32_e32 v48, v48
	ds_read_b128 v[62:65], v7 offset:34304
	v_add_f32_e32 v48, 1.0, v48
	v_log_f32_e32 v48, v48
	s_nop 0
	v_fmac_f32_e32 v49, 0xbf317218, v48
	s_waitcnt lgkmcnt(0)
	v_fma_f32 v48, v0, v62, v46
	v_fmac_f32_e32 v48, v1, v63
	v_fmac_f32_e32 v48, v2, v64
	v_fmac_f32_e32 v48, v3, v65
	ds_read_b128 v[62:65], v7 offset:34320
	v_fmamk_f32 v96, v49, 0x3d800000, v94
	s_waitcnt lgkmcnt(0)
	v_fmac_f32_e32 v48, v133, v62
	v_fmac_f32_e32 v48, v130, v63
	v_fmac_f32_e32 v48, v131, v64
	v_fmac_f32_e32 v48, v132, v65
	ds_read_b128 v[62:65], v7 offset:34336
	s_waitcnt lgkmcnt(0)
	v_fmac_f32_e32 v48, v126, v62
	v_fmac_f32_e32 v48, v127, v63
	v_fmac_f32_e32 v48, v128, v64
	v_fmac_f32_e32 v48, v129, v65
	ds_read_b128 v[62:65], v7 offset:34352
	s_waitcnt lgkmcnt(0)
	v_fmac_f32_e32 v48, v47, v62
	v_fmac_f32_e32 v48, v76, v63
	v_fmac_f32_e32 v48, v124, v64
	v_fmac_f32_e32 v48, v125, v65
	v_min_f32_e32 v49, 0, v48
	v_mul_f32_e64 v48, |v48|, s3
	v_exp_f32_e32 v48, v48
	ds_read_b128 v[62:65], v7 offset:34368
	v_add_f32_e32 v48, 1.0, v48
	v_log_f32_e32 v48, v48
	s_nop 0
	v_fmac_f32_e32 v49, 0xbf317218, v48
	s_waitcnt lgkmcnt(0)
	v_fma_f32 v48, v0, v62, v46
	v_fmac_f32_e32 v48, v1, v63
	v_fmac_f32_e32 v48, v2, v64
	v_fmac_f32_e32 v48, v3, v65
	ds_read_b128 v[62:65], v7 offset:34384
	v_fmamk_f32 v98, v49, 0x3d800000, v96
	s_waitcnt lgkmcnt(0)
	v_fmac_f32_e32 v48, v133, v62
	v_fmac_f32_e32 v48, v130, v63
	v_fmac_f32_e32 v48, v131, v64
	v_fmac_f32_e32 v48, v132, v65
	ds_read_b128 v[62:65], v7 offset:34400
	s_waitcnt lgkmcnt(0)
	v_fmac_f32_e32 v48, v126, v62
	v_fmac_f32_e32 v48, v127, v63
	v_fmac_f32_e32 v48, v128, v64
	v_fmac_f32_e32 v48, v129, v65
	ds_read_b128 v[62:65], v7 offset:34416
	s_waitcnt lgkmcnt(0)
	v_fmac_f32_e32 v48, v47, v62
	v_fmac_f32_e32 v48, v76, v63
	v_fmac_f32_e32 v48, v124, v64
	v_fmac_f32_e32 v48, v125, v65
	v_min_f32_e32 v49, 0, v48
	v_mul_f32_e64 v48, |v48|, s3
	v_exp_f32_e32 v48, v48
	ds_read_b128 v[62:65], v7 offset:34432
	v_add_f32_e32 v48, 1.0, v48
	v_log_f32_e32 v48, v48
	s_nop 0
	v_fmac_f32_e32 v49, 0xbf317218, v48
	s_waitcnt lgkmcnt(0)
	v_fma_f32 v48, v0, v62, v46
	v_fmac_f32_e32 v48, v1, v63
	v_fmac_f32_e32 v48, v2, v64
	v_fmac_f32_e32 v48, v3, v65
	ds_read_b128 v[62:65], v7 offset:34448
	v_fmamk_f32 v101, v49, 0x3d800000, v98
	s_waitcnt lgkmcnt(0)
	v_fmac_f32_e32 v48, v133, v62
	v_fmac_f32_e32 v48, v130, v63
	v_fmac_f32_e32 v48, v131, v64
	v_fmac_f32_e32 v48, v132, v65
	ds_read_b128 v[62:65], v7 offset:34464
	s_waitcnt lgkmcnt(0)
	v_fmac_f32_e32 v48, v126, v62
	v_fmac_f32_e32 v48, v127, v63
	v_fmac_f32_e32 v48, v128, v64
	v_fmac_f32_e32 v48, v129, v65
	ds_read_b128 v[62:65], v7 offset:34480
	s_waitcnt lgkmcnt(0)
	v_fmac_f32_e32 v48, v47, v62
	v_fmac_f32_e32 v48, v76, v63
	v_fmac_f32_e32 v48, v124, v64
	v_fmac_f32_e32 v48, v125, v65
	v_min_f32_e32 v49, 0, v48
	v_mul_f32_e64 v48, |v48|, s3
	v_exp_f32_e32 v48, v48
	ds_read_b128 v[62:65], v7 offset:34496
	v_add_f32_e32 v48, 1.0, v48
	v_log_f32_e32 v48, v48
	s_nop 0
	v_fmac_f32_e32 v49, 0xbf317218, v48
	s_waitcnt lgkmcnt(0)
	v_fma_f32 v48, v0, v62, v46
	v_fmac_f32_e32 v48, v1, v63
	v_fmac_f32_e32 v48, v2, v64
	v_fmac_f32_e32 v48, v3, v65
	ds_read_b128 v[62:65], v7 offset:34512
	v_fmamk_f32 v105, v49, 0x3d800000, v101
	s_waitcnt lgkmcnt(0)
	v_fmac_f32_e32 v48, v133, v62
	v_fmac_f32_e32 v48, v130, v63
	v_fmac_f32_e32 v48, v131, v64
	v_fmac_f32_e32 v48, v132, v65
	ds_read_b128 v[62:65], v7 offset:34528
	s_waitcnt lgkmcnt(0)
; __device__ __forceinline__ float fexp(float x) { return __builtin_amdgcn_exp2f(x * 1.44269504089f); }
; __device__ __forceinline__ void phase_qkrope_gla_prep(const Params& p, LAS unsigned char* lds, int wave, int lane) {
;     ...
;             float bl[64]; float run = 0.f;
; #pragma unroll
;             for (int t = 0; t < 64; ++t) { float lg = bias;
; #pragma unroll
;                 for (int r = 0; r < 16; ++r) lg += gl[t * 16 + r] * gu[r];
;                 const float ls = fminf(lg, 0.f) - 0.69314718056f * __builtin_amdgcn_logf(1.0f + fexp(-fabsf(lg)));
;                 run += ls * (1.0f / 16.0f); bl[t] = run; }
;             const float bref = bl[31], blast = bl[63];
;     ...
;                 for (int t = 0; t < 16; ++t) { const size_t ro = (size_t)(m0 + 16 * tb + t) * ZP + d; const float bb = bl[16 * tb + t];
;                     const float qs = bf2f(qv[t]) * 0.08838834764831845f * fexp(bb - bref), ks = bf2f(kv[t]) * fexp(bref - bb);
	v_fmac_f32_e32 v48, v126, v62
	v_fmac_f32_e32 v48, v127, v63
	v_fmac_f32_e32 v48, v128, v64
	v_fmac_f32_e32 v48, v129, v65
	ds_read_b128 v[62:65], v7 offset:34544
	s_waitcnt lgkmcnt(0)
	v_fmac_f32_e32 v48, v47, v62
	v_fmac_f32_e32 v48, v76, v63
	v_fmac_f32_e32 v48, v124, v64
	v_fmac_f32_e32 v48, v125, v65
	v_min_f32_e32 v49, 0, v48
	v_mul_f32_e64 v48, |v48|, s3
	v_exp_f32_e32 v48, v48
	ds_read_b128 v[62:65], v7 offset:34560
	v_add_f32_e32 v48, 1.0, v48
	v_log_f32_e32 v48, v48
	s_nop 0
	v_fmac_f32_e32 v49, 0xbf317218, v48
	s_waitcnt lgkmcnt(0)
	v_fma_f32 v48, v0, v62, v46
	v_fmac_f32_e32 v48, v1, v63
	v_fmac_f32_e32 v48, v2, v64
	v_fmac_f32_e32 v48, v3, v65
	ds_read_b128 v[62:65], v7 offset:34576
	v_fmamk_f32 v108, v49, 0x3d800000, v105
	s_waitcnt lgkmcnt(0)
	v_fmac_f32_e32 v48, v133, v62
	v_fmac_f32_e32 v48, v130, v63
	v_fmac_f32_e32 v48, v131, v64
	v_fmac_f32_e32 v48, v132, v65
	ds_read_b128 v[62:65], v7 offset:34592
	s_waitcnt lgkmcnt(0)
	v_fmac_f32_e32 v48, v126, v62
	v_fmac_f32_e32 v48, v127, v63
	v_fmac_f32_e32 v48, v128, v64
	v_fmac_f32_e32 v48, v129, v65
	ds_read_b128 v[62:65], v7 offset:34608
	s_waitcnt lgkmcnt(0)
	v_fmac_f32_e32 v48, v47, v62
	v_fmac_f32_e32 v48, v76, v63
	v_fmac_f32_e32 v48, v124, v64
	v_fmac_f32_e32 v48, v125, v65
	v_min_f32_e32 v49, 0, v48
	v_mul_f32_e64 v48, |v48|, s3
	v_exp_f32_e32 v48, v48
	ds_read_b128 v[62:65], v7 offset:34624
	v_add_f32_e32 v48, 1.0, v48
	v_log_f32_e32 v48, v48
	s_nop 0
	v_fmac_f32_e32 v49, 0xbf317218, v48
	s_waitcnt lgkmcnt(0)
	v_fma_f32 v48, v0, v62, v46
	v_fmac_f32_e32 v48, v1, v63
	v_fmac_f32_e32 v48, v2, v64
	v_fmac_f32_e32 v48, v3, v65
	ds_read_b128 v[62:65], v7 offset:34640
	v_fmamk_f32 v110, v49, 0x3d800000, v108
	s_waitcnt lgkmcnt(0)
	v_fmac_f32_e32 v48, v133, v62
	v_fmac_f32_e32 v48, v130, v63
	v_fmac_f32_e32 v48, v131, v64
	v_fmac_f32_e32 v48, v132, v65
	ds_read_b128 v[62:65], v7 offset:34656
	s_waitcnt lgkmcnt(0)
	v_fmac_f32_e32 v48, v126, v62
	v_fmac_f32_e32 v48, v127, v63
	v_fmac_f32_e32 v48, v128, v64
	v_fmac_f32_e32 v48, v129, v65
	ds_read_b128 v[62:65], v7 offset:34672
	s_waitcnt lgkmcnt(0)
	v_fmac_f32_e32 v48, v47, v62
	v_fmac_f32_e32 v48, v76, v63
	v_fmac_f32_e32 v48, v124, v64
	v_fmac_f32_e32 v48, v125, v65
	v_min_f32_e32 v49, 0, v48
	v_mul_f32_e64 v48, |v48|, s3
	v_exp_f32_e32 v48, v48
	ds_read_b128 v[62:65], v7 offset:34688
	v_add_f32_e32 v48, 1.0, v48
	v_log_f32_e32 v48, v48
	s_nop 0
	v_fmac_f32_e32 v49, 0xbf317218, v48
	s_waitcnt lgkmcnt(0)
	v_fma_f32 v48, v0, v62, v46
	v_fmac_f32_e32 v48, v1, v63
	v_fmac_f32_e32 v48, v2, v64
	v_fmac_f32_e32 v48, v3, v65
	ds_read_b128 v[62:65], v7 offset:34704
	v_fmamk_f32 v113, v49, 0x3d800000, v110
	s_waitcnt lgkmcnt(0)
	v_fmac_f32_e32 v48, v133, v62
	v_fmac_f32_e32 v48, v130, v63
	v_fmac_f32_e32 v48, v131, v64
	v_fmac_f32_e32 v48, v132, v65
	ds_read_b128 v[62:65], v7 offset:34720
	s_waitcnt lgkmcnt(0)
	v_fmac_f32_e32 v48, v126, v62
	v_fmac_f32_e32 v48, v127, v63
	v_fmac_f32_e32 v48, v128, v64
	v_fmac_f32_e32 v48, v129, v65
	ds_read_b128 v[62:65], v7 offset:34736
	s_waitcnt lgkmcnt(0)
	v_fmac_f32_e32 v48, v47, v62
	v_fmac_f32_e32 v48, v76, v63
	v_fmac_f32_e32 v48, v124, v64
	v_fmac_f32_e32 v48, v125, v65
	v_min_f32_e32 v49, 0, v48
	v_mul_f32_e64 v48, |v48|, s3
	v_exp_f32_e32 v48, v48
	ds_read_b128 v[62:65], v7 offset:34752
	v_add_f32_e32 v48, 1.0, v48
	v_log_f32_e32 v48, v48
	s_nop 0
	v_fmac_f32_e32 v49, 0xbf317218, v48
	s_waitcnt lgkmcnt(0)
	v_fma_f32 v48, v0, v62, v46
	v_fmac_f32_e32 v48, v1, v63
	v_fmac_f32_e32 v48, v2, v64
	v_fmac_f32_e32 v48, v3, v65
	ds_read_b128 v[62:65], v7 offset:34768
	v_fmamk_f32 v115, v49, 0x3d800000, v113
	s_waitcnt lgkmcnt(0)
	v_fmac_f32_e32 v48, v133, v62
	v_fmac_f32_e32 v48, v130, v63
	v_fmac_f32_e32 v48, v131, v64
	v_fmac_f32_e32 v48, v132, v65
	ds_read_b128 v[62:65], v7 offset:34784
	s_waitcnt lgkmcnt(0)
	v_fmac_f32_e32 v48, v126, v62
	v_fmac_f32_e32 v48, v127, v63
	v_fmac_f32_e32 v48, v128, v64
	v_fmac_f32_e32 v48, v129, v65
	ds_read_b128 v[62:65], v7 offset:34800
	s_waitcnt lgkmcnt(0)
	v_fmac_f32_e32 v48, v47, v62
	v_fmac_f32_e32 v48, v76, v63
	v_fmac_f32_e32 v48, v124, v64
	v_fmac_f32_e32 v48, v125, v65
	v_min_f32_e32 v49, 0, v48
	v_mul_f32_e64 v48, |v48|, s3
	v_exp_f32_e32 v48, v48
	ds_read_b128 v[62:65], v7 offset:34816
	v_add_f32_e32 v48, 1.0, v48
	v_log_f32_e32 v48, v48
	s_nop 0
	v_fmac_f32_e32 v49, 0xbf317218, v48
	v_fmamk_f32 v48, v49, 0x3d800000, v115
	s_waitcnt lgkmcnt(0)
	v_fma_f32 v49, v0, v62, v46
	v_fmac_f32_e32 v49, v1, v63
	v_fmac_f32_e32 v49, v2, v64
	v_fmac_f32_e32 v49, v3, v65
	ds_read_b128 v[62:65], v7 offset:34832
	v_sub_f32_e32 v151, v100, v48
	v_mul_f32_e32 v151, 0x3fb8aa3b, v151
	v_exp_f32_e32 v151, v151
	v_sub_f32_e32 v100, v48, v100
	s_waitcnt lgkmcnt(0)
	v_fmac_f32_e32 v49, v133, v62
	v_fmac_f32_e32 v49, v130, v63
	v_fmac_f32_e32 v49, v131, v64
	v_fmac_f32_e32 v49, v132, v65
	ds_read_b128 v[62:65], v7 offset:34848
	v_mul_f32_e32 v100, 0x3fb8aa3b, v100
	v_exp_f32_e32 v100, v100
	s_waitcnt lgkmcnt(0)
	v_fmac_f32_e32 v49, v126, v62
	v_fmac_f32_e32 v49, v127, v63
	v_fmac_f32_e32 v49, v128, v64
	v_fmac_f32_e32 v49, v129, v65
	ds_read_b128 v[62:65], v7 offset:34864
	s_waitcnt lgkmcnt(0)
	v_fmac_f32_e32 v49, v47, v62
	v_fmac_f32_e32 v49, v76, v63
	v_fmac_f32_e32 v49, v124, v64
	v_fmac_f32_e32 v49, v125, v65
	v_min_f32_e32 v62, 0, v49
	v_mul_f32_e64 v49, |v49|, s3
	v_exp_f32_e32 v49, v49
	s_nop 0
	v_add_f32_e32 v49, 1.0, v49
	v_log_f32_e32 v49, v49
	s_nop 0
	v_fmac_f32_e32 v62, 0xbf317218, v49
	v_fmamk_f32 v68, v62, 0x3d800000, v48
	ds_read_b128 v[62:65], v7 offset:34880
	s_waitcnt lgkmcnt(0)
; __device__ __forceinline__ float fexp(float x) { return __builtin_amdgcn_exp2f(x * 1.44269504089f); }
; __device__ __forceinline__ void phase_qkrope_gla_prep(const Params& p, LAS unsigned char* lds, int wave, int lane) {
;     ...
;             float bl[64]; float run = 0.f;
; #pragma unroll
;             for (int t = 0; t < 64; ++t) { float lg = bias;
; #pragma unroll
;                 for (int r = 0; r < 16; ++r) lg += gl[t * 16 + r] * gu[r];
;                 const float ls = fminf(lg, 0.f) - 0.69314718056f * __builtin_amdgcn_logf(1.0f + fexp(-fabsf(lg)));
;                 run += ls * (1.0f / 16.0f); bl[t] = run; }
;             const float bref = bl[31], blast = bl[63];
	v_fma_f32 v49, v0, v62, v46
	v_fmac_f32_e32 v49, v1, v63
	v_fmac_f32_e32 v49, v2, v64
	v_fmac_f32_e32 v49, v3, v65
	ds_read_b128 v[62:65], v7 offset:34896
	s_waitcnt lgkmcnt(0)
	v_fmac_f32_e32 v49, v133, v62
	v_fmac_f32_e32 v49, v130, v63
	v_fmac_f32_e32 v49, v131, v64
	v_fmac_f32_e32 v49, v132, v65
	ds_read_b128 v[62:65], v7 offset:34912
	s_waitcnt lgkmcnt(0)
	v_fmac_f32_e32 v49, v126, v62
	v_fmac_f32_e32 v49, v127, v63
	v_fmac_f32_e32 v49, v128, v64
	v_fmac_f32_e32 v49, v129, v65
	ds_read_b128 v[62:65], v7 offset:34928
	s_waitcnt lgkmcnt(0)
	v_fmac_f32_e32 v49, v47, v62
	v_fmac_f32_e32 v49, v76, v63
	v_fmac_f32_e32 v49, v124, v64
	v_fmac_f32_e32 v49, v125, v65
	v_min_f32_e32 v62, 0, v49
	v_mul_f32_e64 v49, |v49|, s3
	v_exp_f32_e32 v49, v49
	s_nop 0
	v_add_f32_e32 v49, 1.0, v49
	v_log_f32_e32 v49, v49
	s_nop 0
	v_fmac_f32_e32 v62, 0xbf317218, v49
	v_fmamk_f32 v70, v62, 0x3d800000, v68
	ds_read_b128 v[62:65], v7 offset:34944
	s_waitcnt lgkmcnt(0)
	v_fma_f32 v49, v0, v62, v46
	v_fmac_f32_e32 v49, v1, v63
	v_fmac_f32_e32 v49, v2, v64
	v_fmac_f32_e32 v49, v3, v65
	ds_read_b128 v[62:65], v7 offset:34960
	s_waitcnt lgkmcnt(0)
	v_fmac_f32_e32 v49, v133, v62
	v_fmac_f32_e32 v49, v130, v63
	v_fmac_f32_e32 v49, v131, v64
	v_fmac_f32_e32 v49, v132, v65
	ds_read_b128 v[62:65], v7 offset:34976
	s_waitcnt lgkmcnt(0)
	v_fmac_f32_e32 v49, v126, v62
	v_fmac_f32_e32 v49, v127, v63
	v_fmac_f32_e32 v49, v128, v64
	v_fmac_f32_e32 v49, v129, v65
	ds_read_b128 v[62:65], v7 offset:34992
	s_waitcnt lgkmcnt(0)
	v_fmac_f32_e32 v49, v47, v62
	v_fmac_f32_e32 v49, v76, v63
	v_fmac_f32_e32 v49, v124, v64
	v_fmac_f32_e32 v49, v125, v65
	v_min_f32_e32 v62, 0, v49
	v_mul_f32_e64 v49, |v49|, s3
	v_exp_f32_e32 v49, v49
	s_nop 0
	v_add_f32_e32 v49, 1.0, v49
	v_log_f32_e32 v49, v49
	s_nop 0
	v_fmac_f32_e32 v62, 0xbf317218, v49
	v_fmamk_f32 v72, v62, 0x3d800000, v70
	ds_read_b128 v[62:65], v7 offset:35008
	s_waitcnt lgkmcnt(0)
	v_fma_f32 v49, v0, v62, v46
	v_fmac_f32_e32 v49, v1, v63
	v_fmac_f32_e32 v49, v2, v64
	v_fmac_f32_e32 v49, v3, v65
	ds_read_b128 v[62:65], v7 offset:35024
	s_waitcnt lgkmcnt(0)
	v_fmac_f32_e32 v49, v133, v62
	v_fmac_f32_e32 v49, v130, v63
	v_fmac_f32_e32 v49, v131, v64
	v_fmac_f32_e32 v49, v132, v65
	ds_read_b128 v[62:65], v7 offset:35040
	s_waitcnt lgkmcnt(0)
	v_fmac_f32_e32 v49, v126, v62
	v_fmac_f32_e32 v49, v127, v63
	v_fmac_f32_e32 v49, v128, v64
	v_fmac_f32_e32 v49, v129, v65
	ds_read_b128 v[62:65], v7 offset:35056
	s_waitcnt lgkmcnt(0)
	v_fmac_f32_e32 v49, v47, v62
	v_fmac_f32_e32 v49, v76, v63
	v_fmac_f32_e32 v49, v124, v64
	v_fmac_f32_e32 v49, v125, v65
	v_min_f32_e32 v62, 0, v49
	v_mul_f32_e64 v49, |v49|, s3
	v_exp_f32_e32 v49, v49
	s_nop 0
	v_add_f32_e32 v49, 1.0, v49
	v_log_f32_e32 v49, v49
	s_nop 0
	v_fmac_f32_e32 v62, 0xbf317218, v49
	v_fmamk_f32 v74, v62, 0x3d800000, v72
	ds_read_b128 v[62:65], v7 offset:35072
	s_waitcnt lgkmcnt(0)
	v_fma_f32 v49, v0, v62, v46
	v_fmac_f32_e32 v49, v1, v63
	v_fmac_f32_e32 v49, v2, v64
	v_fmac_f32_e32 v49, v3, v65
	ds_read_b128 v[62:65], v7 offset:35088
	s_waitcnt lgkmcnt(0)
	v_fmac_f32_e32 v49, v133, v62
	v_fmac_f32_e32 v49, v130, v63
	v_fmac_f32_e32 v49, v131, v64
	v_fmac_f32_e32 v49, v132, v65
	ds_read_b128 v[62:65], v7 offset:35104
	s_waitcnt lgkmcnt(0)
	v_fmac_f32_e32 v49, v126, v62
	v_fmac_f32_e32 v49, v127, v63
	v_fmac_f32_e32 v49, v128, v64
	v_fmac_f32_e32 v49, v129, v65
	ds_read_b128 v[62:65], v7 offset:35120
	s_waitcnt lgkmcnt(0)
	v_fmac_f32_e32 v49, v47, v62
	v_fmac_f32_e32 v49, v76, v63
	v_fmac_f32_e32 v49, v124, v64
	v_fmac_f32_e32 v49, v125, v65
	v_min_f32_e32 v62, 0, v49
	v_mul_f32_e64 v49, |v49|, s3
	v_exp_f32_e32 v49, v49
	s_nop 0
	v_add_f32_e32 v49, 1.0, v49
	v_log_f32_e32 v49, v49
	s_nop 0
	v_fmac_f32_e32 v62, 0xbf317218, v49
	v_fmamk_f32 v77, v62, 0x3d800000, v74
	ds_read_b128 v[62:65], v7 offset:35136
	s_waitcnt lgkmcnt(0)
	v_fma_f32 v49, v0, v62, v46
	v_fmac_f32_e32 v49, v1, v63
	v_fmac_f32_e32 v49, v2, v64
	v_fmac_f32_e32 v49, v3, v65
	ds_read_b128 v[62:65], v7 offset:35152
	s_waitcnt lgkmcnt(0)
	v_fmac_f32_e32 v49, v133, v62
	v_fmac_f32_e32 v49, v130, v63
	v_fmac_f32_e32 v49, v131, v64
	v_fmac_f32_e32 v49, v132, v65
	ds_read_b128 v[62:65], v7 offset:35168
	s_waitcnt lgkmcnt(0)
	v_fmac_f32_e32 v49, v126, v62
	v_fmac_f32_e32 v49, v127, v63
	v_fmac_f32_e32 v49, v128, v64
	v_fmac_f32_e32 v49, v129, v65
	ds_read_b128 v[62:65], v7 offset:35184
	s_waitcnt lgkmcnt(0)
	v_fmac_f32_e32 v49, v47, v62
	v_fmac_f32_e32 v49, v76, v63
	v_fmac_f32_e32 v49, v124, v64
	v_fmac_f32_e32 v49, v125, v65
	v_min_f32_e32 v62, 0, v49
	v_mul_f32_e64 v49, |v49|, s3
	v_exp_f32_e32 v49, v49
	s_nop 0
	v_add_f32_e32 v49, 1.0, v49
	v_log_f32_e32 v49, v49
	s_nop 0
	v_fmac_f32_e32 v62, 0xbf317218, v49
	v_fmamk_f32 v79, v62, 0x3d800000, v77
	ds_read_b128 v[62:65], v7 offset:35200
	s_waitcnt lgkmcnt(0)
	v_fma_f32 v49, v0, v62, v46
	v_fmac_f32_e32 v49, v1, v63
	v_fmac_f32_e32 v49, v2, v64
	v_fmac_f32_e32 v49, v3, v65
	ds_read_b128 v[62:65], v7 offset:35216
	s_waitcnt lgkmcnt(0)
	v_fmac_f32_e32 v49, v133, v62
	v_fmac_f32_e32 v49, v130, v63
	v_fmac_f32_e32 v49, v131, v64
	v_fmac_f32_e32 v49, v132, v65
	ds_read_b128 v[62:65], v7 offset:35232
	s_waitcnt lgkmcnt(0)
	v_fmac_f32_e32 v49, v126, v62
	v_fmac_f32_e32 v49, v127, v63
	v_fmac_f32_e32 v49, v128, v64
	v_fmac_f32_e32 v49, v129, v65
	ds_read_b128 v[62:65], v7 offset:35248
	s_waitcnt lgkmcnt(0)
	v_fmac_f32_e32 v49, v47, v62
	v_fmac_f32_e32 v49, v76, v63
	v_fmac_f32_e32 v49, v124, v64
	v_fmac_f32_e32 v49, v125, v65
	v_min_f32_e32 v62, 0, v49
	v_mul_f32_e64 v49, |v49|, s3
	v_exp_f32_e32 v49, v49
	s_nop 0
	v_add_f32_e32 v49, 1.0, v49
	v_log_f32_e32 v49, v49
	s_nop 0
	v_fmac_f32_e32 v62, 0xbf317218, v49
	v_fmamk_f32 v83, v62, 0x3d800000, v79
	ds_read_b128 v[62:65], v7 offset:35264
	s_waitcnt lgkmcnt(0)
; __device__ __forceinline__ float fexp(float x) { return __builtin_amdgcn_exp2f(x * 1.44269504089f); }
; __device__ __forceinline__ void phase_qkrope_gla_prep(const Params& p, LAS unsigned char* lds, int wave, int lane) {
;     ...
;             float bl[64]; float run = 0.f;
; #pragma unroll
;             for (int t = 0; t < 64; ++t) { float lg = bias;
; #pragma unroll
;                 for (int r = 0; r < 16; ++r) lg += gl[t * 16 + r] * gu[r];
;                 const float ls = fminf(lg, 0.f) - 0.69314718056f * __builtin_amdgcn_logf(1.0f + fexp(-fabsf(lg)));
;                 run += ls * (1.0f / 16.0f); bl[t] = run; }
;             const float bref = bl[31], blast = bl[63];
	v_fma_f32 v49, v0, v62, v46
	v_fmac_f32_e32 v49, v1, v63
	v_fmac_f32_e32 v49, v2, v64
	v_fmac_f32_e32 v49, v3, v65
	ds_read_b128 v[62:65], v7 offset:35280
	s_waitcnt lgkmcnt(0)
	v_fmac_f32_e32 v49, v133, v62
	v_fmac_f32_e32 v49, v130, v63
	v_fmac_f32_e32 v49, v131, v64
	v_fmac_f32_e32 v49, v132, v65
	ds_read_b128 v[62:65], v7 offset:35296
	s_waitcnt lgkmcnt(0)
	v_fmac_f32_e32 v49, v126, v62
	v_fmac_f32_e32 v49, v127, v63
	v_fmac_f32_e32 v49, v128, v64
	v_fmac_f32_e32 v49, v129, v65
	ds_read_b128 v[62:65], v7 offset:35312
	s_waitcnt lgkmcnt(0)
	v_fmac_f32_e32 v49, v47, v62
	v_fmac_f32_e32 v49, v76, v63
	v_fmac_f32_e32 v49, v124, v64
	v_fmac_f32_e32 v49, v125, v65
	v_min_f32_e32 v62, 0, v49
	v_mul_f32_e64 v49, |v49|, s3
	v_exp_f32_e32 v49, v49
	s_nop 0
	v_add_f32_e32 v49, 1.0, v49
	v_log_f32_e32 v49, v49
	s_nop 0
	v_fmac_f32_e32 v62, 0xbf317218, v49
	v_fmamk_f32 v86, v62, 0x3d800000, v83
	ds_read_b128 v[62:65], v7 offset:35328
	s_waitcnt lgkmcnt(0)
	v_fma_f32 v49, v0, v62, v46
	v_fmac_f32_e32 v49, v1, v63
	v_fmac_f32_e32 v49, v2, v64
	v_fmac_f32_e32 v49, v3, v65
	ds_read_b128 v[62:65], v7 offset:35344
	s_waitcnt lgkmcnt(0)
	v_fmac_f32_e32 v49, v133, v62
	v_fmac_f32_e32 v49, v130, v63
	v_fmac_f32_e32 v49, v131, v64
	v_fmac_f32_e32 v49, v132, v65
	ds_read_b128 v[62:65], v7 offset:35360
	s_waitcnt lgkmcnt(0)
	v_fmac_f32_e32 v49, v126, v62
	v_fmac_f32_e32 v49, v127, v63
	v_fmac_f32_e32 v49, v128, v64
	v_fmac_f32_e32 v49, v129, v65
	ds_read_b128 v[62:65], v7 offset:35376
	s_waitcnt lgkmcnt(0)
	v_fmac_f32_e32 v49, v47, v62
	v_fmac_f32_e32 v49, v76, v63
	v_fmac_f32_e32 v49, v124, v64
	v_fmac_f32_e32 v49, v125, v65
	v_min_f32_e32 v62, 0, v49
	v_mul_f32_e64 v49, |v49|, s3
	v_exp_f32_e32 v49, v49
	s_nop 0
	v_add_f32_e32 v49, 1.0, v49
	v_log_f32_e32 v49, v49
	s_nop 0
	v_fmac_f32_e32 v62, 0xbf317218, v49
	v_fmamk_f32 v89, v62, 0x3d800000, v86
	ds_read_b128 v[62:65], v7 offset:35392
	s_waitcnt lgkmcnt(0)
	v_fma_f32 v49, v0, v62, v46
	v_fmac_f32_e32 v49, v1, v63
	v_fmac_f32_e32 v49, v2, v64
	v_fmac_f32_e32 v49, v3, v65
	ds_read_b128 v[62:65], v7 offset:35408
	s_waitcnt lgkmcnt(0)
	v_fmac_f32_e32 v49, v133, v62
	v_fmac_f32_e32 v49, v130, v63
	v_fmac_f32_e32 v49, v131, v64
	v_fmac_f32_e32 v49, v132, v65
	ds_read_b128 v[62:65], v7 offset:35424
	s_waitcnt lgkmcnt(0)
	v_fmac_f32_e32 v49, v126, v62
	v_fmac_f32_e32 v49, v127, v63
	v_fmac_f32_e32 v49, v128, v64
	v_fmac_f32_e32 v49, v129, v65
	ds_read_b128 v[62:65], v7 offset:35440
	s_waitcnt lgkmcnt(0)
	v_fmac_f32_e32 v49, v47, v62
	v_fmac_f32_e32 v49, v76, v63
	v_fmac_f32_e32 v49, v124, v64
	v_fmac_f32_e32 v49, v125, v65
	v_min_f32_e32 v62, 0, v49
	v_mul_f32_e64 v49, |v49|, s3
	v_exp_f32_e32 v49, v49
	s_nop 0
	v_add_f32_e32 v49, 1.0, v49
	v_log_f32_e32 v49, v49
	s_nop 0
	v_fmac_f32_e32 v62, 0xbf317218, v49
	v_fmamk_f32 v91, v62, 0x3d800000, v89
	ds_read_b128 v[62:65], v7 offset:35456
	s_waitcnt lgkmcnt(0)
	v_fma_f32 v49, v0, v62, v46
	v_fmac_f32_e32 v49, v1, v63
	v_fmac_f32_e32 v49, v2, v64
	v_fmac_f32_e32 v49, v3, v65
	ds_read_b128 v[62:65], v7 offset:35472
	s_waitcnt lgkmcnt(0)
	v_fmac_f32_e32 v49, v133, v62
	v_fmac_f32_e32 v49, v130, v63
	v_fmac_f32_e32 v49, v131, v64
	v_fmac_f32_e32 v49, v132, v65
	ds_read_b128 v[62:65], v7 offset:35488
	s_waitcnt lgkmcnt(0)
	v_fmac_f32_e32 v49, v126, v62
	v_fmac_f32_e32 v49, v127, v63
	v_fmac_f32_e32 v49, v128, v64
	v_fmac_f32_e32 v49, v129, v65
	ds_read_b128 v[62:65], v7 offset:35504
	s_waitcnt lgkmcnt(0)
	v_fmac_f32_e32 v49, v47, v62
	v_fmac_f32_e32 v49, v76, v63
	v_fmac_f32_e32 v49, v124, v64
	v_fmac_f32_e32 v49, v125, v65
	v_min_f32_e32 v62, 0, v49
	v_mul_f32_e64 v49, |v49|, s3
	v_exp_f32_e32 v49, v49
	s_nop 0
	v_add_f32_e32 v49, 1.0, v49
	v_log_f32_e32 v49, v49
	s_nop 0
	v_fmac_f32_e32 v62, 0xbf317218, v49
	v_fmamk_f32 v93, v62, 0x3d800000, v91
	ds_read_b128 v[62:65], v7 offset:35520
	s_waitcnt lgkmcnt(0)
	v_fma_f32 v49, v0, v62, v46
	v_fmac_f32_e32 v49, v1, v63
	v_fmac_f32_e32 v49, v2, v64
	v_fmac_f32_e32 v49, v3, v65
	ds_read_b128 v[62:65], v7 offset:35536
	s_waitcnt lgkmcnt(0)
	v_fmac_f32_e32 v49, v133, v62
	v_fmac_f32_e32 v49, v130, v63
	v_fmac_f32_e32 v49, v131, v64
	v_fmac_f32_e32 v49, v132, v65
	ds_read_b128 v[62:65], v7 offset:35552
	s_waitcnt lgkmcnt(0)
	v_fmac_f32_e32 v49, v126, v62
	v_fmac_f32_e32 v49, v127, v63
	v_fmac_f32_e32 v49, v128, v64
	v_fmac_f32_e32 v49, v129, v65
	ds_read_b128 v[62:65], v7 offset:35568
	s_waitcnt lgkmcnt(0)
	v_fmac_f32_e32 v49, v47, v62
	v_fmac_f32_e32 v49, v76, v63
	v_fmac_f32_e32 v49, v124, v64
	v_fmac_f32_e32 v49, v125, v65
	v_min_f32_e32 v62, 0, v49
	v_mul_f32_e64 v49, |v49|, s3
	v_exp_f32_e32 v49, v49
	s_nop 0
	v_add_f32_e32 v49, 1.0, v49
	v_log_f32_e32 v49, v49
	s_nop 0
	v_fmac_f32_e32 v62, 0xbf317218, v49
	v_fmamk_f32 v95, v62, 0x3d800000, v93
	ds_read_b128 v[62:65], v7 offset:35584
	s_waitcnt lgkmcnt(0)
	v_fma_f32 v49, v0, v62, v46
	v_fmac_f32_e32 v49, v1, v63
	v_fmac_f32_e32 v49, v2, v64
	v_fmac_f32_e32 v49, v3, v65
	ds_read_b128 v[62:65], v7 offset:35600
	s_waitcnt lgkmcnt(0)
	v_fmac_f32_e32 v49, v133, v62
	v_fmac_f32_e32 v49, v130, v63
	v_fmac_f32_e32 v49, v131, v64
	v_fmac_f32_e32 v49, v132, v65
	ds_read_b128 v[62:65], v7 offset:35616
	s_waitcnt lgkmcnt(0)
	v_fmac_f32_e32 v49, v126, v62
	v_fmac_f32_e32 v49, v127, v63
	v_fmac_f32_e32 v49, v128, v64
	v_fmac_f32_e32 v49, v129, v65
	ds_read_b128 v[62:65], v7 offset:35632
	s_waitcnt lgkmcnt(0)
	v_fmac_f32_e32 v49, v47, v62
	v_fmac_f32_e32 v49, v76, v63
	v_fmac_f32_e32 v49, v124, v64
	v_fmac_f32_e32 v49, v125, v65
	v_min_f32_e32 v62, 0, v49
	v_mul_f32_e64 v49, |v49|, s3
	v_exp_f32_e32 v49, v49
	s_nop 0
	v_add_f32_e32 v49, 1.0, v49
	v_log_f32_e32 v49, v49
	s_nop 0
	v_fmac_f32_e32 v62, 0xbf317218, v49
	v_fmamk_f32 v97, v62, 0x3d800000, v95
	ds_read_b128 v[62:65], v7 offset:35648
	s_waitcnt lgkmcnt(0)
; __device__ __forceinline__ float fexp(float x) { return __builtin_amdgcn_exp2f(x * 1.44269504089f); }
; __device__ __forceinline__ void phase_qkrope_gla_prep(const Params& p, LAS unsigned char* lds, int wave, int lane) {
;     ...
;             float bl[64]; float run = 0.f;
; #pragma unroll
;             for (int t = 0; t < 64; ++t) { float lg = bias;
; #pragma unroll
;                 for (int r = 0; r < 16; ++r) lg += gl[t * 16 + r] * gu[r];
;                 const float ls = fminf(lg, 0.f) - 0.69314718056f * __builtin_amdgcn_logf(1.0f + fexp(-fabsf(lg)));
;                 run += ls * (1.0f / 16.0f); bl[t] = run; }
;             const float bref = bl[31], blast = bl[63];
	v_fma_f32 v49, v0, v62, v46
	v_fmac_f32_e32 v49, v1, v63
	v_fmac_f32_e32 v49, v2, v64
	v_fmac_f32_e32 v49, v3, v65
	ds_read_b128 v[62:65], v7 offset:35664
	s_waitcnt lgkmcnt(0)
	v_fmac_f32_e32 v49, v133, v62
	v_fmac_f32_e32 v49, v130, v63
	v_fmac_f32_e32 v49, v131, v64
	v_fmac_f32_e32 v49, v132, v65
	ds_read_b128 v[62:65], v7 offset:35680
	s_waitcnt lgkmcnt(0)
	v_fmac_f32_e32 v49, v126, v62
	v_fmac_f32_e32 v49, v127, v63
	v_fmac_f32_e32 v49, v128, v64
	v_fmac_f32_e32 v49, v129, v65
	ds_read_b128 v[62:65], v7 offset:35696
	s_waitcnt lgkmcnt(0)
	v_fmac_f32_e32 v49, v47, v62
	v_fmac_f32_e32 v49, v76, v63
	v_fmac_f32_e32 v49, v124, v64
	v_fmac_f32_e32 v49, v125, v65
	v_min_f32_e32 v62, 0, v49
	v_mul_f32_e64 v49, |v49|, s3
	v_exp_f32_e32 v49, v49
	s_nop 0
	v_add_f32_e32 v49, 1.0, v49
	v_log_f32_e32 v49, v49
	s_nop 0
	v_fmac_f32_e32 v62, 0xbf317218, v49
	v_fmamk_f32 v99, v62, 0x3d800000, v97
	ds_read_b128 v[62:65], v7 offset:35712
	s_waitcnt lgkmcnt(0)
	v_fma_f32 v49, v0, v62, v46
	v_fmac_f32_e32 v49, v1, v63
	v_fmac_f32_e32 v49, v2, v64
	v_fmac_f32_e32 v49, v3, v65
	ds_read_b128 v[62:65], v7 offset:35728
	s_waitcnt lgkmcnt(0)
	v_fmac_f32_e32 v49, v133, v62
	v_fmac_f32_e32 v49, v130, v63
	v_fmac_f32_e32 v49, v131, v64
	v_fmac_f32_e32 v49, v132, v65
	ds_read_b128 v[62:65], v7 offset:35744
	s_waitcnt lgkmcnt(0)
	v_fmac_f32_e32 v49, v126, v62
	v_fmac_f32_e32 v49, v127, v63
	v_fmac_f32_e32 v49, v128, v64
	v_fmac_f32_e32 v49, v129, v65
	ds_read_b128 v[62:65], v7 offset:35760
	s_waitcnt lgkmcnt(0)
	v_fmac_f32_e32 v49, v47, v62
	v_fmac_f32_e32 v49, v76, v63
	v_fmac_f32_e32 v49, v124, v64
	v_fmac_f32_e32 v49, v125, v65
	v_min_f32_e32 v62, 0, v49
	v_mul_f32_e64 v49, |v49|, s3
	v_exp_f32_e32 v49, v49
	s_nop 0
	v_add_f32_e32 v49, 1.0, v49
	v_log_f32_e32 v49, v49
	s_nop 0
	v_fmac_f32_e32 v62, 0xbf317218, v49
	v_fmamk_f32 v103, v62, 0x3d800000, v99
	ds_read_b128 v[62:65], v7 offset:35776
	s_waitcnt lgkmcnt(0)
	v_fma_f32 v49, v0, v62, v46
	v_fmac_f32_e32 v49, v1, v63
	v_fmac_f32_e32 v49, v2, v64
	v_fmac_f32_e32 v49, v3, v65
	ds_read_b128 v[62:65], v7 offset:35792
	s_waitcnt lgkmcnt(0)
	v_fmac_f32_e32 v49, v133, v62
	v_fmac_f32_e32 v49, v130, v63
	v_fmac_f32_e32 v49, v131, v64
	v_fmac_f32_e32 v49, v132, v65
	ds_read_b128 v[62:65], v7 offset:35808
	s_waitcnt lgkmcnt(0)
	v_fmac_f32_e32 v49, v126, v62
	v_fmac_f32_e32 v49, v127, v63
	v_fmac_f32_e32 v49, v128, v64
	v_fmac_f32_e32 v49, v129, v65
	ds_read_b128 v[62:65], v7 offset:35824
	s_waitcnt lgkmcnt(0)
	v_fmac_f32_e32 v49, v47, v62
	v_fmac_f32_e32 v49, v76, v63
	v_fmac_f32_e32 v49, v124, v64
	v_fmac_f32_e32 v49, v125, v65
	v_min_f32_e32 v62, 0, v49
	v_mul_f32_e64 v49, |v49|, s3
	v_exp_f32_e32 v49, v49
	s_nop 0
	v_add_f32_e32 v49, 1.0, v49
	v_log_f32_e32 v49, v49
	s_nop 0
	v_fmac_f32_e32 v62, 0xbf317218, v49
	v_fmamk_f32 v106, v62, 0x3d800000, v103
	ds_read_b128 v[62:65], v7 offset:35840
	s_waitcnt lgkmcnt(0)
	v_fma_f32 v49, v0, v62, v46
	v_fmac_f32_e32 v49, v1, v63
	v_fmac_f32_e32 v49, v2, v64
	v_fmac_f32_e32 v49, v3, v65
	ds_read_b128 v[62:65], v7 offset:35856
	s_waitcnt lgkmcnt(0)
	v_fmac_f32_e32 v49, v133, v62
	v_fmac_f32_e32 v49, v130, v63
	v_fmac_f32_e32 v49, v131, v64
	v_fmac_f32_e32 v49, v132, v65
	ds_read_b128 v[62:65], v7 offset:35872
	s_waitcnt lgkmcnt(0)
	v_fmac_f32_e32 v49, v126, v62
	v_fmac_f32_e32 v49, v127, v63
	v_fmac_f32_e32 v49, v128, v64
	v_fmac_f32_e32 v49, v129, v65
	ds_read_b128 v[62:65], v7 offset:35888
	s_waitcnt lgkmcnt(0)
	v_fmac_f32_e32 v49, v47, v62
	v_fmac_f32_e32 v49, v76, v63
	v_fmac_f32_e32 v49, v124, v64
	v_fmac_f32_e32 v49, v125, v65
	v_min_f32_e32 v62, 0, v49
	v_mul_f32_e64 v49, |v49|, s3
	v_exp_f32_e32 v49, v49
	s_nop 0
	v_add_f32_e32 v49, 1.0, v49
	v_log_f32_e32 v49, v49
	s_nop 0
	v_fmac_f32_e32 v62, 0xbf317218, v49
	v_fmamk_f32 v49, v62, 0x3d800000, v106
	ds_read_b128 v[62:65], v7 offset:35904
	s_waitcnt lgkmcnt(0)
	v_fma_f32 v66, v0, v62, v46
	v_fmac_f32_e32 v66, v1, v63
	v_fmac_f32_e32 v66, v2, v64
	v_fmac_f32_e32 v66, v3, v65
	ds_read_b128 v[62:65], v7 offset:35920
	s_waitcnt lgkmcnt(0)
	v_fmac_f32_e32 v66, v133, v62
	v_fmac_f32_e32 v66, v130, v63
	v_fmac_f32_e32 v66, v131, v64
	v_fmac_f32_e32 v66, v132, v65
	ds_read_b128 v[62:65], v7 offset:35936
	s_waitcnt lgkmcnt(0)
	v_fmac_f32_e32 v66, v126, v62
	v_fmac_f32_e32 v66, v127, v63
	v_fmac_f32_e32 v66, v128, v64
	v_fmac_f32_e32 v66, v129, v65
	ds_read_b128 v[62:65], v7 offset:35952
	s_waitcnt lgkmcnt(0)
	v_fmac_f32_e32 v66, v47, v62
	v_fmac_f32_e32 v66, v76, v63
	v_fmac_f32_e32 v66, v124, v64
	v_fmac_f32_e32 v66, v125, v65
	v_mul_f32_e64 v63, |v66|, s3
	v_exp_f32_e32 v63, v63
	v_min_f32_e32 v62, 0, v66
	ds_read_b128 v[64:67], v7 offset:35968
	v_add_f32_e32 v63, 1.0, v63
	v_log_f32_e32 v63, v63
	s_nop 0
	v_fmac_f32_e32 v62, 0xbf317218, v63
	s_waitcnt lgkmcnt(0)
	v_fma_f32 v63, v0, v64, v46
	v_fmac_f32_e32 v63, v1, v65
	v_fmac_f32_e32 v63, v2, v66
	v_fmac_f32_e32 v63, v3, v67
	ds_read_b128 v[64:67], v7 offset:35984
	v_fmamk_f32 v62, v62, 0x3d800000, v49
	s_waitcnt lgkmcnt(0)
	v_fmac_f32_e32 v63, v133, v64
	v_fmac_f32_e32 v63, v130, v65
	v_fmac_f32_e32 v63, v131, v66
	v_fmac_f32_e32 v63, v132, v67
	ds_read_b128 v[64:67], v7 offset:36000
	s_waitcnt lgkmcnt(0)
	v_fmac_f32_e32 v63, v126, v64
	v_fmac_f32_e32 v63, v127, v65
	v_fmac_f32_e32 v63, v128, v66
	v_fmac_f32_e32 v63, v129, v67
	ds_read_b128 v[64:67], v7 offset:36016
	s_waitcnt lgkmcnt(0)
	v_fmac_f32_e32 v63, v47, v64
	v_fmac_f32_e32 v63, v76, v65
	v_fmac_f32_e32 v63, v124, v66
	v_fmac_f32_e32 v63, v125, v67
	v_min_f32_e32 v64, 0, v63
	v_mul_f32_e64 v63, |v63|, s3
	v_exp_f32_e32 v63, v63
	s_nop 0
	v_add_f32_e32 v63, 1.0, v63
	v_log_f32_e32 v63, v63
	s_nop 0
	v_fmac_f32_e32 v64, 0xbf317218, v63
	v_fmamk_f32 v63, v64, 0x3d800000, v62
	ds_read_b128 v[64:67], v7 offset:36032
	s_waitcnt lgkmcnt(0)
; __device__ __forceinline__ float fexp(float x) { return __builtin_amdgcn_exp2f(x * 1.44269504089f); }
; __device__ __forceinline__ void phase_qkrope_gla_prep(const Params& p, LAS unsigned char* lds, int wave, int lane) {
;     ...
;             float bl[64]; float run = 0.f;
; #pragma unroll
;             for (int t = 0; t < 64; ++t) { float lg = bias;
; #pragma unroll
;                 for (int r = 0; r < 16; ++r) lg += gl[t * 16 + r] * gu[r];
;                 const float ls = fminf(lg, 0.f) - 0.69314718056f * __builtin_amdgcn_logf(1.0f + fexp(-fabsf(lg)));
;                 run += ls * (1.0f / 16.0f); bl[t] = run; }
;             const float bref = bl[31], blast = bl[63];
	v_fma_f32 v69, v0, v64, v46
	v_fmac_f32_e32 v69, v1, v65
	v_fmac_f32_e32 v69, v2, v66
	v_fmac_f32_e32 v69, v3, v67
	ds_read_b128 v[64:67], v7 offset:36048
	s_waitcnt lgkmcnt(0)
	v_fmac_f32_e32 v69, v133, v64
	v_fmac_f32_e32 v69, v130, v65
	v_fmac_f32_e32 v69, v131, v66
	v_fmac_f32_e32 v69, v132, v67
	ds_read_b128 v[64:67], v7 offset:36064
	s_waitcnt lgkmcnt(0)
	v_fmac_f32_e32 v69, v126, v64
	v_fmac_f32_e32 v69, v127, v65
	v_fmac_f32_e32 v69, v128, v66
	v_fmac_f32_e32 v69, v129, v67
	ds_read_b128 v[64:67], v7 offset:36080
	s_waitcnt lgkmcnt(0)
	v_fmac_f32_e32 v69, v47, v64
	v_fmac_f32_e32 v69, v76, v65
	v_fmac_f32_e32 v69, v124, v66
	v_fmac_f32_e32 v69, v125, v67
	v_mul_f32_e64 v65, |v69|, s3
	v_exp_f32_e32 v65, v65
	v_min_f32_e32 v64, 0, v69
	v_add_f32_e32 v65, 1.0, v65
	v_log_f32_e32 v65, v65
	s_nop 0
	v_fmac_f32_e32 v64, 0xbf317218, v65
	v_fma_f32 v65, v0, v134, v46
	v_fmac_f32_e32 v65, v1, v135
	v_fmac_f32_e32 v65, v2, v136
	v_fmac_f32_e32 v65, v3, v137
	ds_read_b128 v[134:137], v7 offset:36112
	v_fmamk_f32 v64, v64, 0x3d800000, v63
	s_waitcnt lgkmcnt(0)
	v_fmac_f32_e32 v65, v133, v134
	v_fmac_f32_e32 v65, v130, v135
	v_fmac_f32_e32 v65, v131, v136
	v_fmac_f32_e32 v65, v132, v137
	ds_read_b128 v[134:137], v7 offset:36128
	s_waitcnt lgkmcnt(0)
	v_fmac_f32_e32 v65, v126, v134
	v_fmac_f32_e32 v65, v127, v135
	v_fmac_f32_e32 v65, v128, v136
	v_fmac_f32_e32 v65, v129, v137
	ds_read_b128 v[134:137], v7 offset:36144
	s_waitcnt lgkmcnt(0)
	v_fmac_f32_e32 v65, v47, v134
	v_fmac_f32_e32 v65, v76, v135
	v_fmac_f32_e32 v65, v124, v136
	v_fmac_f32_e32 v65, v125, v137
	v_min_f32_e32 v66, 0, v65
	v_mul_f32_e64 v65, |v65|, s3
	v_exp_f32_e32 v65, v65
	ds_read_b128 v[134:137], v7 offset:36160
	v_add_f32_e32 v65, 1.0, v65
	v_log_f32_e32 v65, v65
	s_nop 0
	v_fmac_f32_e32 v66, 0xbf317218, v65
	v_fmamk_f32 v65, v66, 0x3d800000, v64
	s_waitcnt lgkmcnt(0)
	v_fma_f32 v66, v0, v134, v46
	v_fmac_f32_e32 v66, v1, v135
	v_fmac_f32_e32 v66, v2, v136
	v_fmac_f32_e32 v66, v3, v137
	ds_read_b128 v[134:137], v7 offset:36176
	s_waitcnt lgkmcnt(0)
	v_fmac_f32_e32 v66, v133, v134
	v_fmac_f32_e32 v66, v130, v135
	v_fmac_f32_e32 v66, v131, v136
	v_fmac_f32_e32 v66, v132, v137
	ds_read_b128 v[134:137], v7 offset:36192
	s_waitcnt lgkmcnt(0)
	v_fmac_f32_e32 v66, v126, v134
	v_fmac_f32_e32 v66, v127, v135
	v_fmac_f32_e32 v66, v128, v136
	v_fmac_f32_e32 v66, v129, v137
	ds_read_b128 v[134:137], v7 offset:36208
	s_waitcnt lgkmcnt(0)
	v_fmac_f32_e32 v66, v47, v134
	v_fmac_f32_e32 v66, v76, v135
	v_fmac_f32_e32 v66, v124, v136
	v_fmac_f32_e32 v66, v125, v137
	v_min_f32_e32 v67, 0, v66
	v_mul_f32_e64 v66, |v66|, s3
	v_exp_f32_e32 v66, v66
	ds_read_b128 v[134:137], v7 offset:36224
	v_add_f32_e32 v66, 1.0, v66
	v_log_f32_e32 v66, v66
	s_nop 0
	v_fmac_f32_e32 v67, 0xbf317218, v66
	v_fmamk_f32 v66, v67, 0x3d800000, v65
	s_waitcnt lgkmcnt(0)
	v_fma_f32 v67, v0, v134, v46
	v_fmac_f32_e32 v67, v1, v135
	v_fmac_f32_e32 v67, v2, v136
	v_fmac_f32_e32 v67, v3, v137
	ds_read_b128 v[134:137], v7 offset:36240
	s_waitcnt lgkmcnt(0)
	v_fmac_f32_e32 v67, v133, v134
	v_fmac_f32_e32 v67, v130, v135
	v_fmac_f32_e32 v67, v131, v136
	v_fmac_f32_e32 v67, v132, v137
	ds_read_b128 v[134:137], v7 offset:36256
	s_waitcnt lgkmcnt(0)
	v_fmac_f32_e32 v67, v126, v134
	v_fmac_f32_e32 v67, v127, v135
	v_fmac_f32_e32 v67, v128, v136
	v_fmac_f32_e32 v67, v129, v137
	ds_read_b128 v[134:137], v7 offset:36272
	s_waitcnt lgkmcnt(0)
	v_fmac_f32_e32 v67, v47, v134
	v_fmac_f32_e32 v67, v76, v135
	v_fmac_f32_e32 v67, v124, v136
	v_fmac_f32_e32 v67, v125, v137
	v_min_f32_e32 v69, 0, v67
	v_mul_f32_e64 v67, |v67|, s3
	v_exp_f32_e32 v67, v67
	ds_read_b128 v[134:137], v7 offset:36288
	v_add_f32_e32 v67, 1.0, v67
	v_log_f32_e32 v67, v67
	s_nop 0
	v_fmac_f32_e32 v69, 0xbf317218, v67
	v_fmamk_f32 v67, v69, 0x3d800000, v66
	s_waitcnt lgkmcnt(0)
	v_fma_f32 v69, v0, v134, v46
	v_fmac_f32_e32 v69, v1, v135
	v_fmac_f32_e32 v69, v2, v136
	v_fmac_f32_e32 v69, v3, v137
	ds_read_b128 v[134:137], v7 offset:36304
	s_waitcnt lgkmcnt(0)
	v_fmac_f32_e32 v69, v133, v134
	v_fmac_f32_e32 v69, v130, v135
	v_fmac_f32_e32 v69, v131, v136
	v_fmac_f32_e32 v69, v132, v137
	ds_read_b128 v[134:137], v7 offset:36320
	s_waitcnt lgkmcnt(0)
	v_fmac_f32_e32 v69, v126, v134
	v_fmac_f32_e32 v69, v127, v135
	v_fmac_f32_e32 v69, v128, v136
	v_fmac_f32_e32 v69, v129, v137
	ds_read_b128 v[134:137], v7 offset:36336
	s_waitcnt lgkmcnt(0)
	v_fmac_f32_e32 v69, v47, v134
	v_fmac_f32_e32 v69, v76, v135
	v_fmac_f32_e32 v69, v124, v136
	v_fmac_f32_e32 v69, v125, v137
	v_min_f32_e32 v71, 0, v69
	v_mul_f32_e64 v69, |v69|, s3
	v_exp_f32_e32 v69, v69
	ds_read_b128 v[134:137], v7 offset:36352
	v_add_f32_e32 v69, 1.0, v69
	v_log_f32_e32 v69, v69
	s_nop 0
	v_fmac_f32_e32 v71, 0xbf317218, v69
	v_fmamk_f32 v69, v71, 0x3d800000, v67
	s_waitcnt lgkmcnt(0)
	v_fma_f32 v71, v0, v134, v46
	v_fmac_f32_e32 v71, v1, v135
	v_fmac_f32_e32 v71, v2, v136
	v_fmac_f32_e32 v71, v3, v137
	ds_read_b128 v[134:137], v7 offset:36368
	s_waitcnt lgkmcnt(0)
	v_fmac_f32_e32 v71, v133, v134
	v_fmac_f32_e32 v71, v130, v135
	v_fmac_f32_e32 v71, v131, v136
	v_fmac_f32_e32 v71, v132, v137
	ds_read_b128 v[134:137], v7 offset:36384
	s_waitcnt lgkmcnt(0)
	v_fmac_f32_e32 v71, v126, v134
	v_fmac_f32_e32 v71, v127, v135
	v_fmac_f32_e32 v71, v128, v136
	v_fmac_f32_e32 v71, v129, v137
	ds_read_b128 v[134:137], v7 offset:36400
	s_waitcnt lgkmcnt(0)
	v_fmac_f32_e32 v71, v47, v134
	v_fmac_f32_e32 v71, v76, v135
	v_fmac_f32_e32 v71, v124, v136
	v_fmac_f32_e32 v71, v125, v137
	v_min_f32_e32 v73, 0, v71
	v_mul_f32_e64 v71, |v71|, s3
	v_exp_f32_e32 v71, v71
	ds_read_b128 v[134:137], v7 offset:36416
	v_add_f32_e32 v71, 1.0, v71
	v_log_f32_e32 v71, v71
	s_nop 0
	v_fmac_f32_e32 v73, 0xbf317218, v71
	v_fmamk_f32 v71, v73, 0x3d800000, v69
	s_waitcnt lgkmcnt(0)
; __device__ __forceinline__ float fexp(float x) { return __builtin_amdgcn_exp2f(x * 1.44269504089f); }
; __device__ __forceinline__ void phase_qkrope_gla_prep(const Params& p, LAS unsigned char* lds, int wave, int lane) {
;     ...
;             float bl[64]; float run = 0.f;
; #pragma unroll
;             for (int t = 0; t < 64; ++t) { float lg = bias;
; #pragma unroll
;                 for (int r = 0; r < 16; ++r) lg += gl[t * 16 + r] * gu[r];
;                 const float ls = fminf(lg, 0.f) - 0.69314718056f * __builtin_amdgcn_logf(1.0f + fexp(-fabsf(lg)));
;                 run += ls * (1.0f / 16.0f); bl[t] = run; }
;             const float bref = bl[31], blast = bl[63];
	v_fma_f32 v73, v0, v134, v46
	v_fmac_f32_e32 v73, v1, v135
	v_fmac_f32_e32 v73, v2, v136
	v_fmac_f32_e32 v73, v3, v137
	ds_read_b128 v[134:137], v7 offset:36432
	s_waitcnt lgkmcnt(0)
	v_fmac_f32_e32 v73, v133, v134
	v_fmac_f32_e32 v73, v130, v135
	v_fmac_f32_e32 v73, v131, v136
	v_fmac_f32_e32 v73, v132, v137
	ds_read_b128 v[134:137], v7 offset:36448
	s_waitcnt lgkmcnt(0)
	v_fmac_f32_e32 v73, v126, v134
	v_fmac_f32_e32 v73, v127, v135
	v_fmac_f32_e32 v73, v128, v136
	v_fmac_f32_e32 v73, v129, v137
	ds_read_b128 v[134:137], v7 offset:36464
	s_waitcnt lgkmcnt(0)
	v_fmac_f32_e32 v73, v47, v134
	v_fmac_f32_e32 v73, v76, v135
	v_fmac_f32_e32 v73, v124, v136
	v_fmac_f32_e32 v73, v125, v137
	v_min_f32_e32 v75, 0, v73
	v_mul_f32_e64 v73, |v73|, s3
	v_exp_f32_e32 v73, v73
	ds_read_b128 v[134:137], v7 offset:36480
	v_add_f32_e32 v73, 1.0, v73
	v_log_f32_e32 v73, v73
	s_nop 0
	v_fmac_f32_e32 v75, 0xbf317218, v73
	v_fmamk_f32 v73, v75, 0x3d800000, v71
	s_waitcnt lgkmcnt(0)
	v_fma_f32 v75, v0, v134, v46
	v_fmac_f32_e32 v75, v1, v135
	v_fmac_f32_e32 v75, v2, v136
	v_fmac_f32_e32 v75, v3, v137
	ds_read_b128 v[134:137], v7 offset:36496
	s_waitcnt lgkmcnt(0)
	v_fmac_f32_e32 v75, v133, v134
	v_fmac_f32_e32 v75, v130, v135
	v_fmac_f32_e32 v75, v131, v136
	v_fmac_f32_e32 v75, v132, v137
	ds_read_b128 v[134:137], v7 offset:36512
	s_waitcnt lgkmcnt(0)
	v_fmac_f32_e32 v75, v126, v134
	v_fmac_f32_e32 v75, v127, v135
	v_fmac_f32_e32 v75, v128, v136
	v_fmac_f32_e32 v75, v129, v137
	ds_read_b128 v[134:137], v7 offset:36528
	s_waitcnt lgkmcnt(0)
	v_fmac_f32_e32 v75, v47, v134
	v_fmac_f32_e32 v75, v76, v135
	v_fmac_f32_e32 v75, v124, v136
	v_fmac_f32_e32 v75, v125, v137
	v_min_f32_e32 v78, 0, v75
	v_mul_f32_e64 v75, |v75|, s3
	v_exp_f32_e32 v75, v75
	ds_read_b128 v[134:137], v7 offset:36544
	v_add_f32_e32 v75, 1.0, v75
	v_log_f32_e32 v75, v75
	s_nop 0
	v_fmac_f32_e32 v78, 0xbf317218, v75
	v_fmamk_f32 v75, v78, 0x3d800000, v73
	s_waitcnt lgkmcnt(0)
	v_fma_f32 v78, v0, v134, v46
	v_fmac_f32_e32 v78, v1, v135
	v_fmac_f32_e32 v78, v2, v136
	v_fmac_f32_e32 v78, v3, v137
	ds_read_b128 v[134:137], v7 offset:36560
	s_waitcnt lgkmcnt(0)
	v_fmac_f32_e32 v78, v133, v134
	v_fmac_f32_e32 v78, v130, v135
	v_fmac_f32_e32 v78, v131, v136
	v_fmac_f32_e32 v78, v132, v137
	ds_read_b128 v[134:137], v7 offset:36576
	s_waitcnt lgkmcnt(0)
	v_fmac_f32_e32 v78, v126, v134
	v_fmac_f32_e32 v78, v127, v135
	v_fmac_f32_e32 v78, v128, v136
	v_fmac_f32_e32 v78, v129, v137
	ds_read_b128 v[134:137], v7 offset:36592
	s_waitcnt lgkmcnt(0)
	v_fmac_f32_e32 v78, v47, v134
	v_fmac_f32_e32 v78, v76, v135
	v_fmac_f32_e32 v78, v124, v136
	v_fmac_f32_e32 v78, v125, v137
	v_min_f32_e32 v80, 0, v78
	v_mul_f32_e64 v78, |v78|, s3
	v_exp_f32_e32 v78, v78
	ds_read_b128 v[134:137], v7 offset:36608
	v_add_f32_e32 v78, 1.0, v78
	v_log_f32_e32 v78, v78
	s_nop 0
	v_fmac_f32_e32 v80, 0xbf317218, v78
	v_fmamk_f32 v78, v80, 0x3d800000, v75
	s_waitcnt lgkmcnt(0)
	v_fma_f32 v80, v0, v134, v46
	v_fmac_f32_e32 v80, v1, v135
	v_fmac_f32_e32 v80, v2, v136
	v_fmac_f32_e32 v80, v3, v137
	ds_read_b128 v[134:137], v7 offset:36624
	s_waitcnt lgkmcnt(0)
	v_fmac_f32_e32 v80, v133, v134
	v_fmac_f32_e32 v80, v130, v135
	v_fmac_f32_e32 v80, v131, v136
	v_fmac_f32_e32 v80, v132, v137
	ds_read_b128 v[134:137], v7 offset:36640
	s_waitcnt lgkmcnt(0)
	v_fmac_f32_e32 v80, v126, v134
	v_fmac_f32_e32 v80, v127, v135
	v_fmac_f32_e32 v80, v128, v136
	v_fmac_f32_e32 v80, v129, v137
	ds_read_b128 v[134:137], v7 offset:36656
	s_waitcnt lgkmcnt(0)
	v_fmac_f32_e32 v80, v47, v134
	v_fmac_f32_e32 v80, v76, v135
	v_fmac_f32_e32 v80, v124, v136
	v_fmac_f32_e32 v80, v125, v137
	v_min_f32_e32 v84, 0, v80
	v_mul_f32_e64 v80, |v80|, s3
	v_exp_f32_e32 v80, v80
	ds_read_b128 v[134:137], v7 offset:36672
	v_add_f32_e32 v80, 1.0, v80
	v_log_f32_e32 v80, v80
	s_nop 0
	v_fmac_f32_e32 v84, 0xbf317218, v80
	v_fmamk_f32 v80, v84, 0x3d800000, v78
	s_waitcnt lgkmcnt(0)
	v_fma_f32 v84, v0, v134, v46
	v_fmac_f32_e32 v84, v1, v135
	v_fmac_f32_e32 v84, v2, v136
	v_fmac_f32_e32 v84, v3, v137
	ds_read_b128 v[134:137], v7 offset:36688
	s_waitcnt lgkmcnt(0)
	v_fmac_f32_e32 v84, v133, v134
	v_fmac_f32_e32 v84, v130, v135
	v_fmac_f32_e32 v84, v131, v136
	v_fmac_f32_e32 v84, v132, v137
	ds_read_b128 v[134:137], v7 offset:36704
	s_waitcnt lgkmcnt(0)
	v_fmac_f32_e32 v84, v126, v134
	v_fmac_f32_e32 v84, v127, v135
	v_fmac_f32_e32 v84, v128, v136
	v_fmac_f32_e32 v84, v129, v137
	ds_read_b128 v[134:137], v7 offset:36720
	s_waitcnt lgkmcnt(0)
	v_fmac_f32_e32 v84, v47, v134
	v_fmac_f32_e32 v84, v76, v135
	v_fmac_f32_e32 v84, v124, v136
	v_fmac_f32_e32 v84, v125, v137
	v_min_f32_e32 v87, 0, v84
	v_mul_f32_e64 v84, |v84|, s3
	v_exp_f32_e32 v84, v84
	ds_read_b128 v[134:137], v7 offset:36736
	v_add_f32_e32 v84, 1.0, v84
	v_log_f32_e32 v84, v84
	s_nop 0
	v_fmac_f32_e32 v87, 0xbf317218, v84
	v_fmamk_f32 v84, v87, 0x3d800000, v80
	s_waitcnt lgkmcnt(0)
	v_fma_f32 v87, v0, v134, v46
	v_fmac_f32_e32 v87, v1, v135
	v_fmac_f32_e32 v87, v2, v136
	v_fmac_f32_e32 v87, v3, v137
	ds_read_b128 v[134:137], v7 offset:36752
	s_waitcnt lgkmcnt(0)
	v_fmac_f32_e32 v87, v133, v134
	v_fmac_f32_e32 v87, v130, v135
	v_fmac_f32_e32 v87, v131, v136
	v_fmac_f32_e32 v87, v132, v137
	ds_read_b128 v[134:137], v7 offset:36768
	s_waitcnt lgkmcnt(0)
	v_fmac_f32_e32 v87, v126, v134
	v_fmac_f32_e32 v87, v127, v135
	v_fmac_f32_e32 v87, v128, v136
	v_fmac_f32_e32 v87, v129, v137
	ds_read_b128 v[134:137], v7 offset:36784
	s_waitcnt lgkmcnt(0)
; __device__ __forceinline__ unsigned cvtpk(float lo, float hi) { f32x2 v = {lo, hi}; bf16x2_t b = __builtin_convertvector(v, bf16x2_t); return __builtin_bit_cast(unsigned, b); }
; __device__ __forceinline__ float fexp(float x) { return __builtin_amdgcn_exp2f(x * 1.44269504089f); }
; __device__ __forceinline__ void phase_qkrope_gla_prep(const Params& p, LAS unsigned char* lds, int wave, int lane) {
;     ...
;             float bl[64]; float run = 0.f;
; #pragma unroll
;             for (int t = 0; t < 64; ++t) { float lg = bias;
; #pragma unroll
;                 for (int r = 0; r < 16; ++r) lg += gl[t * 16 + r] * gu[r];
;                 const float ls = fminf(lg, 0.f) - 0.69314718056f * __builtin_amdgcn_logf(1.0f + fexp(-fabsf(lg)));
;                 run += ls * (1.0f / 16.0f); bl[t] = run; }
;             const float bref = bl[31], blast = bl[63];
;     ...
;             for (int tb = 0; tb < 4; ++tb) {
;                 unsigned short qv[16], kv[16];
; #pragma unroll
;                 for (int t = 0; t < 16; ++t) { const size_t ro = (size_t)(m0 + 16 * tb + t) * ZP + d; qv[t] = Z[ro + C_QG]; kv[t] = Z[ro + C_KG]; }
; #pragma unroll
;                 for (int t = 0; t < 16; ++t) { const size_t ro = (size_t)(m0 + 16 * tb + t) * ZP + d; const float bb = bl[16 * tb + t];
;                     const float qs = bf2f(qv[t]) * 0.08838834764831845f * fexp(bb - bref), ks = bf2f(kv[t]) * fexp(bref - bb);
;                     Z[ro + C_QG] = (bf16_t)(cvtpk(qs, 0.f) & 0xffffu); Z[ro + C_KG] = (bf16_t)(cvtpk(ks, 0.f) & 0xffffu); }
	v_fmac_f32_e32 v87, v47, v134
	v_fmac_f32_e32 v87, v76, v135
	v_fmac_f32_e32 v87, v124, v136
	v_fmac_f32_e32 v87, v125, v137
	v_min_f32_e32 v134, 0, v87
	v_mul_f32_e64 v87, |v87|, s3
	v_exp_f32_e32 v87, v87
	s_nop 0
	v_add_f32_e32 v87, 1.0, v87
	v_log_f32_e32 v87, v87
	s_nop 0
	v_fmac_f32_e32 v134, 0xbf317218, v87
	v_fmamk_f32 v87, v134, 0x3d800000, v84
	ds_read_b128 v[134:137], v7 offset:36800
	s_waitcnt lgkmcnt(0)
	v_fmac_f32_e32 v46, v0, v134
	v_fmac_f32_e32 v46, v1, v135
	v_fmac_f32_e32 v46, v2, v136
	v_fmac_f32_e32 v46, v3, v137
	ds_read_b128 v[0:3], v7 offset:36816
	s_waitcnt lgkmcnt(0)
	v_fmac_f32_e32 v46, v133, v0
	v_fmac_f32_e32 v46, v130, v1
	v_fmac_f32_e32 v46, v131, v2
	v_fmac_f32_e32 v46, v132, v3
	ds_read_b128 v[0:3], v7 offset:36832
	s_waitcnt lgkmcnt(0)
	v_fmac_f32_e32 v46, v126, v0
	v_fmac_f32_e32 v46, v127, v1
	v_fmac_f32_e32 v46, v128, v2
	v_fmac_f32_e32 v46, v129, v3
	ds_read_b128 v[0:3], v7 offset:36848
	s_waitcnt lgkmcnt(0)
	v_fmac_f32_e32 v46, v47, v0
	v_fmac_f32_e32 v46, v76, v1
	v_fmac_f32_e32 v46, v124, v2
	v_fmac_f32_e32 v46, v125, v3
	v_mul_f32_e64 v1, |v46|, s3
	v_exp_f32_e32 v1, v1
	v_min_f32_e32 v0, 0, v46
	v_add_f32_e32 v1, 1.0, v1
	v_log_f32_e32 v1, v1
	s_nop 0
	v_fmac_f32_e32 v0, 0xbf317218, v1
	v_fmamk_f32 v76, v0, 0x3d800000, v87
	v_mad_i64_i32 v[0:1], s[4:5], s19, v61, v[8:9]
	global_load_ushort v150, v[0:1], off
	s_sub_i32 s4, s0, 62
	v_mad_i64_i32 v[124:125], s[4:5], s4, v61, v[8:9]
	s_sub_i32 s4, s0, 61
	s_nop 0
	v_mad_i64_i32 v[126:127], s[4:5], s4, v61, v[8:9]
	s_sub_i32 s4, s0, 60
	s_nop 0
	v_mad_i64_i32 v[128:129], s[4:5], s4, v61, v[8:9]
	s_sub_i32 s4, s0, 59
	s_nop 0
	v_mad_i64_i32 v[130:131], s[4:5], s4, v61, v[8:9]
	s_sub_i32 s4, s0, 58
	s_nop 0
	v_mad_i64_i32 v[132:133], s[4:5], s4, v61, v[8:9]
	s_sub_i32 s4, s0, 57
	s_nop 0
	v_mad_i64_i32 v[134:135], s[4:5], s4, v61, v[8:9]
	s_sub_i32 s4, s0, 56
	s_nop 0
	v_mad_i64_i32 v[136:137], s[4:5], s4, v61, v[8:9]
	s_sub_i32 s4, s0, 55
	s_nop 0
	v_mad_i64_i32 v[138:139], s[4:5], s4, v61, v[8:9]
	s_sub_i32 s4, s0, 54
	s_nop 0
	v_mad_i64_i32 v[140:141], s[4:5], s4, v61, v[8:9]
	s_sub_i32 s4, s0, 53
	s_nop 0
	v_mad_i64_i32 v[142:143], s[4:5], s4, v61, v[8:9]
	s_sub_i32 s4, s0, 52
	s_nop 0
	v_mad_i64_i32 v[144:145], s[4:5], s4, v61, v[8:9]
	s_sub_i32 s4, s0, 51
	s_nop 0
	v_mad_i64_i32 v[146:147], s[4:5], s4, v61, v[8:9]
	s_sub_i32 s4, s0, 50
	s_nop 0
	v_mad_i64_i32 v[148:149], s[4:5], s4, v61, v[8:9]
	s_sub_i32 s4, s0, 49
	s_nop 0
	v_mad_i64_i32 v[46:47], s[4:5], s4, v61, v[8:9]
	s_sub_i32 s4, s0, 48
	s_nop 0
	v_mad_i64_i32 v[2:3], s[4:5], s4, v61, v[8:9]
	s_sub_i32 s4, s0, 47
	s_ashr_i32 s19, s18, 31
	s_waitcnt vmcnt(0)
	v_lshlrev_b32_e32 v150, 16, v150
	v_mul_f32_e32 v150, 0x3db504f3, v150
	v_mul_f32_e32 v150, v151, v150
	global_load_ushort v151, v[0:1], off offset:1024
	v_cvt_pk_bf16_f32 v150, v150, s0
	s_waitcnt vmcnt(0)
	v_lshlrev_b32_e32 v151, 16, v151
	v_mul_f32_e32 v100, v100, v151
	global_load_ushort v151, v[124:125], off
	global_load_ushort v152, v[124:125], off offset:1024
	global_load_ushort v153, v[126:127], off
	global_load_ushort v154, v[126:127], off offset:1024
	global_load_ushort v155, v[128:129], off
	global_load_ushort v156, v[128:129], off offset:1024
	global_load_ushort v157, v[130:131], off
	global_load_ushort v158, v[130:131], off offset:1024
	global_load_ushort v159, v[132:133], off
	global_load_ushort v160, v[132:133], off offset:1024
	global_load_ushort v161, v[134:135], off
	global_load_ushort v162, v[134:135], off offset:1024
	global_load_ushort v163, v[136:137], off
	global_load_ushort v164, v[136:137], off offset:1024
	global_load_ushort v165, v[138:139], off
	global_load_ushort v166, v[138:139], off offset:1024
	global_load_ushort v167, v[140:141], off
	global_load_ushort v168, v[140:141], off offset:1024
	global_load_ushort v169, v[142:143], off
	global_load_ushort v170, v[142:143], off offset:1024
	global_load_ushort v171, v[144:145], off
	global_load_ushort v172, v[144:145], off offset:1024
	global_load_ushort v173, v[146:147], off
	global_load_ushort v174, v[146:147], off offset:1024
	global_load_ushort v175, v[148:149], off
	global_load_ushort v176, v[148:149], off offset:1024
	global_load_ushort v177, v[46:47], off
	global_load_ushort v178, v[46:47], off offset:1024
	global_load_ushort v179, v[2:3], off
	global_load_ushort v180, v[2:3], off offset:1024
	v_cvt_pk_bf16_f32 v100, v100, s0
	global_store_short v[0:1], v150, off
	global_store_short v[0:1], v100, off offset:1024
	v_sub_f32_e32 v1, v102, v48
	v_mul_f32_e32 v1, 0x3fb8aa3b, v1
	v_sub_f32_e32 v100, v48, v102
	v_exp_f32_e32 v1, v1
	v_mul_f32_e32 v100, 0x3fb8aa3b, v100
	v_exp_f32_e32 v100, v100
	v_sub_f32_e32 v102, v81, v48
	v_mul_f32_e32 v102, 0x3fb8aa3b, v102
	v_exp_f32_e32 v102, v102
	v_sub_f32_e32 v81, v48, v81
	v_mul_f32_e32 v81, 0x3fb8aa3b, v81
	v_exp_f32_e32 v81, v81
	s_waitcnt vmcnt(31)
	v_lshlrev_b32_e32 v0, 16, v151
	v_mul_f32_e32 v0, 0x3db504f3, v0
	v_mul_f32_e32 v0, v1, v0
	s_waitcnt vmcnt(30)
	v_lshlrev_b32_e32 v1, 16, v152
	v_mul_f32_e32 v1, v100, v1
	v_cvt_pk_bf16_f32 v0, v0, s0
	global_store_short v[124:125], v0, off
	v_cvt_pk_bf16_f32 v0, v1, s0
	v_sub_f32_e32 v1, v104, v48
	v_mul_f32_e32 v1, 0x3fb8aa3b, v1
	v_sub_f32_e32 v100, v48, v104
	v_exp_f32_e32 v1, v1
	v_mul_f32_e32 v100, 0x3fb8aa3b, v100
	v_exp_f32_e32 v100, v100
	global_store_short v[124:125], v0, off offset:1024
	s_waitcnt vmcnt(31)
	v_lshlrev_b32_e32 v0, 16, v153
	v_mul_f32_e32 v0, 0x3db504f3, v0
	v_mul_f32_e32 v0, v1, v0
	s_waitcnt vmcnt(30)
; __device__ __forceinline__ unsigned cvtpk(float lo, float hi) { f32x2 v = {lo, hi}; bf16x2_t b = __builtin_convertvector(v, bf16x2_t); return __builtin_bit_cast(unsigned, b); }
; __device__ __forceinline__ float fexp(float x) { return __builtin_amdgcn_exp2f(x * 1.44269504089f); }
; __device__ __forceinline__ void phase_qkrope_gla_prep(const Params& p, LAS unsigned char* lds, int wave, int lane) {
;     ...
;                 for (int t = 0; t < 16; ++t) { const size_t ro = (size_t)(m0 + 16 * tb + t) * ZP + d; const float bb = bl[16 * tb + t];
;                     const float qs = bf2f(qv[t]) * 0.08838834764831845f * fexp(bb - bref), ks = bf2f(kv[t]) * fexp(bref - bb);
;                     Z[ro + C_QG] = (bf16_t)(cvtpk(qs, 0.f) & 0xffffu); Z[ro + C_KG] = (bf16_t)(cvtpk(ks, 0.f) & 0xffffu); }
	v_lshlrev_b32_e32 v1, 16, v154
	v_mul_f32_e32 v1, v100, v1
	v_cvt_pk_bf16_f32 v0, v0, s0
	global_store_short v[126:127], v0, off
	v_cvt_pk_bf16_f32 v0, v1, s0
	v_sub_f32_e32 v1, v107, v48
	v_mul_f32_e32 v1, 0x3fb8aa3b, v1
	v_sub_f32_e32 v100, v48, v107
	v_exp_f32_e32 v1, v1
	v_mul_f32_e32 v100, 0x3fb8aa3b, v100
	v_exp_f32_e32 v100, v100
	global_store_short v[126:127], v0, off offset:1024
	s_waitcnt vmcnt(31)
	v_lshlrev_b32_e32 v0, 16, v155
	v_mul_f32_e32 v0, 0x3db504f3, v0
	v_mul_f32_e32 v0, v1, v0
	s_waitcnt vmcnt(30)
	v_lshlrev_b32_e32 v1, 16, v156
	v_mul_f32_e32 v1, v100, v1
	v_cvt_pk_bf16_f32 v0, v0, s0
	global_store_short v[128:129], v0, off
	v_cvt_pk_bf16_f32 v0, v1, s0
	v_sub_f32_e32 v1, v109, v48
	v_mul_f32_e32 v1, 0x3fb8aa3b, v1
	v_sub_f32_e32 v100, v48, v109
	v_exp_f32_e32 v1, v1
	v_mul_f32_e32 v100, 0x3fb8aa3b, v100
	v_exp_f32_e32 v100, v100
	global_store_short v[128:129], v0, off offset:1024
	s_waitcnt vmcnt(31)
	v_lshlrev_b32_e32 v0, 16, v157
	v_mul_f32_e32 v0, 0x3db504f3, v0
	v_mul_f32_e32 v0, v1, v0
	s_waitcnt vmcnt(30)
	v_lshlrev_b32_e32 v1, 16, v158
	v_mul_f32_e32 v1, v100, v1
	v_cvt_pk_bf16_f32 v0, v0, s0
	global_store_short v[130:131], v0, off
	v_cvt_pk_bf16_f32 v0, v1, s0
	v_sub_f32_e32 v1, v111, v48
	v_mul_f32_e32 v1, 0x3fb8aa3b, v1
	v_sub_f32_e32 v100, v48, v111
	v_exp_f32_e32 v1, v1
	v_mul_f32_e32 v100, 0x3fb8aa3b, v100
	v_exp_f32_e32 v100, v100
	global_store_short v[130:131], v0, off offset:1024
	s_waitcnt vmcnt(31)
	v_lshlrev_b32_e32 v0, 16, v159
	v_mul_f32_e32 v0, 0x3db504f3, v0
	v_mul_f32_e32 v0, v1, v0
	s_waitcnt vmcnt(30)
	v_lshlrev_b32_e32 v1, 16, v160
	v_mul_f32_e32 v1, v100, v1
	v_cvt_pk_bf16_f32 v0, v0, s0
	global_store_short v[132:133], v0, off
	v_cvt_pk_bf16_f32 v0, v1, s0
	v_sub_f32_e32 v1, v112, v48
	v_mul_f32_e32 v1, 0x3fb8aa3b, v1
	v_sub_f32_e32 v100, v48, v112
	v_exp_f32_e32 v1, v1
	v_mul_f32_e32 v100, 0x3fb8aa3b, v100
	v_exp_f32_e32 v100, v100
	global_store_short v[132:133], v0, off offset:1024
	s_waitcnt vmcnt(31)
	v_lshlrev_b32_e32 v0, 16, v161
	v_mul_f32_e32 v0, 0x3db504f3, v0
	v_mul_f32_e32 v0, v1, v0
	s_waitcnt vmcnt(30)
	v_lshlrev_b32_e32 v1, 16, v162
	v_mul_f32_e32 v1, v100, v1
	v_cvt_pk_bf16_f32 v0, v0, s0
	global_store_short v[134:135], v0, off
	v_cvt_pk_bf16_f32 v0, v1, s0
	v_sub_f32_e32 v1, v114, v48
	v_mul_f32_e32 v1, 0x3fb8aa3b, v1
	v_sub_f32_e32 v100, v48, v114
	v_exp_f32_e32 v1, v1
	v_mul_f32_e32 v100, 0x3fb8aa3b, v100
	v_exp_f32_e32 v100, v100
	global_store_short v[134:135], v0, off offset:1024
	s_waitcnt vmcnt(31)
	v_lshlrev_b32_e32 v0, 16, v163
	v_mul_f32_e32 v0, 0x3db504f3, v0
	v_mul_f32_e32 v0, v1, v0
	s_waitcnt vmcnt(30)
	v_lshlrev_b32_e32 v1, 16, v164
	v_mul_f32_e32 v1, v100, v1
	v_cvt_pk_bf16_f32 v0, v0, s0
	global_store_short v[136:137], v0, off
	v_cvt_pk_bf16_f32 v0, v1, s0
	v_sub_f32_e32 v1, v116, v48
	v_mul_f32_e32 v1, 0x3fb8aa3b, v1
	v_sub_f32_e32 v100, v48, v116
	v_exp_f32_e32 v1, v1
	v_mul_f32_e32 v100, 0x3fb8aa3b, v100
	v_exp_f32_e32 v100, v100
	global_store_short v[136:137], v0, off offset:1024
	s_waitcnt vmcnt(31)
	v_lshlrev_b32_e32 v0, 16, v165
	v_mul_f32_e32 v0, 0x3db504f3, v0
	v_mul_f32_e32 v0, v1, v0
	s_waitcnt vmcnt(30)
	v_lshlrev_b32_e32 v1, 16, v166
	v_mul_f32_e32 v1, v100, v1
	v_cvt_pk_bf16_f32 v0, v0, s0
	global_store_short v[138:139], v0, off
	v_cvt_pk_bf16_f32 v0, v1, s0
	v_sub_f32_e32 v1, v117, v48
	v_mul_f32_e32 v1, 0x3fb8aa3b, v1
	v_sub_f32_e32 v100, v48, v117
	v_exp_f32_e32 v1, v1
	v_mul_f32_e32 v100, 0x3fb8aa3b, v100
	v_exp_f32_e32 v100, v100
	global_store_short v[138:139], v0, off offset:1024
	s_waitcnt vmcnt(31)
	v_lshlrev_b32_e32 v0, 16, v167
	v_mul_f32_e32 v0, 0x3db504f3, v0
	v_mul_f32_e32 v0, v1, v0
	s_waitcnt vmcnt(30)
	v_lshlrev_b32_e32 v1, 16, v168
	v_mul_f32_e32 v1, v100, v1
	v_cvt_pk_bf16_f32 v0, v0, s0
	global_store_short v[140:141], v0, off
	v_cvt_pk_bf16_f32 v0, v1, s0
	v_sub_f32_e32 v1, v118, v48
	v_mul_f32_e32 v1, 0x3fb8aa3b, v1
	v_sub_f32_e32 v100, v48, v118
	v_exp_f32_e32 v1, v1
	v_mul_f32_e32 v100, 0x3fb8aa3b, v100
	v_exp_f32_e32 v100, v100
	global_store_short v[140:141], v0, off offset:1024
	s_waitcnt vmcnt(31)
	v_lshlrev_b32_e32 v0, 16, v169
	v_mul_f32_e32 v0, 0x3db504f3, v0
	v_mul_f32_e32 v0, v1, v0
	s_waitcnt vmcnt(30)
	v_lshlrev_b32_e32 v1, 16, v170
	v_mul_f32_e32 v1, v100, v1
	v_cvt_pk_bf16_f32 v0, v0, s0
	global_store_short v[142:143], v0, off
	v_cvt_pk_bf16_f32 v0, v1, s0
	v_sub_f32_e32 v1, v119, v48
	v_mul_f32_e32 v1, 0x3fb8aa3b, v1
	v_sub_f32_e32 v100, v48, v119
	v_exp_f32_e32 v1, v1
	v_mul_f32_e32 v100, 0x3fb8aa3b, v100
	v_exp_f32_e32 v100, v100
	global_store_short v[142:143], v0, off offset:1024
	s_waitcnt vmcnt(31)
	v_lshlrev_b32_e32 v0, 16, v171
	v_mul_f32_e32 v0, 0x3db504f3, v0
	v_mul_f32_e32 v0, v1, v0
	s_waitcnt vmcnt(30)
	v_lshlrev_b32_e32 v1, 16, v172
	v_mul_f32_e32 v1, v100, v1
	v_cvt_pk_bf16_f32 v0, v0, s0
	global_store_short v[144:145], v0, off
	v_cvt_pk_bf16_f32 v0, v1, s0
	v_sub_f32_e32 v1, v120, v48
	v_mul_f32_e32 v1, 0x3fb8aa3b, v1
	v_sub_f32_e32 v100, v48, v120
	v_exp_f32_e32 v1, v1
	v_mul_f32_e32 v100, 0x3fb8aa3b, v100
	v_exp_f32_e32 v100, v100
	global_store_short v[144:145], v0, off offset:1024
	s_waitcnt vmcnt(31)
	v_lshlrev_b32_e32 v0, 16, v173
	v_mul_f32_e32 v0, 0x3db504f3, v0
	v_mul_f32_e32 v0, v1, v0
	s_waitcnt vmcnt(30)
	v_lshlrev_b32_e32 v1, 16, v174
	v_mul_f32_e32 v1, v100, v1
	v_cvt_pk_bf16_f32 v0, v0, s0
	global_store_short v[146:147], v0, off
	v_cvt_pk_bf16_f32 v0, v1, s0
	v_sub_f32_e32 v1, v121, v48
	v_mul_f32_e32 v1, 0x3fb8aa3b, v1
	v_sub_f32_e32 v100, v48, v121
	v_exp_f32_e32 v1, v1
	v_mul_f32_e32 v100, 0x3fb8aa3b, v100
	v_exp_f32_e32 v100, v100
	global_store_short v[146:147], v0, off offset:1024
	s_waitcnt vmcnt(31)
; __device__ __forceinline__ unsigned cvtpk(float lo, float hi) { f32x2 v = {lo, hi}; bf16x2_t b = __builtin_convertvector(v, bf16x2_t); return __builtin_bit_cast(unsigned, b); }
; __device__ __forceinline__ float fexp(float x) { return __builtin_amdgcn_exp2f(x * 1.44269504089f); }
; __device__ __forceinline__ void phase_qkrope_gla_prep(const Params& p, LAS unsigned char* lds, int wave, int lane) {
;     ...
;             for (int tb = 0; tb < 4; ++tb) {
;                 unsigned short qv[16], kv[16];
; #pragma unroll
;                 for (int t = 0; t < 16; ++t) { const size_t ro = (size_t)(m0 + 16 * tb + t) * ZP + d; qv[t] = Z[ro + C_QG]; kv[t] = Z[ro + C_KG]; }
; #pragma unroll
;                 for (int t = 0; t < 16; ++t) { const size_t ro = (size_t)(m0 + 16 * tb + t) * ZP + d; const float bb = bl[16 * tb + t];
;                     const float qs = bf2f(qv[t]) * 0.08838834764831845f * fexp(bb - bref), ks = bf2f(kv[t]) * fexp(bref - bb);
;                     Z[ro + C_QG] = (bf16_t)(cvtpk(qs, 0.f) & 0xffffu); Z[ro + C_KG] = (bf16_t)(cvtpk(ks, 0.f) & 0xffffu); }
	v_lshlrev_b32_e32 v0, 16, v175
	v_mul_f32_e32 v0, 0x3db504f3, v0
	v_mul_f32_e32 v0, v1, v0
	s_waitcnt vmcnt(30)
	v_lshlrev_b32_e32 v1, 16, v176
	v_mul_f32_e32 v1, v100, v1
	v_cvt_pk_bf16_f32 v0, v0, s0
	global_store_short v[148:149], v0, off
	v_cvt_pk_bf16_f32 v0, v1, s0
	v_sub_f32_e32 v1, v122, v48
	v_mul_f32_e32 v1, 0x3fb8aa3b, v1
	v_sub_f32_e32 v100, v48, v122
	v_exp_f32_e32 v1, v1
	v_mul_f32_e32 v100, 0x3fb8aa3b, v100
	v_exp_f32_e32 v100, v100
	global_store_short v[148:149], v0, off offset:1024
	s_waitcnt vmcnt(31)
	v_lshlrev_b32_e32 v0, 16, v177
	v_mul_f32_e32 v0, 0x3db504f3, v0
	v_mul_f32_e32 v0, v1, v0
	s_waitcnt vmcnt(30)
	v_lshlrev_b32_e32 v1, 16, v178
	v_mul_f32_e32 v1, v100, v1
	v_cvt_pk_bf16_f32 v0, v0, s0
	global_store_short v[46:47], v0, off
	v_cvt_pk_bf16_f32 v0, v1, s0
	v_sub_f32_e32 v1, v123, v48
	global_store_short v[46:47], v0, off offset:1024
	v_mul_f32_e32 v1, 0x3fb8aa3b, v1
	v_sub_f32_e32 v46, v48, v123
	v_exp_f32_e32 v1, v1
	v_mul_f32_e32 v46, 0x3fb8aa3b, v46
	v_exp_f32_e32 v46, v46
	s_waitcnt vmcnt(31)
	v_lshlrev_b32_e32 v0, 16, v179
	v_mul_f32_e32 v0, 0x3db504f3, v0
	v_mul_f32_e32 v0, v1, v0
	s_waitcnt vmcnt(30)
	v_lshlrev_b32_e32 v1, 16, v180
	v_mul_f32_e32 v1, v46, v1
	v_mad_i64_i32 v[46:47], s[4:5], s4, v61, v[8:9]
	global_load_ushort v100, v[46:47], off
	s_sub_i32 s4, s0, 46
	v_mad_i64_i32 v[116:117], s[4:5], s4, v61, v[8:9]
	s_sub_i32 s4, s0, 45
	s_nop 0
	v_mad_i64_i32 v[118:119], s[4:5], s4, v61, v[8:9]
	s_sub_i32 s4, s0, 44
	s_nop 0
	v_mad_i64_i32 v[120:121], s[4:5], s4, v61, v[8:9]
	s_sub_i32 s4, s0, 43
	s_nop 0
	v_mad_i64_i32 v[122:123], s[4:5], s4, v61, v[8:9]
	s_sub_i32 s4, s0, 42
	s_nop 0
	v_mad_i64_i32 v[124:125], s[4:5], s4, v61, v[8:9]
	s_sub_i32 s4, s0, 41
	s_nop 0
	v_mad_i64_i32 v[126:127], s[4:5], s4, v61, v[8:9]
	s_sub_i32 s4, s0, 40
	s_nop 0
	v_mad_i64_i32 v[128:129], s[4:5], s4, v61, v[8:9]
	s_sub_i32 s4, s0, 39
	s_nop 0
	v_mad_i64_i32 v[130:131], s[4:5], s4, v61, v[8:9]
	s_sub_i32 s4, s0, 38
	s_nop 0
	v_mad_i64_i32 v[132:133], s[4:5], s4, v61, v[8:9]
	s_sub_i32 s4, s0, 37
	s_nop 0
	v_mad_i64_i32 v[134:135], s[4:5], s4, v61, v[8:9]
	s_sub_i32 s4, s0, 36
	s_nop 0
	v_mad_i64_i32 v[136:137], s[4:5], s4, v61, v[8:9]
	s_sub_i32 s4, s0, 35
	s_nop 0
	v_mad_i64_i32 v[138:139], s[4:5], s4, v61, v[8:9]
	s_sub_i32 s4, s0, 34
	v_cvt_pk_bf16_f32 v0, v0, s0
	v_mad_i64_i32 v[140:141], s[4:5], s4, v61, v[8:9]
	global_store_short v[2:3], v0, off
	v_cvt_pk_bf16_f32 v0, v1, s0
	s_sub_i32 s4, s0, 33
	global_store_short v[2:3], v0, off offset:1024
	v_mad_i64_i32 v[2:3], s[4:5], s4, v61, v[8:9]
	s_sub_i32 s4, s0, 32
	s_nop 0
	v_mad_i64_i32 v[0:1], s[4:5], s4, v61, v[8:9]
	s_sub_i32 s4, s0, 31
	s_waitcnt vmcnt(2)
	v_lshlrev_b32_e32 v100, 16, v100
	v_mul_f32_e32 v100, 0x3db504f3, v100
	v_mul_f32_e32 v100, v102, v100
	global_load_ushort v102, v[46:47], off offset:1024
	v_cvt_pk_bf16_f32 v100, v100, s0
	s_waitcnt vmcnt(0)
	v_lshlrev_b32_e32 v102, 16, v102
	v_mul_f32_e32 v81, v81, v102
	global_load_ushort v102, v[116:117], off
	global_load_ushort v104, v[116:117], off offset:1024
	global_load_ushort v107, v[118:119], off
	global_load_ushort v109, v[118:119], off offset:1024
	global_load_ushort v111, v[120:121], off
	global_load_ushort v112, v[120:121], off offset:1024
	global_load_ushort v114, v[122:123], off
	global_load_ushort v142, v[122:123], off offset:1024
	global_load_ushort v143, v[124:125], off
	global_load_ushort v144, v[124:125], off offset:1024
	global_load_ushort v145, v[126:127], off
	global_load_ushort v146, v[126:127], off offset:1024
	global_load_ushort v147, v[128:129], off
	global_load_ushort v148, v[128:129], off offset:1024
	global_load_ushort v149, v[130:131], off
	global_load_ushort v150, v[130:131], off offset:1024
	global_load_ushort v151, v[132:133], off
	global_load_ushort v152, v[132:133], off offset:1024
	global_load_ushort v153, v[134:135], off
	global_load_ushort v154, v[134:135], off offset:1024
	global_load_ushort v155, v[136:137], off
	global_load_ushort v156, v[136:137], off offset:1024
	global_load_ushort v157, v[138:139], off
	global_load_ushort v158, v[138:139], off offset:1024
	global_load_ushort v159, v[140:141], off
	global_load_ushort v160, v[140:141], off offset:1024
	global_load_ushort v161, v[2:3], off
	global_load_ushort v162, v[2:3], off offset:1024
	global_load_ushort v163, v[0:1], off
	global_load_ushort v164, v[0:1], off offset:1024
	v_cvt_pk_bf16_f32 v81, v81, s0
	global_store_short v[46:47], v100, off
	global_store_short v[46:47], v81, off offset:1024
	v_sub_f32_e32 v47, v82, v48
	v_mul_f32_e32 v47, 0x3fb8aa3b, v47
	v_sub_f32_e32 v81, v48, v82
	v_exp_f32_e32 v47, v47
	v_mul_f32_e32 v81, 0x3fb8aa3b, v81
	v_exp_f32_e32 v81, v81
	v_sub_f32_e32 v82, v68, v48
	v_mul_f32_e32 v82, 0x3fb8aa3b, v82
	v_exp_f32_e32 v82, v82
	v_sub_f32_e32 v68, v48, v68
	v_mul_f32_e32 v68, 0x3fb8aa3b, v68
	v_exp_f32_e32 v68, v68
	s_waitcnt vmcnt(31)
	v_lshlrev_b32_e32 v46, 16, v102
	v_mul_f32_e32 v46, 0x3db504f3, v46
	v_mul_f32_e32 v46, v47, v46
	s_waitcnt vmcnt(30)
	v_lshlrev_b32_e32 v47, 16, v104
	v_mul_f32_e32 v47, v81, v47
	v_cvt_pk_bf16_f32 v46, v46, s0
	global_store_short v[116:117], v46, off
	v_cvt_pk_bf16_f32 v46, v47, s0
	v_sub_f32_e32 v47, v85, v48
	v_mul_f32_e32 v47, 0x3fb8aa3b, v47
	v_sub_f32_e32 v81, v48, v85
	v_exp_f32_e32 v47, v47
	v_mul_f32_e32 v81, 0x3fb8aa3b, v81
	v_exp_f32_e32 v81, v81
	global_store_short v[116:117], v46, off offset:1024
	s_waitcnt vmcnt(31)
	v_lshlrev_b32_e32 v46, 16, v107
	v_mul_f32_e32 v46, 0x3db504f3, v46
	v_mul_f32_e32 v46, v47, v46
	s_waitcnt vmcnt(30)
; __device__ __forceinline__ unsigned cvtpk(float lo, float hi) { f32x2 v = {lo, hi}; bf16x2_t b = __builtin_convertvector(v, bf16x2_t); return __builtin_bit_cast(unsigned, b); }
; __device__ __forceinline__ float fexp(float x) { return __builtin_amdgcn_exp2f(x * 1.44269504089f); }
; __device__ __forceinline__ void phase_qkrope_gla_prep(const Params& p, LAS unsigned char* lds, int wave, int lane) {
;     ...
;                 for (int t = 0; t < 16; ++t) { const size_t ro = (size_t)(m0 + 16 * tb + t) * ZP + d; const float bb = bl[16 * tb + t];
;                     const float qs = bf2f(qv[t]) * 0.08838834764831845f * fexp(bb - bref), ks = bf2f(kv[t]) * fexp(bref - bb);
;                     Z[ro + C_QG] = (bf16_t)(cvtpk(qs, 0.f) & 0xffffu); Z[ro + C_KG] = (bf16_t)(cvtpk(ks, 0.f) & 0xffffu); }
	v_lshlrev_b32_e32 v47, 16, v109
	v_mul_f32_e32 v47, v81, v47
	v_cvt_pk_bf16_f32 v46, v46, s0
	global_store_short v[118:119], v46, off
	v_cvt_pk_bf16_f32 v46, v47, s0
	v_sub_f32_e32 v47, v88, v48
	v_mul_f32_e32 v47, 0x3fb8aa3b, v47
	v_sub_f32_e32 v81, v48, v88
	v_exp_f32_e32 v47, v47
	v_mul_f32_e32 v81, 0x3fb8aa3b, v81
	v_exp_f32_e32 v81, v81
	global_store_short v[118:119], v46, off offset:1024
	s_waitcnt vmcnt(31)
	v_lshlrev_b32_e32 v46, 16, v111
	v_mul_f32_e32 v46, 0x3db504f3, v46
	v_mul_f32_e32 v46, v47, v46
	s_waitcnt vmcnt(30)
	v_lshlrev_b32_e32 v47, 16, v112
	v_mul_f32_e32 v47, v81, v47
	v_cvt_pk_bf16_f32 v46, v46, s0
	global_store_short v[120:121], v46, off
	v_cvt_pk_bf16_f32 v46, v47, s0
	v_sub_f32_e32 v47, v90, v48
	v_mul_f32_e32 v47, 0x3fb8aa3b, v47
	v_sub_f32_e32 v81, v48, v90
	v_exp_f32_e32 v47, v47
	v_mul_f32_e32 v81, 0x3fb8aa3b, v81
	v_exp_f32_e32 v81, v81
	global_store_short v[120:121], v46, off offset:1024
	s_waitcnt vmcnt(31)
	v_lshlrev_b32_e32 v46, 16, v114
	v_mul_f32_e32 v46, 0x3db504f3, v46
	v_mul_f32_e32 v46, v47, v46
	s_waitcnt vmcnt(30)
	v_lshlrev_b32_e32 v47, 16, v142
	v_mul_f32_e32 v47, v81, v47
	v_cvt_pk_bf16_f32 v46, v46, s0
	global_store_short v[122:123], v46, off
	v_cvt_pk_bf16_f32 v46, v47, s0
	v_sub_f32_e32 v47, v92, v48
	v_mul_f32_e32 v47, 0x3fb8aa3b, v47
	v_sub_f32_e32 v81, v48, v92
	v_exp_f32_e32 v47, v47
	v_mul_f32_e32 v81, 0x3fb8aa3b, v81
	v_exp_f32_e32 v81, v81
	global_store_short v[122:123], v46, off offset:1024
	s_waitcnt vmcnt(31)
	v_lshlrev_b32_e32 v46, 16, v143
	v_mul_f32_e32 v46, 0x3db504f3, v46
	v_mul_f32_e32 v46, v47, v46
	s_waitcnt vmcnt(30)
	v_lshlrev_b32_e32 v47, 16, v144
	v_mul_f32_e32 v47, v81, v47
	v_cvt_pk_bf16_f32 v46, v46, s0
	global_store_short v[124:125], v46, off
	v_cvt_pk_bf16_f32 v46, v47, s0
	v_sub_f32_e32 v47, v94, v48
	v_mul_f32_e32 v47, 0x3fb8aa3b, v47
	v_sub_f32_e32 v81, v48, v94
	v_exp_f32_e32 v47, v47
	v_mul_f32_e32 v81, 0x3fb8aa3b, v81
	v_exp_f32_e32 v81, v81
	global_store_short v[124:125], v46, off offset:1024
	s_waitcnt vmcnt(31)
	v_lshlrev_b32_e32 v46, 16, v145
	v_mul_f32_e32 v46, 0x3db504f3, v46
	v_mul_f32_e32 v46, v47, v46
	s_waitcnt vmcnt(30)
	v_lshlrev_b32_e32 v47, 16, v146
	v_mul_f32_e32 v47, v81, v47
	v_cvt_pk_bf16_f32 v46, v46, s0
	global_store_short v[126:127], v46, off
	v_cvt_pk_bf16_f32 v46, v47, s0
	v_sub_f32_e32 v47, v96, v48
	v_mul_f32_e32 v47, 0x3fb8aa3b, v47
	v_sub_f32_e32 v81, v48, v96
	v_exp_f32_e32 v47, v47
	v_mul_f32_e32 v81, 0x3fb8aa3b, v81
	v_exp_f32_e32 v81, v81
	global_store_short v[126:127], v46, off offset:1024
	s_waitcnt vmcnt(31)
	v_lshlrev_b32_e32 v46, 16, v147
	v_mul_f32_e32 v46, 0x3db504f3, v46
	v_mul_f32_e32 v46, v47, v46
	s_waitcnt vmcnt(30)
	v_lshlrev_b32_e32 v47, 16, v148
	v_mul_f32_e32 v47, v81, v47
	v_cvt_pk_bf16_f32 v46, v46, s0
	global_store_short v[128:129], v46, off
	v_cvt_pk_bf16_f32 v46, v47, s0
	v_sub_f32_e32 v47, v98, v48
	v_mul_f32_e32 v47, 0x3fb8aa3b, v47
	v_sub_f32_e32 v81, v48, v98
	v_exp_f32_e32 v47, v47
	v_mul_f32_e32 v81, 0x3fb8aa3b, v81
	v_exp_f32_e32 v81, v81
	global_store_short v[128:129], v46, off offset:1024
	s_waitcnt vmcnt(31)
	v_lshlrev_b32_e32 v46, 16, v149
	v_mul_f32_e32 v46, 0x3db504f3, v46
	v_mul_f32_e32 v46, v47, v46
	s_waitcnt vmcnt(30)
	v_lshlrev_b32_e32 v47, 16, v150
	v_mul_f32_e32 v47, v81, v47
	v_cvt_pk_bf16_f32 v46, v46, s0
	global_store_short v[130:131], v46, off
	v_cvt_pk_bf16_f32 v46, v47, s0
	v_sub_f32_e32 v47, v101, v48
	v_mul_f32_e32 v47, 0x3fb8aa3b, v47
	v_sub_f32_e32 v81, v48, v101
	v_exp_f32_e32 v47, v47
	v_mul_f32_e32 v81, 0x3fb8aa3b, v81
	v_exp_f32_e32 v81, v81
	global_store_short v[130:131], v46, off offset:1024
	s_waitcnt vmcnt(31)
	v_lshlrev_b32_e32 v46, 16, v151
	v_mul_f32_e32 v46, 0x3db504f3, v46
	v_mul_f32_e32 v46, v47, v46
	s_waitcnt vmcnt(30)
	v_lshlrev_b32_e32 v47, 16, v152
	v_mul_f32_e32 v47, v81, v47
	v_cvt_pk_bf16_f32 v46, v46, s0
	global_store_short v[132:133], v46, off
	v_cvt_pk_bf16_f32 v46, v47, s0
	v_sub_f32_e32 v47, v105, v48
	v_mul_f32_e32 v47, 0x3fb8aa3b, v47
	v_sub_f32_e32 v81, v48, v105
	v_exp_f32_e32 v47, v47
	v_mul_f32_e32 v81, 0x3fb8aa3b, v81
	v_exp_f32_e32 v81, v81
	global_store_short v[132:133], v46, off offset:1024
	s_waitcnt vmcnt(31)
	v_lshlrev_b32_e32 v46, 16, v153
	v_mul_f32_e32 v46, 0x3db504f3, v46
	v_mul_f32_e32 v46, v47, v46
	s_waitcnt vmcnt(30)
	v_lshlrev_b32_e32 v47, 16, v154
	v_mul_f32_e32 v47, v81, v47
	v_cvt_pk_bf16_f32 v46, v46, s0
	global_store_short v[134:135], v46, off
	v_cvt_pk_bf16_f32 v46, v47, s0
	v_sub_f32_e32 v47, v108, v48
	v_mul_f32_e32 v47, 0x3fb8aa3b, v47
	v_sub_f32_e32 v81, v48, v108
	v_exp_f32_e32 v47, v47
	v_mul_f32_e32 v81, 0x3fb8aa3b, v81
	v_exp_f32_e32 v81, v81
	global_store_short v[134:135], v46, off offset:1024
	s_waitcnt vmcnt(31)
	v_lshlrev_b32_e32 v46, 16, v155
	v_mul_f32_e32 v46, 0x3db504f3, v46
	v_mul_f32_e32 v46, v47, v46
	s_waitcnt vmcnt(30)
	v_lshlrev_b32_e32 v47, 16, v156
	v_mul_f32_e32 v47, v81, v47
	v_cvt_pk_bf16_f32 v46, v46, s0
	global_store_short v[136:137], v46, off
	v_cvt_pk_bf16_f32 v46, v47, s0
	v_sub_f32_e32 v47, v110, v48
	v_mul_f32_e32 v47, 0x3fb8aa3b, v47
	v_sub_f32_e32 v81, v48, v110
	v_exp_f32_e32 v47, v47
	v_mul_f32_e32 v81, 0x3fb8aa3b, v81
	v_exp_f32_e32 v81, v81
	global_store_short v[136:137], v46, off offset:1024
	s_waitcnt vmcnt(31)
	v_lshlrev_b32_e32 v46, 16, v157
	v_mul_f32_e32 v46, 0x3db504f3, v46
	v_mul_f32_e32 v46, v47, v46
	s_waitcnt vmcnt(30)
	v_lshlrev_b32_e32 v47, 16, v158
	v_mul_f32_e32 v47, v81, v47
	v_cvt_pk_bf16_f32 v46, v46, s0
	global_store_short v[138:139], v46, off
	v_cvt_pk_bf16_f32 v46, v47, s0
	v_sub_f32_e32 v47, v113, v48
	v_mul_f32_e32 v47, 0x3fb8aa3b, v47
	v_sub_f32_e32 v81, v48, v113
	v_exp_f32_e32 v47, v47
	v_mul_f32_e32 v81, 0x3fb8aa3b, v81
	v_exp_f32_e32 v81, v81
	global_store_short v[138:139], v46, off offset:1024
	s_waitcnt vmcnt(31)
; __device__ __forceinline__ unsigned cvtpk(float lo, float hi) { f32x2 v = {lo, hi}; bf16x2_t b = __builtin_convertvector(v, bf16x2_t); return __builtin_bit_cast(unsigned, b); }
; __device__ __forceinline__ float fexp(float x) { return __builtin_amdgcn_exp2f(x * 1.44269504089f); }
; __device__ __forceinline__ void phase_qkrope_gla_prep(const Params& p, LAS unsigned char* lds, int wave, int lane) {
;     ...
;             for (int tb = 0; tb < 4; ++tb) {
;                 unsigned short qv[16], kv[16];
; #pragma unroll
;                 for (int t = 0; t < 16; ++t) { const size_t ro = (size_t)(m0 + 16 * tb + t) * ZP + d; qv[t] = Z[ro + C_QG]; kv[t] = Z[ro + C_KG]; }
; #pragma unroll
;                 for (int t = 0; t < 16; ++t) { const size_t ro = (size_t)(m0 + 16 * tb + t) * ZP + d; const float bb = bl[16 * tb + t];
;                     const float qs = bf2f(qv[t]) * 0.08838834764831845f * fexp(bb - bref), ks = bf2f(kv[t]) * fexp(bref - bb);
;                     Z[ro + C_QG] = (bf16_t)(cvtpk(qs, 0.f) & 0xffffu); Z[ro + C_KG] = (bf16_t)(cvtpk(ks, 0.f) & 0xffffu); }
	v_lshlrev_b32_e32 v46, 16, v159
	v_mul_f32_e32 v46, 0x3db504f3, v46
	v_mul_f32_e32 v46, v47, v46
	s_waitcnt vmcnt(30)
	v_lshlrev_b32_e32 v47, 16, v160
	v_mul_f32_e32 v47, v81, v47
	v_cvt_pk_bf16_f32 v46, v46, s0
	global_store_short v[140:141], v46, off
	v_cvt_pk_bf16_f32 v46, v47, s0
	v_sub_f32_e32 v47, v115, v48
	v_mul_f32_e32 v47, 0x3fb8aa3b, v47
	v_sub_f32_e32 v81, v48, v115
	v_exp_f32_e32 v47, v47
	v_mul_f32_e32 v81, 0x3fb8aa3b, v81
	v_exp_f32_e32 v81, v81
	global_store_short v[140:141], v46, off offset:1024
	s_waitcnt vmcnt(31)
	v_lshlrev_b32_e32 v46, 16, v161
	v_mul_f32_e32 v46, 0x3db504f3, v46
	v_mul_f32_e32 v46, v47, v46
	s_waitcnt vmcnt(30)
	v_lshlrev_b32_e32 v47, 16, v162
	v_mul_f32_e32 v47, v81, v47
	v_cvt_pk_bf16_f32 v46, v46, s0
	global_store_short v[2:3], v46, off
	v_cvt_pk_bf16_f32 v46, v47, s0
	global_store_short v[2:3], v46, off offset:1024
	v_sub_f32_e32 v3, v48, v48
	v_mul_f32_e32 v3, 0x3fb8aa3b, v3
	v_exp_f32_e32 v3, v3
	s_waitcnt vmcnt(31)
	v_lshlrev_b32_e32 v2, 16, v163
	v_mul_f32_e32 v2, 0x3db504f3, v2
	s_waitcnt vmcnt(30)
	v_lshlrev_b32_e32 v46, 16, v164
	v_mul_f32_e32 v2, v3, v2
	v_mul_f32_e32 v3, v3, v46
	v_mad_i64_i32 v[46:47], s[4:5], s4, v61, v[8:9]
	global_load_ushort v81, v[46:47], off
	s_sub_i32 s4, s0, 30
	v_mad_i64_i32 v[100:101], s[4:5], s4, v61, v[8:9]
	s_sub_i32 s4, s0, 29
	s_nop 0
	v_mad_i64_i32 v[104:105], s[4:5], s4, v61, v[8:9]
	s_sub_i32 s4, s0, 28
	s_nop 0
	v_mad_i64_i32 v[108:109], s[4:5], s4, v61, v[8:9]
	s_sub_i32 s4, s0, 27
	s_nop 0
	v_mad_i64_i32 v[110:111], s[4:5], s4, v61, v[8:9]
	s_sub_i32 s4, s0, 26
	s_nop 0
	v_mad_i64_i32 v[112:113], s[4:5], s4, v61, v[8:9]
	s_sub_i32 s4, s0, 25
	s_nop 0
	v_mad_i64_i32 v[114:115], s[4:5], s4, v61, v[8:9]
	s_sub_i32 s4, s0, 24
	s_nop 0
	v_mad_i64_i32 v[116:117], s[4:5], s4, v61, v[8:9]
	s_sub_i32 s4, s0, 23
	s_nop 0
	v_mad_i64_i32 v[118:119], s[4:5], s4, v61, v[8:9]
	s_sub_i32 s4, s0, 22
	s_nop 0
	v_mad_i64_i32 v[120:121], s[4:5], s4, v61, v[8:9]
	s_sub_i32 s4, s0, 21
	s_nop 0
	v_mad_i64_i32 v[122:123], s[4:5], s4, v61, v[8:9]
	s_sub_i32 s4, s0, 20
	s_nop 0
	v_mad_i64_i32 v[124:125], s[4:5], s4, v61, v[8:9]
	s_sub_i32 s4, s0, 19
	s_nop 0
	v_mad_i64_i32 v[126:127], s[4:5], s4, v61, v[8:9]
	s_sub_i32 s4, s0, 18
	v_cvt_pk_bf16_f32 v2, v2, s0
	v_mad_i64_i32 v[128:129], s[4:5], s4, v61, v[8:9]
	global_store_short v[0:1], v2, off
	v_cvt_pk_bf16_f32 v2, v3, s0
	s_sub_i32 s4, s0, 17
	global_store_short v[0:1], v2, off offset:1024
	v_mad_i64_i32 v[2:3], s[4:5], s4, v61, v[8:9]
	s_add_i32 s4, s0, -16
	s_nop 0
	v_mad_i64_i32 v[0:1], s[4:5], s4, v61, v[8:9]
	s_add_i32 s4, s0, -15
	s_waitcnt vmcnt(2)
	v_lshlrev_b32_e32 v81, 16, v81
	v_mul_f32_e32 v81, 0x3db504f3, v81
	v_mul_f32_e32 v81, v82, v81
	global_load_ushort v82, v[46:47], off offset:1024
	v_cvt_pk_bf16_f32 v81, v81, s0
	s_waitcnt vmcnt(0)
	v_lshlrev_b32_e32 v82, 16, v82
	v_mul_f32_e32 v68, v68, v82
	global_load_ushort v82, v[100:101], off
	global_load_ushort v85, v[100:101], off offset:1024
	global_load_ushort v88, v[104:105], off
	global_load_ushort v90, v[104:105], off offset:1024
	global_load_ushort v92, v[108:109], off
	global_load_ushort v94, v[108:109], off offset:1024
	global_load_ushort v96, v[110:111], off
	global_load_ushort v98, v[110:111], off offset:1024
	global_load_ushort v102, v[112:113], off
	global_load_ushort v107, v[112:113], off offset:1024
	global_load_ushort v130, v[114:115], off
	global_load_ushort v131, v[114:115], off offset:1024
	global_load_ushort v132, v[116:117], off
	global_load_ushort v133, v[116:117], off offset:1024
	global_load_ushort v134, v[118:119], off
	global_load_ushort v135, v[118:119], off offset:1024
	global_load_ushort v136, v[120:121], off
	global_load_ushort v137, v[120:121], off offset:1024
	global_load_ushort v138, v[122:123], off
	global_load_ushort v139, v[122:123], off offset:1024
	global_load_ushort v140, v[124:125], off
	global_load_ushort v141, v[124:125], off offset:1024
	global_load_ushort v142, v[126:127], off
	global_load_ushort v143, v[126:127], off offset:1024
	global_load_ushort v144, v[128:129], off
	global_load_ushort v145, v[128:129], off offset:1024
	global_load_ushort v146, v[2:3], off
	global_load_ushort v147, v[2:3], off offset:1024
	global_load_ushort v148, v[0:1], off
	global_load_ushort v149, v[0:1], off offset:1024
	v_cvt_pk_bf16_f32 v68, v68, s0
	global_store_short v[46:47], v81, off
	global_store_short v[46:47], v68, off offset:1024
	v_sub_f32_e32 v47, v70, v48
	v_mul_f32_e32 v47, 0x3fb8aa3b, v47
	v_sub_f32_e32 v68, v48, v70
	v_exp_f32_e32 v47, v47
	v_mul_f32_e32 v68, 0x3fb8aa3b, v68
	v_exp_f32_e32 v68, v68
	v_sub_f32_e32 v70, v49, v48
	v_mul_f32_e32 v70, 0x3fb8aa3b, v70
	v_exp_f32_e32 v70, v70
	v_sub_f32_e32 v49, v48, v49
	v_mul_f32_e32 v49, 0x3fb8aa3b, v49
	v_exp_f32_e32 v49, v49
	s_waitcnt vmcnt(31)
	v_lshlrev_b32_e32 v46, 16, v82
	v_mul_f32_e32 v46, 0x3db504f3, v46
	v_mul_f32_e32 v46, v47, v46
	s_waitcnt vmcnt(30)
	v_lshlrev_b32_e32 v47, 16, v85
	v_mul_f32_e32 v47, v68, v47
	v_cvt_pk_bf16_f32 v46, v46, s0
	global_store_short v[100:101], v46, off
	v_cvt_pk_bf16_f32 v46, v47, s0
	v_sub_f32_e32 v47, v72, v48
	v_mul_f32_e32 v47, 0x3fb8aa3b, v47
	v_sub_f32_e32 v68, v48, v72
	v_exp_f32_e32 v47, v47
	v_mul_f32_e32 v68, 0x3fb8aa3b, v68
	v_exp_f32_e32 v68, v68
	global_store_short v[100:101], v46, off offset:1024
	s_waitcnt vmcnt(31)
	v_lshlrev_b32_e32 v46, 16, v88
	v_mul_f32_e32 v46, 0x3db504f3, v46
	v_mul_f32_e32 v46, v47, v46
	s_waitcnt vmcnt(30)
; __device__ __forceinline__ unsigned cvtpk(float lo, float hi) { f32x2 v = {lo, hi}; bf16x2_t b = __builtin_convertvector(v, bf16x2_t); return __builtin_bit_cast(unsigned, b); }
; __device__ __forceinline__ float fexp(float x) { return __builtin_amdgcn_exp2f(x * 1.44269504089f); }
; __device__ __forceinline__ void phase_qkrope_gla_prep(const Params& p, LAS unsigned char* lds, int wave, int lane) {
;     ...
;                 for (int t = 0; t < 16; ++t) { const size_t ro = (size_t)(m0 + 16 * tb + t) * ZP + d; const float bb = bl[16 * tb + t];
;                     const float qs = bf2f(qv[t]) * 0.08838834764831845f * fexp(bb - bref), ks = bf2f(kv[t]) * fexp(bref - bb);
;                     Z[ro + C_QG] = (bf16_t)(cvtpk(qs, 0.f) & 0xffffu); Z[ro + C_KG] = (bf16_t)(cvtpk(ks, 0.f) & 0xffffu); }
	v_lshlrev_b32_e32 v47, 16, v90
	v_mul_f32_e32 v47, v68, v47
	v_cvt_pk_bf16_f32 v46, v46, s0
	global_store_short v[104:105], v46, off
	v_cvt_pk_bf16_f32 v46, v47, s0
	v_sub_f32_e32 v47, v74, v48
	v_mul_f32_e32 v47, 0x3fb8aa3b, v47
	v_sub_f32_e32 v68, v48, v74
	v_exp_f32_e32 v47, v47
	v_mul_f32_e32 v68, 0x3fb8aa3b, v68
	v_exp_f32_e32 v68, v68
	global_store_short v[104:105], v46, off offset:1024
	s_waitcnt vmcnt(31)
	v_lshlrev_b32_e32 v46, 16, v92
	v_mul_f32_e32 v46, 0x3db504f3, v46
	v_mul_f32_e32 v46, v47, v46
	s_waitcnt vmcnt(30)
	v_lshlrev_b32_e32 v47, 16, v94
	v_mul_f32_e32 v47, v68, v47
	v_cvt_pk_bf16_f32 v46, v46, s0
	global_store_short v[108:109], v46, off
	v_cvt_pk_bf16_f32 v46, v47, s0
	v_sub_f32_e32 v47, v77, v48
	v_mul_f32_e32 v47, 0x3fb8aa3b, v47
	v_sub_f32_e32 v68, v48, v77
	v_exp_f32_e32 v47, v47
	v_mul_f32_e32 v68, 0x3fb8aa3b, v68
	v_exp_f32_e32 v68, v68
	global_store_short v[108:109], v46, off offset:1024
	s_waitcnt vmcnt(31)
	v_lshlrev_b32_e32 v46, 16, v96
	v_mul_f32_e32 v46, 0x3db504f3, v46
	v_mul_f32_e32 v46, v47, v46
	s_waitcnt vmcnt(30)
	v_lshlrev_b32_e32 v47, 16, v98
	v_mul_f32_e32 v47, v68, v47
	v_cvt_pk_bf16_f32 v46, v46, s0
	global_store_short v[110:111], v46, off
	v_cvt_pk_bf16_f32 v46, v47, s0
	v_sub_f32_e32 v47, v79, v48
	v_mul_f32_e32 v47, 0x3fb8aa3b, v47
	v_sub_f32_e32 v68, v48, v79
	v_exp_f32_e32 v47, v47
	v_mul_f32_e32 v68, 0x3fb8aa3b, v68
	v_exp_f32_e32 v68, v68
	global_store_short v[110:111], v46, off offset:1024
	s_waitcnt vmcnt(31)
	v_lshlrev_b32_e32 v46, 16, v102
	v_mul_f32_e32 v46, 0x3db504f3, v46
	v_mul_f32_e32 v46, v47, v46
	s_waitcnt vmcnt(30)
	v_lshlrev_b32_e32 v47, 16, v107
	v_mul_f32_e32 v47, v68, v47
	v_cvt_pk_bf16_f32 v46, v46, s0
	global_store_short v[112:113], v46, off
	v_cvt_pk_bf16_f32 v46, v47, s0
	v_sub_f32_e32 v47, v83, v48
	v_mul_f32_e32 v47, 0x3fb8aa3b, v47
	v_sub_f32_e32 v68, v48, v83
	v_exp_f32_e32 v47, v47
	v_mul_f32_e32 v68, 0x3fb8aa3b, v68
	v_exp_f32_e32 v68, v68
	global_store_short v[112:113], v46, off offset:1024
	s_waitcnt vmcnt(31)
	v_lshlrev_b32_e32 v46, 16, v130
	v_mul_f32_e32 v46, 0x3db504f3, v46
	v_mul_f32_e32 v46, v47, v46
	s_waitcnt vmcnt(30)
	v_lshlrev_b32_e32 v47, 16, v131
	v_mul_f32_e32 v47, v68, v47
	v_cvt_pk_bf16_f32 v46, v46, s0
	global_store_short v[114:115], v46, off
	v_cvt_pk_bf16_f32 v46, v47, s0
	v_sub_f32_e32 v47, v86, v48
	v_mul_f32_e32 v47, 0x3fb8aa3b, v47
	v_sub_f32_e32 v68, v48, v86
	v_exp_f32_e32 v47, v47
	v_mul_f32_e32 v68, 0x3fb8aa3b, v68
	v_exp_f32_e32 v68, v68
	global_store_short v[114:115], v46, off offset:1024
	s_waitcnt vmcnt(31)
	v_lshlrev_b32_e32 v46, 16, v132
	v_mul_f32_e32 v46, 0x3db504f3, v46
	v_mul_f32_e32 v46, v47, v46
	s_waitcnt vmcnt(30)
	v_lshlrev_b32_e32 v47, 16, v133
	v_mul_f32_e32 v47, v68, v47
	v_cvt_pk_bf16_f32 v46, v46, s0
	global_store_short v[116:117], v46, off
	v_cvt_pk_bf16_f32 v46, v47, s0
	v_sub_f32_e32 v47, v89, v48
	v_mul_f32_e32 v47, 0x3fb8aa3b, v47
	v_sub_f32_e32 v68, v48, v89
	v_exp_f32_e32 v47, v47
	v_mul_f32_e32 v68, 0x3fb8aa3b, v68
	v_exp_f32_e32 v68, v68
	global_store_short v[116:117], v46, off offset:1024
	s_waitcnt vmcnt(31)
	v_lshlrev_b32_e32 v46, 16, v134
	v_mul_f32_e32 v46, 0x3db504f3, v46
	v_mul_f32_e32 v46, v47, v46
	s_waitcnt vmcnt(30)
	v_lshlrev_b32_e32 v47, 16, v135
	v_mul_f32_e32 v47, v68, v47
	v_cvt_pk_bf16_f32 v46, v46, s0
	global_store_short v[118:119], v46, off
	v_cvt_pk_bf16_f32 v46, v47, s0
	v_sub_f32_e32 v47, v91, v48
	v_mul_f32_e32 v47, 0x3fb8aa3b, v47
	v_sub_f32_e32 v68, v48, v91
	v_exp_f32_e32 v47, v47
	v_mul_f32_e32 v68, 0x3fb8aa3b, v68
	v_exp_f32_e32 v68, v68
	global_store_short v[118:119], v46, off offset:1024
	s_waitcnt vmcnt(31)
	v_lshlrev_b32_e32 v46, 16, v136
	v_mul_f32_e32 v46, 0x3db504f3, v46
	v_mul_f32_e32 v46, v47, v46
	s_waitcnt vmcnt(30)
	v_lshlrev_b32_e32 v47, 16, v137
	v_mul_f32_e32 v47, v68, v47
	v_cvt_pk_bf16_f32 v46, v46, s0
	global_store_short v[120:121], v46, off
	v_cvt_pk_bf16_f32 v46, v47, s0
	v_sub_f32_e32 v47, v93, v48
	v_mul_f32_e32 v47, 0x3fb8aa3b, v47
	v_sub_f32_e32 v68, v48, v93
	v_exp_f32_e32 v47, v47
	v_mul_f32_e32 v68, 0x3fb8aa3b, v68
	v_exp_f32_e32 v68, v68
	global_store_short v[120:121], v46, off offset:1024
	s_waitcnt vmcnt(31)
	v_lshlrev_b32_e32 v46, 16, v138
	v_mul_f32_e32 v46, 0x3db504f3, v46
	v_mul_f32_e32 v46, v47, v46
	s_waitcnt vmcnt(30)
	v_lshlrev_b32_e32 v47, 16, v139
	v_mul_f32_e32 v47, v68, v47
	v_cvt_pk_bf16_f32 v46, v46, s0
	global_store_short v[122:123], v46, off
	v_cvt_pk_bf16_f32 v46, v47, s0
	v_sub_f32_e32 v47, v95, v48
	v_mul_f32_e32 v47, 0x3fb8aa3b, v47
	v_sub_f32_e32 v68, v48, v95
	v_exp_f32_e32 v47, v47
	v_mul_f32_e32 v68, 0x3fb8aa3b, v68
	v_exp_f32_e32 v68, v68
	global_store_short v[122:123], v46, off offset:1024
	s_waitcnt vmcnt(31)
	v_lshlrev_b32_e32 v46, 16, v140
	v_mul_f32_e32 v46, 0x3db504f3, v46
	v_mul_f32_e32 v46, v47, v46
	s_waitcnt vmcnt(30)
	v_lshlrev_b32_e32 v47, 16, v141
	v_mul_f32_e32 v47, v68, v47
	v_cvt_pk_bf16_f32 v46, v46, s0
	global_store_short v[124:125], v46, off
	v_cvt_pk_bf16_f32 v46, v47, s0
	v_sub_f32_e32 v47, v97, v48
	v_mul_f32_e32 v47, 0x3fb8aa3b, v47
	v_sub_f32_e32 v68, v48, v97
	v_exp_f32_e32 v47, v47
	v_mul_f32_e32 v68, 0x3fb8aa3b, v68
	v_exp_f32_e32 v68, v68
	global_store_short v[124:125], v46, off offset:1024
	s_waitcnt vmcnt(31)
	v_lshlrev_b32_e32 v46, 16, v142
	v_mul_f32_e32 v46, 0x3db504f3, v46
	v_mul_f32_e32 v46, v47, v46
	s_waitcnt vmcnt(30)
	v_lshlrev_b32_e32 v47, 16, v143
	v_mul_f32_e32 v47, v68, v47
	v_cvt_pk_bf16_f32 v46, v46, s0
	global_store_short v[126:127], v46, off
	v_cvt_pk_bf16_f32 v46, v47, s0
	v_sub_f32_e32 v47, v99, v48
	v_mul_f32_e32 v47, 0x3fb8aa3b, v47
	v_sub_f32_e32 v68, v48, v99
	v_exp_f32_e32 v47, v47
	v_mul_f32_e32 v68, 0x3fb8aa3b, v68
	v_exp_f32_e32 v68, v68
	global_store_short v[126:127], v46, off offset:1024
	s_waitcnt vmcnt(31)
; __device__ __forceinline__ unsigned cvtpk(float lo, float hi) { f32x2 v = {lo, hi}; bf16x2_t b = __builtin_convertvector(v, bf16x2_t); return __builtin_bit_cast(unsigned, b); }
; __device__ __forceinline__ float fexp(float x) { return __builtin_amdgcn_exp2f(x * 1.44269504089f); }
; __device__ __forceinline__ void phase_qkrope_gla_prep(const Params& p, LAS unsigned char* lds, int wave, int lane) {
;     ...
;             for (int tb = 0; tb < 4; ++tb) {
;                 unsigned short qv[16], kv[16];
; #pragma unroll
;                 for (int t = 0; t < 16; ++t) { const size_t ro = (size_t)(m0 + 16 * tb + t) * ZP + d; qv[t] = Z[ro + C_QG]; kv[t] = Z[ro + C_KG]; }
; #pragma unroll
;                 for (int t = 0; t < 16; ++t) { const size_t ro = (size_t)(m0 + 16 * tb + t) * ZP + d; const float bb = bl[16 * tb + t];
;                     const float qs = bf2f(qv[t]) * 0.08838834764831845f * fexp(bb - bref), ks = bf2f(kv[t]) * fexp(bref - bb);
;                     Z[ro + C_QG] = (bf16_t)(cvtpk(qs, 0.f) & 0xffffu); Z[ro + C_KG] = (bf16_t)(cvtpk(ks, 0.f) & 0xffffu); }
	v_lshlrev_b32_e32 v46, 16, v144
	v_mul_f32_e32 v46, 0x3db504f3, v46
	v_mul_f32_e32 v46, v47, v46
	s_waitcnt vmcnt(30)
	v_lshlrev_b32_e32 v47, 16, v145
	v_mul_f32_e32 v47, v68, v47
	v_cvt_pk_bf16_f32 v46, v46, s0
	global_store_short v[128:129], v46, off
	v_cvt_pk_bf16_f32 v46, v47, s0
	v_sub_f32_e32 v47, v103, v48
	v_mul_f32_e32 v47, 0x3fb8aa3b, v47
	v_sub_f32_e32 v68, v48, v103
	v_exp_f32_e32 v47, v47
	v_mul_f32_e32 v68, 0x3fb8aa3b, v68
	v_exp_f32_e32 v68, v68
	global_store_short v[128:129], v46, off offset:1024
	s_waitcnt vmcnt(31)
	v_lshlrev_b32_e32 v46, 16, v146
	v_mul_f32_e32 v46, 0x3db504f3, v46
	v_mul_f32_e32 v46, v47, v46
	s_waitcnt vmcnt(30)
	v_lshlrev_b32_e32 v47, 16, v147
	v_mul_f32_e32 v47, v68, v47
	v_cvt_pk_bf16_f32 v46, v46, s0
	global_store_short v[2:3], v46, off
	v_cvt_pk_bf16_f32 v46, v47, s0
	global_store_short v[2:3], v46, off offset:1024
	v_sub_f32_e32 v3, v106, v48
	v_mul_f32_e32 v3, 0x3fb8aa3b, v3
	v_sub_f32_e32 v46, v48, v106
	v_exp_f32_e32 v3, v3
	v_mul_f32_e32 v46, 0x3fb8aa3b, v46
	v_exp_f32_e32 v46, v46
	s_waitcnt vmcnt(31)
	v_lshlrev_b32_e32 v2, 16, v148
	v_mul_f32_e32 v2, 0x3db504f3, v2
	v_mul_f32_e32 v2, v3, v2
	s_waitcnt vmcnt(30)
	v_lshlrev_b32_e32 v3, 16, v149
	v_mul_f32_e32 v3, v46, v3
	v_mad_i64_i32 v[46:47], s[4:5], s4, v61, v[8:9]
	global_load_ushort v68, v[46:47], off
	s_add_i32 s4, s0, -14
	v_mad_i64_i32 v[82:83], s[4:5], s4, v61, v[8:9]
	s_add_i32 s4, s0, -13
	s_nop 0
	v_mad_i64_i32 v[88:89], s[4:5], s4, v61, v[8:9]
	s_add_i32 s4, s0, -12
	s_nop 0
	v_mad_i64_i32 v[90:91], s[4:5], s4, v61, v[8:9]
	s_add_i32 s4, s0, -11
	s_nop 0
	v_mad_i64_i32 v[92:93], s[4:5], s4, v61, v[8:9]
	s_add_i32 s4, s0, -10
	s_nop 0
	v_mad_i64_i32 v[94:95], s[4:5], s4, v61, v[8:9]
	s_add_i32 s4, s0, -9
	s_nop 0
	v_mad_i64_i32 v[96:97], s[4:5], s4, v61, v[8:9]
	s_add_i32 s4, s0, -8
	s_nop 0
	v_mad_i64_i32 v[98:99], s[4:5], s4, v61, v[8:9]
	s_add_i32 s4, s0, -7
	s_nop 0
	v_mad_i64_i32 v[100:101], s[4:5], s4, v61, v[8:9]
	s_add_i32 s4, s0, -6
	s_nop 0
	v_mad_i64_i32 v[102:103], s[4:5], s4, v61, v[8:9]
	s_add_i32 s4, s0, -5
	s_nop 0
	v_mad_i64_i32 v[104:105], s[4:5], s4, v61, v[8:9]
	s_add_i32 s4, s0, -4
	s_nop 0
	v_mad_i64_i32 v[106:107], s[4:5], s4, v61, v[8:9]
	s_add_i32 s4, s0, -3
	s_nop 0
	v_mad_i64_i32 v[108:109], s[4:5], s4, v61, v[8:9]
	v_cvt_pk_bf16_f32 v2, v2, s0
	s_add_i32 s4, s0, -2
	global_store_short v[0:1], v2, off
	v_cvt_pk_bf16_f32 v2, v3, s0
	v_mad_i64_i32 v[110:111], s[4:5], s4, v61, v[8:9]
	global_store_short v[0:1], v2, off offset:1024
	s_add_i32 s4, s0, -1
	v_mad_i64_i32 v[2:3], s[4:5], s4, v61, v[8:9]
	v_mad_i64_i32 v[0:1], s[4:5], s0, v61, v[8:9]
	s_lshl_b64 s[4:5], s[18:19], 9
	s_add_i32 s18, s18, s70
	s_waitcnt vmcnt(2)
	v_lshlrev_b32_e32 v68, 16, v68
	v_mul_f32_e32 v68, 0x3db504f3, v68
	v_mul_f32_e32 v68, v70, v68
	global_load_ushort v70, v[46:47], off offset:1024
	v_cvt_pk_bf16_f32 v68, v68, s0
	s_waitcnt vmcnt(0)
	v_lshlrev_b32_e32 v70, 16, v70
	v_mul_f32_e32 v49, v49, v70
	global_load_ushort v70, v[82:83], off
	global_load_ushort v72, v[82:83], off offset:1024
	global_load_ushort v74, v[88:89], off
	global_load_ushort v77, v[88:89], off offset:1024
	global_load_ushort v79, v[90:91], off
	global_load_ushort v81, v[90:91], off offset:1024
	global_load_ushort v85, v[92:93], off
	global_load_ushort v86, v[92:93], off offset:1024
	global_load_ushort v112, v[94:95], off
	global_load_ushort v113, v[94:95], off offset:1024
	global_load_ushort v114, v[96:97], off
	global_load_ushort v115, v[96:97], off offset:1024
	global_load_ushort v116, v[98:99], off
	global_load_ushort v117, v[98:99], off offset:1024
	global_load_ushort v118, v[100:101], off
	global_load_ushort v119, v[100:101], off offset:1024
	global_load_ushort v120, v[102:103], off
	global_load_ushort v121, v[102:103], off offset:1024
	global_load_ushort v122, v[104:105], off
	global_load_ushort v123, v[104:105], off offset:1024
	global_load_ushort v124, v[106:107], off
	global_load_ushort v125, v[106:107], off offset:1024
	global_load_ushort v126, v[108:109], off
	global_load_ushort v127, v[108:109], off offset:1024
	global_load_ushort v128, v[110:111], off
	global_load_ushort v129, v[110:111], off offset:1024
	global_load_ushort v130, v[2:3], off
	global_load_ushort v131, v[2:3], off offset:1024
	global_load_ushort v132, v[0:1], off
	global_load_ushort v133, v[0:1], off offset:1024
	v_cvt_pk_bf16_f32 v49, v49, s0
	global_store_short v[46:47], v68, off
	global_store_short v[46:47], v49, off offset:1024
	v_sub_f32_e32 v47, v62, v48
	v_mul_f32_e32 v47, 0x3fb8aa3b, v47
	v_sub_f32_e32 v49, v48, v62
	v_exp_f32_e32 v47, v47
	v_mul_f32_e32 v49, 0x3fb8aa3b, v49
	v_exp_f32_e32 v49, v49
	s_waitcnt vmcnt(31)
	v_lshlrev_b32_e32 v46, 16, v70
	v_mul_f32_e32 v46, 0x3db504f3, v46
	v_mul_f32_e32 v46, v47, v46
	s_waitcnt vmcnt(30)
	v_lshlrev_b32_e32 v47, 16, v72
	v_mul_f32_e32 v47, v49, v47
	v_cvt_pk_bf16_f32 v46, v46, s0
	global_store_short v[82:83], v46, off
	v_cvt_pk_bf16_f32 v46, v47, s0
	v_sub_f32_e32 v47, v63, v48
	v_mul_f32_e32 v47, 0x3fb8aa3b, v47
	v_sub_f32_e32 v49, v48, v63
	v_exp_f32_e32 v47, v47
	v_mul_f32_e32 v49, 0x3fb8aa3b, v49
	v_exp_f32_e32 v49, v49
	global_store_short v[82:83], v46, off offset:1024
	s_waitcnt vmcnt(31)
	v_lshlrev_b32_e32 v46, 16, v74
	v_mul_f32_e32 v46, 0x3db504f3, v46
	v_mul_f32_e32 v46, v47, v46
	s_waitcnt vmcnt(30)
	v_lshlrev_b32_e32 v47, 16, v77
	v_mul_f32_e32 v47, v49, v47
	v_cvt_pk_bf16_f32 v46, v46, s0
	global_store_short v[88:89], v46, off
	v_cvt_pk_bf16_f32 v46, v47, s0
	v_sub_f32_e32 v47, v64, v48
	v_mul_f32_e32 v47, 0x3fb8aa3b, v47
	v_sub_f32_e32 v49, v48, v64
	v_exp_f32_e32 v47, v47
	v_mul_f32_e32 v49, 0x3fb8aa3b, v49
	v_exp_f32_e32 v49, v49
	global_store_short v[88:89], v46, off offset:1024
	s_waitcnt vmcnt(31)
; __device__ __forceinline__ unsigned cvtpk(float lo, float hi) { f32x2 v = {lo, hi}; bf16x2_t b = __builtin_convertvector(v, bf16x2_t); return __builtin_bit_cast(unsigned, b); }
; __device__ __forceinline__ float fexp(float x) { return __builtin_amdgcn_exp2f(x * 1.44269504089f); }
; __device__ __forceinline__ void phase_qkrope_gla_prep(const Params& p, LAS unsigned char* lds, int wave, int lane) {
;     ...
;                 for (int t = 0; t < 16; ++t) { const size_t ro = (size_t)(m0 + 16 * tb + t) * ZP + d; const float bb = bl[16 * tb + t];
;                     const float qs = bf2f(qv[t]) * 0.08838834764831845f * fexp(bb - bref), ks = bf2f(kv[t]) * fexp(bref - bb);
;                     Z[ro + C_QG] = (bf16_t)(cvtpk(qs, 0.f) & 0xffffu); Z[ro + C_KG] = (bf16_t)(cvtpk(ks, 0.f) & 0xffffu); }
	v_lshlrev_b32_e32 v46, 16, v79
	v_mul_f32_e32 v46, 0x3db504f3, v46
	v_mul_f32_e32 v46, v47, v46
	s_waitcnt vmcnt(30)
	v_lshlrev_b32_e32 v47, 16, v81
	v_mul_f32_e32 v47, v49, v47
	v_cvt_pk_bf16_f32 v46, v46, s0
	global_store_short v[90:91], v46, off
	v_cvt_pk_bf16_f32 v46, v47, s0
	v_sub_f32_e32 v47, v65, v48
	v_mul_f32_e32 v47, 0x3fb8aa3b, v47
	v_sub_f32_e32 v49, v48, v65
	v_exp_f32_e32 v47, v47
	v_mul_f32_e32 v49, 0x3fb8aa3b, v49
	v_exp_f32_e32 v49, v49
	global_store_short v[90:91], v46, off offset:1024
	s_waitcnt vmcnt(31)
	v_lshlrev_b32_e32 v46, 16, v85
	v_mul_f32_e32 v46, 0x3db504f3, v46
	v_mul_f32_e32 v46, v47, v46
	s_waitcnt vmcnt(30)
	v_lshlrev_b32_e32 v47, 16, v86
	v_mul_f32_e32 v47, v49, v47
	v_cvt_pk_bf16_f32 v46, v46, s0
	global_store_short v[92:93], v46, off
	v_cvt_pk_bf16_f32 v46, v47, s0
	v_sub_f32_e32 v47, v66, v48
	v_mul_f32_e32 v47, 0x3fb8aa3b, v47
	v_sub_f32_e32 v49, v48, v66
	v_exp_f32_e32 v47, v47
	v_mul_f32_e32 v49, 0x3fb8aa3b, v49
	v_exp_f32_e32 v49, v49
	global_store_short v[92:93], v46, off offset:1024
	s_waitcnt vmcnt(31)
	v_lshlrev_b32_e32 v46, 16, v112
	v_mul_f32_e32 v46, 0x3db504f3, v46
	v_mul_f32_e32 v46, v47, v46
	s_waitcnt vmcnt(30)
	v_lshlrev_b32_e32 v47, 16, v113
	v_mul_f32_e32 v47, v49, v47
	v_cvt_pk_bf16_f32 v46, v46, s0
	global_store_short v[94:95], v46, off
	v_cvt_pk_bf16_f32 v46, v47, s0
	v_sub_f32_e32 v47, v67, v48
	v_mul_f32_e32 v47, 0x3fb8aa3b, v47
	v_sub_f32_e32 v49, v48, v67
	v_exp_f32_e32 v47, v47
	v_mul_f32_e32 v49, 0x3fb8aa3b, v49
	v_exp_f32_e32 v49, v49
	global_store_short v[94:95], v46, off offset:1024
	s_waitcnt vmcnt(31)
	v_lshlrev_b32_e32 v46, 16, v114
	v_mul_f32_e32 v46, 0x3db504f3, v46
	v_mul_f32_e32 v46, v47, v46
	s_waitcnt vmcnt(30)
	v_lshlrev_b32_e32 v47, 16, v115
	v_mul_f32_e32 v47, v49, v47
	v_cvt_pk_bf16_f32 v46, v46, s0
	global_store_short v[96:97], v46, off
	v_cvt_pk_bf16_f32 v46, v47, s0
	v_sub_f32_e32 v47, v69, v48
	v_mul_f32_e32 v47, 0x3fb8aa3b, v47
	v_sub_f32_e32 v49, v48, v69
	v_exp_f32_e32 v47, v47
	v_mul_f32_e32 v49, 0x3fb8aa3b, v49
	v_exp_f32_e32 v49, v49
	global_store_short v[96:97], v46, off offset:1024
	s_waitcnt vmcnt(31)
	v_lshlrev_b32_e32 v46, 16, v116
	v_mul_f32_e32 v46, 0x3db504f3, v46
	v_mul_f32_e32 v46, v47, v46
	s_waitcnt vmcnt(30)
	v_lshlrev_b32_e32 v47, 16, v117
	v_mul_f32_e32 v47, v49, v47
	v_cvt_pk_bf16_f32 v46, v46, s0
	global_store_short v[98:99], v46, off
	v_cvt_pk_bf16_f32 v46, v47, s0
	v_sub_f32_e32 v47, v71, v48
	v_mul_f32_e32 v47, 0x3fb8aa3b, v47
	v_sub_f32_e32 v49, v48, v71
	v_exp_f32_e32 v47, v47
	v_mul_f32_e32 v49, 0x3fb8aa3b, v49
	v_exp_f32_e32 v49, v49
	global_store_short v[98:99], v46, off offset:1024
	s_waitcnt vmcnt(31)
	v_lshlrev_b32_e32 v46, 16, v118
	v_mul_f32_e32 v46, 0x3db504f3, v46
	v_mul_f32_e32 v46, v47, v46
	s_waitcnt vmcnt(30)
	v_lshlrev_b32_e32 v47, 16, v119
	v_mul_f32_e32 v47, v49, v47
	v_cvt_pk_bf16_f32 v46, v46, s0
	global_store_short v[100:101], v46, off
	v_cvt_pk_bf16_f32 v46, v47, s0
	v_sub_f32_e32 v47, v73, v48
	v_mul_f32_e32 v47, 0x3fb8aa3b, v47
	v_sub_f32_e32 v49, v48, v73
	v_exp_f32_e32 v47, v47
	v_mul_f32_e32 v49, 0x3fb8aa3b, v49
	v_exp_f32_e32 v49, v49
	global_store_short v[100:101], v46, off offset:1024
	s_waitcnt vmcnt(31)
	v_lshlrev_b32_e32 v46, 16, v120
	v_mul_f32_e32 v46, 0x3db504f3, v46
	v_mul_f32_e32 v46, v47, v46
	s_waitcnt vmcnt(30)
	v_lshlrev_b32_e32 v47, 16, v121
	v_mul_f32_e32 v47, v49, v47
	v_cvt_pk_bf16_f32 v46, v46, s0
	global_store_short v[102:103], v46, off
	v_cvt_pk_bf16_f32 v46, v47, s0
	v_sub_f32_e32 v47, v75, v48
	v_mul_f32_e32 v47, 0x3fb8aa3b, v47
	v_sub_f32_e32 v49, v48, v75
	v_exp_f32_e32 v47, v47
	v_mul_f32_e32 v49, 0x3fb8aa3b, v49
	v_exp_f32_e32 v49, v49
	global_store_short v[102:103], v46, off offset:1024
	s_waitcnt vmcnt(31)
; __device__ __forceinline__ unsigned cvtpk(float lo, float hi) { f32x2 v = {lo, hi}; bf16x2_t b = __builtin_convertvector(v, bf16x2_t); return __builtin_bit_cast(unsigned, b); }
; __device__ __forceinline__ float fexp(float x) { return __builtin_amdgcn_exp2f(x * 1.44269504089f); }
; __device__ __forceinline__ void phase_qkrope_gla_prep(const Params& p, LAS unsigned char* lds, int wave, int lane) {
;     ...
;                 for (int t = 0; t < 16; ++t) { const size_t ro = (size_t)(m0 + 16 * tb + t) * ZP + d; const float bb = bl[16 * tb + t];
;                     const float qs = bf2f(qv[t]) * 0.08838834764831845f * fexp(bb - bref), ks = bf2f(kv[t]) * fexp(bref - bb);
;                     Z[ro + C_QG] = (bf16_t)(cvtpk(qs, 0.f) & 0xffffu); Z[ro + C_KG] = (bf16_t)(cvtpk(ks, 0.f) & 0xffffu); }
;             }
;             { const size_t eo = (size_t)bc * 512 + d; E1[eo] = fexp(bref); E2[eo] = fexp(blast - bref); E3[eo] = fexp(blast); }
;         }
	v_lshlrev_b32_e32 v46, 16, v122
	v_mul_f32_e32 v46, 0x3db504f3, v46
	v_mul_f32_e32 v46, v47, v46
	s_waitcnt vmcnt(30)
	v_lshlrev_b32_e32 v47, 16, v123
	v_mul_f32_e32 v47, v49, v47
	v_cvt_pk_bf16_f32 v46, v46, s0
	global_store_short v[104:105], v46, off
	v_cvt_pk_bf16_f32 v46, v47, s0
	v_sub_f32_e32 v47, v78, v48
	v_mul_f32_e32 v47, 0x3fb8aa3b, v47
	v_sub_f32_e32 v49, v48, v78
	v_exp_f32_e32 v47, v47
	v_mul_f32_e32 v49, 0x3fb8aa3b, v49
	v_exp_f32_e32 v49, v49
	global_store_short v[104:105], v46, off offset:1024
	s_waitcnt vmcnt(31)
	v_lshlrev_b32_e32 v46, 16, v124
	v_mul_f32_e32 v46, 0x3db504f3, v46
	v_mul_f32_e32 v46, v47, v46
	s_waitcnt vmcnt(30)
	v_lshlrev_b32_e32 v47, 16, v125
	v_mul_f32_e32 v47, v49, v47
	v_cvt_pk_bf16_f32 v46, v46, s0
	global_store_short v[106:107], v46, off
	v_cvt_pk_bf16_f32 v46, v47, s0
	v_sub_f32_e32 v47, v80, v48
	v_mul_f32_e32 v47, 0x3fb8aa3b, v47
	v_sub_f32_e32 v49, v48, v80
	v_exp_f32_e32 v47, v47
	v_mul_f32_e32 v49, 0x3fb8aa3b, v49
	v_exp_f32_e32 v49, v49
	global_store_short v[106:107], v46, off offset:1024
	s_waitcnt vmcnt(31)
	v_lshlrev_b32_e32 v46, 16, v126
	v_mul_f32_e32 v46, 0x3db504f3, v46
	v_mul_f32_e32 v46, v47, v46
	s_waitcnt vmcnt(30)
	v_lshlrev_b32_e32 v47, 16, v127
	v_mul_f32_e32 v47, v49, v47
	v_cvt_pk_bf16_f32 v46, v46, s0
	global_store_short v[108:109], v46, off
	v_cvt_pk_bf16_f32 v46, v47, s0
	v_sub_f32_e32 v47, v84, v48
	v_mul_f32_e32 v47, 0x3fb8aa3b, v47
	v_sub_f32_e32 v49, v48, v84
	v_exp_f32_e32 v47, v47
	v_mul_f32_e32 v49, 0x3fb8aa3b, v49
	v_exp_f32_e32 v49, v49
	global_store_short v[108:109], v46, off offset:1024
	s_waitcnt vmcnt(31)
	v_lshlrev_b32_e32 v46, 16, v128
	v_mul_f32_e32 v46, 0x3db504f3, v46
	v_mul_f32_e32 v46, v47, v46
	s_waitcnt vmcnt(30)
	v_lshlrev_b32_e32 v47, 16, v129
	v_mul_f32_e32 v47, v49, v47
	v_cvt_pk_bf16_f32 v46, v46, s0
	global_store_short v[110:111], v46, off
	v_cvt_pk_bf16_f32 v46, v47, s0
	v_sub_f32_e32 v47, v87, v48
	v_mul_f32_e32 v47, 0x3fb8aa3b, v47
	v_sub_f32_e32 v49, v48, v87
	v_exp_f32_e32 v47, v47
	v_mul_f32_e32 v49, 0x3fb8aa3b, v49
	v_exp_f32_e32 v49, v49
	global_store_short v[110:111], v46, off offset:1024
	s_waitcnt vmcnt(31)
	v_lshlrev_b32_e32 v46, 16, v130
	v_mul_f32_e32 v46, 0x3db504f3, v46
	v_mul_f32_e32 v46, v47, v46
	s_waitcnt vmcnt(30)
	v_lshlrev_b32_e32 v47, 16, v131
	v_mul_f32_e32 v47, v49, v47
	v_cvt_pk_bf16_f32 v46, v46, s0
	global_store_short v[2:3], v46, off
	v_cvt_pk_bf16_f32 v46, v47, s0
	global_store_short v[2:3], v46, off offset:1024
	s_waitcnt vmcnt(31)
	v_lshlrev_b32_e32 v2, 16, v132
	v_mul_f32_e32 v3, 0x3db504f3, v2
	v_sub_f32_e32 v2, v76, v48
	v_mul_f32_e32 v2, 0x3fb8aa3b, v2
	v_sub_f32_e32 v47, v48, v76
	v_exp_f32_e32 v2, v2
	v_mul_f32_e32 v47, 0x3fb8aa3b, v47
	v_exp_f32_e32 v47, v47
	s_waitcnt vmcnt(30)
	v_lshlrev_b32_e32 v46, 16, v133
	v_mul_f32_e32 v3, v2, v3
	v_cvt_pk_bf16_f32 v3, v3, s0
	v_mul_f32_e32 v46, v47, v46
	global_store_short v[0:1], v3, off
	v_cvt_pk_bf16_f32 v3, v46, s0
	global_store_short v[0:1], v3, off offset:1024
	v_mul_f32_e32 v3, 0x3fb8aa3b, v48
	v_exp_f32_e32 v3, v3
	v_lshl_add_u64 v[0:1], s[4:5], 0, v[4:5]
	v_lshlrev_b64 v[0:1], 2, v[0:1]
	v_lshl_add_u64 v[46:47], s[6:7], 0, v[0:1]
	global_store_dword v[46:47], v3, off
	v_lshl_add_u64 v[46:47], s[8:9], 0, v[0:1]
	global_store_dword v[46:47], v2, off
	v_mul_f32_e32 v2, 0x3fb8aa3b, v76
	v_exp_f32_e32 v2, v2
	s_add_i32 s0, s0, s1
	v_lshl_add_u64 v[0:1], s[10:11], 0, v[0:1]
	s_cmpk_gt_i32 s18, 0xff
	global_store_dword v[0:1], v2, off
	s_cbranch_scc0 .LBB0_518
